# hand-written mamba scan, RWKV step B/ISSUE restructure, attention pk_add split
# speedup vs baseline: 1.1521x; 1.0387x over previous
.LBB0_421:
	s_or_b64 exec, exec, s[18:19]
	s_mul_i32 s52, s36, 0x20800
	s_xor_b64 s[76:77], s[22:23], -1
	s_lshl_b64 s[18:19], s[52:53], 2
	s_add_u32 s18, s20, s18
	v_mov_b32_e32 v6, 0xc200
	v_mov_b32_e32 v7, 0xb000
	s_addc_u32 s19, s21, s19
	v_cndmask_b32_e64 v6, v6, v7, s[16:17]
	s_lshl_b32 s16, s34, 1
	s_add_u32 s20, s20, s16
	s_addc_u32 s21, s21, 0
	s_lshl_b32 s22, s35, 2
	s_add_u32 s18, s18, s22
	s_addc_u32 s19, s19, 0
	s_add_u32 s78, s18, 0x118000
	v_readlane_b32 s18, v255, 3
	v_lshlrev_b32_e32 v4, 1, v116
	s_addc_u32 s79, s19, 0
	v_lshl_add_u32 v61, v235, 2, s18
	s_lshl_b32 s18, s37, 1
	v_and_b32_e32 v5, 14, v4
	v_lshrrev_b32_e32 v7, 2, v116
	s_add_u32 s18, s20, s18
	v_and_b32_e32 v52, 16, v7
	s_addc_u32 s19, s21, 0
	v_lshlrev_b32_e32 v16, 1, v5
	v_ashrrev_i32_e32 v87, 4, v116
	v_add_u32_e32 v64, 0, v4
	v_lshlrev_b32_e32 v67, 5, v5
	v_lshl_add_u64 v[4:5], s[18:19], 0, v[16:17]
	v_lshlrev_b32_e32 v16, 8, v52
	v_lshl_or_b32 v69, v139, 10, v16
	v_lshl_or_b32 v16, v87, 8, v122
	v_add_u32_e32 v92, 16, v87
	v_and_b32_e32 v60, 1, v116
	v_add_u32_e32 v91, 0, v16
	v_lshl_or_b32 v16, v92, 8, v122
	v_add_u32_e32 v93, 0, v16
	v_add_u32_e32 v16, 0x11200, v64
	v_cmp_eq_u32_e32 vcc, 0, v60
	v_or_b32_e32 v7, v52, v140
	v_mul_u32_u24_e32 v7, 0x90, v7
	v_cndmask_b32_e32 v98, v61, v16, vcc
	v_add_u32_e32 v16, 0x11000, v64
	v_cndmask_b32_e32 v99, v61, v16, vcc
	v_add_u32_e32 v16, 0x10e00, v64
	v_cndmask_b32_e32 v100, v61, v16, vcc
	v_add_u32_e32 v16, 0x10c00, v64
	v_cndmask_b32_e32 v101, v61, v16, vcc
	v_add_u32_e32 v16, 0x10a00, v64
	s_mov_b64 s[18:19], 0xe488000
	v_cndmask_b32_e32 v102, v61, v16, vcc
	v_add_u32_e32 v16, 0x10800, v64
	v_add3_u32 v62, 0, v6, v7
	v_or_b32_e32 v6, s38, v140
	v_lshl_add_u64 v[18:19], v[4:5], 0, s[18:19]
	s_mov_b32 s18, 0x5040100
	s_movk_i32 s20, 0xffde
	v_add_u32_e32 v97, v106, v105
	v_cndmask_b32_e32 v103, v61, v16, vcc
	v_add_u32_e32 v16, 0x10600, v64
	v_cmp_eq_u32_e64 s[16:17], 0, v6
	v_perm_b32 v7, v153, v151, s18
	v_perm_b32 v6, v149, v147, s18
	v_perm_b32 v5, v145, v143, s18
	v_perm_b32 v4, v142, v141, s18
	v_perm_b32 v11, v165, v163, s18
	v_perm_b32 v10, v162, v161, s18
	v_perm_b32 v9, v160, v159, s18
	v_perm_b32 v8, v158, v157, s18
	v_perm_b32 v15, v186, v184, s18
	v_perm_b32 v14, v182, v180, s18
	v_perm_b32 v13, v178, v176, s18
	v_perm_b32 v12, v174, v173, s18
	v_perm_b32 v27, v198, v195, s18
	v_perm_b32 v26, v194, v193, s18
	v_perm_b32 v25, v192, v191, s18
	v_perm_b32 v24, v190, v189, s18
	v_perm_b32 v35, v156, v155, s18
	v_perm_b32 v34, v154, v152, s18
	v_perm_b32 v33, v150, v148, s18
	v_perm_b32 v32, v146, v144, s18
	v_perm_b32 v39, v172, v171, s18
	v_perm_b32 v38, v170, v169, s18
	v_perm_b32 v37, v168, v167, s18
	v_perm_b32 v36, v166, v164, s18
	v_perm_b32 v43, v188, v187, s18
	v_perm_b32 v42, v185, v183, s18
	v_perm_b32 v41, v181, v179, s18
	v_perm_b32 v40, v177, v175, s18
	v_perm_b32 v47, v204, v203, s18
	v_perm_b32 v46, v202, v201, s18
	v_perm_b32 v45, v200, v199, s18
	v_perm_b32 v44, v197, v196, s18
	v_mad_u64_u32 v[58:59], s[18:19], v97, s20, v[104:105]
	v_cndmask_b32_e32 v104, v61, v16, vcc
	v_add_u32_e32 v16, 0x10400, v64
	v_cndmask_b32_e32 v105, v61, v16, vcc
	v_add_u32_e32 v16, 0x10200, v64
	v_cndmask_b32_e32 v106, v61, v16, vcc
	v_add_u32_e32 v16, 0x10000, v64
	v_cndmask_b32_e32 v107, v61, v16, vcc
	v_add_u32_e32 v16, 0xfe00, v64
	v_cndmask_b32_e32 v108, v61, v16, vcc
	v_add_u32_e32 v16, 0xfc00, v64
	v_cndmask_b32_e32 v109, v61, v16, vcc
	v_add_u32_e32 v16, 0xfa00, v64
	v_cndmask_b32_e32 v110, v61, v16, vcc
	v_add_u32_e32 v16, 0xf800, v64
	v_cndmask_b32_e32 v111, v61, v16, vcc
	v_add_u32_e32 v16, 0xf600, v64
	v_cndmask_b32_e32 v112, v61, v16, vcc
	v_add_u32_e32 v16, 0xf400, v64
	v_cndmask_b32_e32 v113, v61, v16, vcc
	v_add_u32_e32 v16, 0xf200, v64
	v_cndmask_b32_e32 v114, v61, v16, vcc
	v_add_u32_e32 v16, 0xf000, v64
	v_add_u32_e32 v94, v206, v205
	v_cndmask_b32_e32 v115, v61, v16, vcc
	v_add_u32_e32 v16, 0xee00, v64
	v_and_b32_e32 v63, 48, v116
	v_ashrrev_i32_e32 v90, 3, v116
	v_mad_u64_u32 v[52:53], s[18:19], v94, s20, v[116:117]
	v_cndmask_b32_e32 v116, v61, v16, vcc
	v_add_u32_e32 v16, 0xec00, v64
	v_add_u32_e32 v95, v234, v233
	v_cndmask_b32_e32 v122, v61, v16, vcc
	v_add_u32_e32 v16, 0xea00, v64
	v_mad_u64_u32 v[54:55], s[18:19], v95, s20, v[124:125]
	v_add_u32_e32 v96, v237, v236
	v_cndmask_b32_e32 v124, v61, v16, vcc
	v_add_u32_e32 v16, 0xe800, v64
	v_mad_u64_u32 v[56:57], s[18:19], v96, s20, v[126:127]
	v_cndmask_b32_e32 v126, v61, v16, vcc
	v_add_u32_e32 v16, 0xe600, v64
	v_lshl_add_u32 v88, v140, 4, 0
	v_cndmask_b32_e32 v139, v61, v16, vcc
	v_add_u32_e32 v16, 0xe400, v64
	v_mad_i32_i24 v68, v140, -12, v88
	v_cndmask_b32_e32 v140, v61, v16, vcc
	v_add_u32_e32 v16, 0xe200, v64
	v_cndmask_b32_e32 v141, v61, v16, vcc
	v_add_u32_e32 v16, 0xe000, v64
	v_cndmask_b32_e32 v142, v61, v16, vcc
	v_add_u32_e32 v16, 0xde00, v64
	v_cndmask_b32_e32 v143, v61, v16, vcc
	v_add_u32_e32 v16, 0xdc00, v64
	v_cndmask_b32_e32 v144, v61, v16, vcc
	v_add_u32_e32 v16, 0xda00, v64
	v_cndmask_b32_e32 v145, v61, v16, vcc
	v_add_u32_e32 v16, 0xd800, v64
	v_cndmask_b32_e32 v146, v61, v16, vcc
	v_add_u32_e32 v16, 0xd600, v64
	v_cndmask_b32_e32 v147, v61, v16, vcc
	v_and_b32_e32 v16, -16, v52
	v_add_u32_e32 v65, 0xd400, v64
	v_cmp_ne_u32_e64 s[18:19], 16, v16
	v_lshl_add_u32 v16, v94, 6, 0
	v_lshlrev_b32_e32 v53, 5, v52
	s_mov_b32 s28, 0x9c00
	s_movk_i32 s29, 0xc0
	s_movk_i32 s30, 0xff90
	v_cndmask_b32_e32 v148, v61, v65, vcc
	v_add3_u32 v55, v16, v53, s28
	v_mad_u64_u32 v[60:61], s[20:21], v94, s29, v[16:17]
	v_mul_lo_u32 v16, v94, s30
	v_lshlrev_b32_e32 v59, 4, v52
	v_add3_u32 v59, v60, v16, v59
	v_and_b32_e32 v16, -16, v54
	v_cmp_ne_u32_e64 s[20:21], 16, v16
	v_lshl_add_u32 v16, v95, 6, 0
	v_add_u32_e32 v53, v60, v53
	v_lshlrev_b32_e32 v64, 5, v54
	v_mad_u64_u32 v[60:61], s[22:23], v95, s29, v[16:17]
	v_add3_u32 v65, v16, v64, s28
	v_mul_lo_u32 v16, v95, s30
	v_lshlrev_b32_e32 v61, 4, v54
	v_add3_u32 v71, v60, v16, v61
	v_and_b32_e32 v16, -16, v56
	v_cmp_ne_u32_e64 s[22:23], 16, v16
	v_lshl_add_u32 v16, v96, 6, 0
	v_add_u32_e32 v64, v60, v64
	v_lshlrev_b32_e32 v72, 5, v56
	v_mad_u64_u32 v[60:61], s[24:25], v96, s29, v[16:17]
	v_add3_u32 v82, v16, v72, s28
	v_mul_lo_u32 v16, v96, s30
	v_lshlrev_b32_e32 v61, 4, v56
	v_add3_u32 v158, v60, v16, v61
	v_and_b32_e32 v16, -16, v58
	v_cmp_ne_u32_e64 s[24:25], 16, v16
	v_lshl_add_u32 v16, v97, 6, 0
	v_add_u32_e32 v83, v60, v72
	v_lshlrev_b32_e32 v72, 5, v58
	v_mad_u64_u32 v[60:61], s[26:27], v97, s29, v[16:17]
	v_add3_u32 v152, v16, v72, s28
	v_mul_lo_u32 v16, v97, s30
	v_lshlrev_b32_e32 v61, 4, v58
	v_add3_u32 v159, v60, v16, v61
	v_lshl_add_u32 v16, v86, 6, 0
	v_add_u32_e32 v153, v60, v72
	v_lshlrev_b32_e32 v72, 5, v84
	v_mad_u64_u32 v[60:61], s[26:27], v86, s29, v[16:17]
	v_add3_u32 v155, v16, v72, s28
	v_add_u32_e32 v16, v60, v72
	v_mul_lo_u32 v61, v86, s30
	v_lshlrev_b32_e32 v72, 4, v84
	v_mov_b32_e32 v149, s40
	v_mov_b32_e32 v150, s41
	v_cmp_gt_u32_e64 s[26:27], 32, v52
	v_add3_u32 v160, v60, v61, v72
	v_mov_b32_e32 v80, s42
	v_mov_b32_e32 v81, s34
	v_cmp_gt_i32_e32 vcc, 8, v52
	v_cndmask_b32_e64 v61, v149, v150, s[26:27]
	v_mov_b32_e32 v151, s39
	v_cmp_gt_u32_e64 s[26:27], 24, v52
	v_cndmask_b32_e32 v60, v80, v81, vcc
	v_cmp_gt_i32_e64 s[28:29], 16, v52
	v_cndmask_b32_e64 v61, v61, v151, s[26:27]
	v_cmp_gt_u32_e64 s[30:31], 32, v54
	v_cndmask_b32_e64 v60, v61, v60, s[28:29]
	v_lshl_add_u32 v60, v52, 3, v60
	v_ashrrev_i32_e32 v61, 31, v60
	v_lshl_add_u64 v[72:73], v[60:61], 1, s[58:59]
	v_cmp_gt_i32_e64 s[28:29], 8, v54
	v_cndmask_b32_e64 v61, v149, v150, s[30:31]
	v_cmp_gt_u32_e64 s[30:31], 24, v54
	v_cndmask_b32_e64 v60, v80, v81, s[28:29]
	v_cmp_gt_i32_e64 s[34:35], 16, v54
	v_cndmask_b32_e64 v61, v61, v151, s[30:31]
	v_cmp_gt_u32_e64 s[36:37], 32, v56
	v_cndmask_b32_e64 v60, v61, v60, s[34:35]
	v_lshl_add_u32 v60, v54, 3, v60
	v_ashrrev_i32_e32 v61, 31, v60
	v_lshl_add_u64 v[74:75], v[60:61], 1, s[58:59]
	v_cmp_gt_i32_e64 s[34:35], 8, v56
	v_cndmask_b32_e64 v61, v149, v150, s[36:37]
	v_cmp_gt_u32_e64 s[36:37], 24, v56
	v_cndmask_b32_e64 v60, v80, v81, s[34:35]
	v_cmp_gt_i32_e64 s[38:39], 16, v56
	v_cndmask_b32_e64 v61, v61, v151, s[36:37]
	v_cmp_gt_u32_e64 s[40:41], 32, v58
	v_cndmask_b32_e64 v60, v61, v60, s[38:39]
	v_lshl_add_u32 v60, v56, 3, v60
	v_ashrrev_i32_e32 v61, 31, v60
	v_lshl_add_u64 v[76:77], v[60:61], 1, s[58:59]
	v_cmp_gt_i32_e64 s[38:39], 8, v58
	v_cndmask_b32_e64 v61, v149, v150, s[40:41]
	v_cmp_gt_u32_e64 s[40:41], 24, v58
	v_cndmask_b32_e64 v60, v80, v81, s[38:39]
	v_cmp_gt_i32_e64 s[42:43], 16, v58
	v_cndmask_b32_e64 v61, v61, v151, s[40:41]
	v_cmp_gt_u32_e64 s[44:45], 32, v84
	v_cndmask_b32_e64 v60, v61, v60, s[42:43]
	v_lshl_add_u32 v60, v58, 3, v60
	v_ashrrev_i32_e32 v61, 31, v60
	v_lshl_add_u64 v[78:79], v[60:61], 1, s[58:59]
	v_cmp_gt_i32_e64 s[42:43], 8, v84
	v_cndmask_b32_e64 v61, v149, v150, s[44:45]
	v_cmp_gt_u32_e64 s[44:45], 24, v84
	v_cndmask_b32_e64 v60, v80, v81, s[42:43]
	v_cmp_gt_i32_e64 s[48:49], 16, v84
	v_cndmask_b32_e64 v61, v61, v151, s[44:45]
	v_add_u32_e32 v57, 0x1f00, v53
	v_cndmask_b32_e64 v60, v61, v60, s[48:49]
	v_cmp_gt_u32_e64 s[48:49], 16, v52
	v_add_u32_e32 v70, 0x1f00, v64
	v_add_u32_e32 v85, 0x1f00, v83
	v_cndmask_b32_e64 v52, v55, v57, s[48:49]
	v_cndmask_b32_e32 v149, v52, v53, vcc
	v_cmp_gt_u32_e32 vcc, 16, v54
	v_add_u32_e32 v154, 0x1f00, v153
	v_add_u32_e32 v156, 0x1f00, v16
	v_cndmask_b32_e32 v53, v65, v70, vcc
	v_cmp_gt_u32_e32 vcc, 16, v56
	v_lshl_add_u32 v60, v84, 3, v60
	v_mov_b32_e32 v57, 0xc080
	v_cndmask_b32_e32 v54, v82, v85, vcc
	v_cmp_gt_u32_e32 vcc, 16, v58
	v_lshl_add_u32 v66, v90, 9, 0
	v_ashrrev_i32_e32 v61, 31, v60
	v_cndmask_b32_e32 v55, v152, v154, vcc
	v_cmp_gt_u32_e32 vcc, 16, v84
	v_cndmask_b32_e64 v52, v57, v254, s[26:27]
	v_cndmask_b32_e64 v150, v53, v64, s[28:29]
	v_cndmask_b32_e32 v56, v155, v156, vcc
	v_cndmask_b32_e64 v53, v57, v254, s[30:31]
	v_cndmask_b32_e64 v151, v54, v83, s[34:35]
	v_cndmask_b32_e64 v54, v57, v254, s[36:37]
	v_cndmask_b32_e64 v152, v55, v153, s[38:39]
	v_cndmask_b32_e64 v55, v57, v254, s[40:41]
	v_cndmask_b32_e64 v153, v56, v16, s[42:43]
	v_cndmask_b32_e64 v56, v57, v254, s[44:45]
	v_mov_b32_e32 v16, v17
	v_lshl_add_u32 v89, v87, 2, 0
	v_lshl_add_u64 v[80:81], v[60:61], 1, s[58:59]
	s_mov_b32 s34, -8
	v_add_u32_e32 v154, v62, v63
	v_add_u32_e32 v155, v66, v67
	v_add_u32_e32 v156, v59, v52
	v_add_u32_e32 v157, v71, v53
	v_add_u32_e32 v158, v158, v54
	v_add_u32_e32 v159, v159, v55
	v_add_u32_e32 v160, v160, v56
	v_add_u32_e32 v161, v68, v69
	v_mov_b64_e32 v[82:83], v[16:17]
	v_mov_b64_e32 v[84:85], v[16:17]
	v_mov_b32_e32 v52, v232
	v_mov_b32_e32 v53, v231
	v_mov_b32_e32 v54, v230
	v_mov_b32_e32 v55, v207
	s_waitcnt lgkmcnt(0)
	s_barrier
	v_mad_u64_u32 v[218:219], s[26:27], v94, s83, v[72:73]
	v_mad_u64_u32 v[220:221], s[26:27], v95, s83, v[74:75]
	v_mad_u64_u32 v[222:223], s[26:27], v96, s83, v[76:77]
	v_mad_u64_u32 v[244:245], s[26:27], v97, s83, v[78:79]
	v_mad_u64_u32 v[246:247], s[26:27], v86, s83, v[80:81]
	s_branch .LBB0_424

.LBB0_424:
	ds_read_b128 v[56:59], v154
	ds_read_b128 v[162:165], v154 offset:64
	s_waitcnt lgkmcnt(1)
	v_mfma_f32_16x16x32_bf16 v[68:71], v[56:59], v[4:7], 0
	v_mfma_f32_16x16x32_bf16 v[64:67], v[56:59], v[8:11], 0
	v_mfma_f32_16x16x32_bf16 v[60:63], v[56:59], v[12:15], 0
	v_mfma_f32_16x16x32_bf16 v[166:169], v[56:59], v[24:27], 0
	s_waitcnt lgkmcnt(0)
	v_mfma_f32_16x16x32_bf16 v[68:71], v[162:165], v[32:35], v[68:71]
	v_mfma_f32_16x16x32_bf16 v[64:67], v[162:165], v[36:39], v[64:67]
	v_mfma_f32_16x16x32_bf16 v[60:63], v[162:165], v[40:43], v[60:63]
	v_mfma_f32_16x16x32_bf16 v[166:169], v[162:165], v[44:47], v[166:169]
	s_nop 7
	v_add_f32_e32 v170, v117, v68
	v_add_f32_e32 v171, v117, v69
	v_add_f32_e32 v172, v117, v70
	v_add_f32_e32 v173, v117, v71
	v_add_f32_e32 v174, v121, v64
	v_add_f32_e32 v175, v121, v65
	v_add_f32_e32 v176, v121, v66
	v_add_f32_e32 v177, v121, v67
	v_add_f32_e32 v178, v123, v60
	v_add_f32_e32 v179, v123, v61
	v_add_f32_e32 v180, v123, v62
	v_add_f32_e32 v181, v123, v63
	v_add_f32_e32 v182, v125, v166
	v_add_f32_e32 v183, v125, v167
	v_add_f32_e32 v184, v125, v168
	v_add_f32_e32 v185, v125, v169
	v_mul_f32_e32 v170, 0xbfb8aa3b, v170
	v_mul_f32_e32 v171, 0xbfb8aa3b, v171
	v_mul_f32_e32 v172, 0xbfb8aa3b, v172
	v_mul_f32_e32 v173, 0xbfb8aa3b, v173
	v_mul_f32_e32 v174, 0xbfb8aa3b, v174
	v_mul_f32_e32 v175, 0xbfb8aa3b, v175
	v_mul_f32_e32 v176, 0xbfb8aa3b, v176
	v_mul_f32_e32 v177, 0xbfb8aa3b, v177
	v_mul_f32_e32 v178, 0xbfb8aa3b, v178
	v_mul_f32_e32 v179, 0xbfb8aa3b, v179
	v_mul_f32_e32 v180, 0xbfb8aa3b, v180
	v_mul_f32_e32 v181, 0xbfb8aa3b, v181
	v_mul_f32_e32 v182, 0xbfb8aa3b, v182
	v_mul_f32_e32 v183, 0xbfb8aa3b, v183
	v_mul_f32_e32 v184, 0xbfb8aa3b, v184
	v_mul_f32_e32 v185, 0xbfb8aa3b, v185
	v_exp_f32_e32 v170, v170
	v_exp_f32_e32 v171, v171
	v_exp_f32_e32 v172, v172
	v_exp_f32_e32 v173, v173
	v_exp_f32_e32 v174, v174
	v_exp_f32_e32 v175, v175
	v_exp_f32_e32 v176, v176
	v_exp_f32_e32 v177, v177
	v_exp_f32_e32 v178, v178
	v_exp_f32_e32 v179, v179
	v_exp_f32_e32 v180, v180
	v_exp_f32_e32 v181, v181
	v_exp_f32_e32 v182, v182
	v_exp_f32_e32 v183, v183
	v_exp_f32_e32 v184, v184
	v_exp_f32_e32 v185, v185
	v_add_f32_e32 v170, 1.0, v170
	v_add_f32_e32 v171, 1.0, v171
	v_add_f32_e32 v172, 1.0, v172
	v_add_f32_e32 v173, 1.0, v173
	v_add_f32_e32 v174, 1.0, v174
	v_add_f32_e32 v175, 1.0, v175
	v_add_f32_e32 v176, 1.0, v176
	v_add_f32_e32 v177, 1.0, v177
	v_add_f32_e32 v178, 1.0, v178
	v_add_f32_e32 v179, 1.0, v179
	v_add_f32_e32 v180, 1.0, v180
	v_add_f32_e32 v181, 1.0, v181
	v_add_f32_e32 v182, 1.0, v182
	v_add_f32_e32 v183, 1.0, v183
	v_add_f32_e32 v184, 1.0, v184
	v_add_f32_e32 v185, 1.0, v185
	v_rcp_f32_e32 v170, v170
	v_rcp_f32_e32 v171, v171
	v_rcp_f32_e32 v172, v172
	v_rcp_f32_e32 v173, v173
	v_rcp_f32_e32 v174, v174
	v_rcp_f32_e32 v175, v175
	v_rcp_f32_e32 v176, v176
	v_rcp_f32_e32 v177, v177
	v_rcp_f32_e32 v178, v178
	v_rcp_f32_e32 v179, v179
	v_rcp_f32_e32 v180, v180
	v_rcp_f32_e32 v181, v181
	v_rcp_f32_e32 v182, v182
	v_rcp_f32_e32 v183, v183
	v_rcp_f32_e32 v184, v184
	v_rcp_f32_e32 v185, v185
	s_and_b64 vcc, exec, s[4:5]
	s_cbranch_vccz .Lrb_p0
	ds_write_b32 v161, v170 offset:32768
	ds_write_b32 v161, v171 offset:33024
	ds_write_b32 v161, v172 offset:33280
	ds_write_b32 v161, v173 offset:33536
	ds_write_b32 v161, v174 offset:32832
	ds_write_b32 v161, v175 offset:33088
	ds_write_b32 v161, v176 offset:33344
	ds_write_b32 v161, v177 offset:33600
	ds_write_b32 v161, v178 offset:32896
	ds_write_b32 v161, v179 offset:33152
	ds_write_b32 v161, v180 offset:33408
	ds_write_b32 v161, v181 offset:33664
	ds_write_b32 v161, v182 offset:32960
	ds_write_b32 v161, v183 offset:33216
	ds_write_b32 v161, v184 offset:33472
	ds_write_b32 v161, v185 offset:33728
	s_branch .Lrb_done
.Lrb_p0:
	v_mul_f32_e32 v170, 0xbf1b4598, v170
	v_mul_f32_e32 v171, 0xbf1b4598, v171
	v_mul_f32_e32 v172, 0xbf1b4598, v172
	v_mul_f32_e32 v173, 0xbf1b4598, v173
	v_mul_f32_e32 v174, 0xbf1b4598, v174
	v_mul_f32_e32 v175, 0xbf1b4598, v175
	v_mul_f32_e32 v176, 0xbf1b4598, v176
	v_mul_f32_e32 v177, 0xbf1b4598, v177
	v_mul_f32_e32 v178, 0xbf1b4598, v178
	v_mul_f32_e32 v179, 0xbf1b4598, v179
	v_mul_f32_e32 v180, 0xbf1b4598, v180
	v_mul_f32_e32 v181, 0xbf1b4598, v181
	v_mul_f32_e32 v182, 0xbf1b4598, v182
	v_mul_f32_e32 v183, 0xbf1b4598, v183
	v_mul_f32_e32 v184, 0xbf1b4598, v184
	v_mul_f32_e32 v185, 0xbf1b4598, v185
	v_mul_f32_e32 v170, 0x3fb8aa3b, v170
	v_mul_f32_e32 v171, 0x3fb8aa3b, v171
	v_mul_f32_e32 v172, 0x3fb8aa3b, v172
	v_mul_f32_e32 v173, 0x3fb8aa3b, v173
	v_mul_f32_e32 v174, 0x3fb8aa3b, v174
	v_mul_f32_e32 v175, 0x3fb8aa3b, v175
	v_mul_f32_e32 v176, 0x3fb8aa3b, v176
	v_mul_f32_e32 v177, 0x3fb8aa3b, v177
	v_mul_f32_e32 v178, 0x3fb8aa3b, v178
	v_mul_f32_e32 v179, 0x3fb8aa3b, v179
	v_mul_f32_e32 v180, 0x3fb8aa3b, v180
	v_mul_f32_e32 v181, 0x3fb8aa3b, v181
	v_mul_f32_e32 v182, 0x3fb8aa3b, v182
	v_mul_f32_e32 v183, 0x3fb8aa3b, v183
	v_mul_f32_e32 v184, 0x3fb8aa3b, v184
	v_mul_f32_e32 v185, 0x3fb8aa3b, v185
	v_exp_f32_e32 v170, v170
	v_exp_f32_e32 v171, v171
	v_exp_f32_e32 v172, v172
	v_exp_f32_e32 v173, v173
	v_exp_f32_e32 v174, v174
	v_exp_f32_e32 v175, v175
	v_exp_f32_e32 v176, v176
	v_exp_f32_e32 v177, v177
	v_exp_f32_e32 v178, v178
	v_exp_f32_e32 v179, v179
	v_exp_f32_e32 v180, v180
	v_exp_f32_e32 v181, v181
	v_exp_f32_e32 v182, v182
	v_exp_f32_e32 v183, v183
	v_exp_f32_e32 v184, v184
	v_exp_f32_e32 v185, v185
	ds_write_b32 v161, v170 offset:16384
	ds_write_b32 v161, v171 offset:16640
	ds_write_b32 v161, v172 offset:16896
	ds_write_b32 v161, v173 offset:17152
	ds_write_b32 v161, v174 offset:16448
	ds_write_b32 v161, v175 offset:16704
	ds_write_b32 v161, v176 offset:16960
	ds_write_b32 v161, v177 offset:17216
	ds_write_b32 v161, v178 offset:16512
	ds_write_b32 v161, v179 offset:16768
	ds_write_b32 v161, v180 offset:17024
	ds_write_b32 v161, v181 offset:17280
	ds_write_b32 v161, v182 offset:16576
	ds_write_b32 v161, v183 offset:16832
	ds_write_b32 v161, v184 offset:17088
	ds_write_b32 v161, v185 offset:17344
.Lrb_done:
	v_add_u32_e32 v64, 0x8000, v91
	v_add_co_u32_e64 v16, s[26:27], s34, 8
	s_waitcnt lgkmcnt(0)
	s_barrier
	ds_read2_b32 v[58:59], v64 offset1:16
	v_readfirstlane_b32 s30, v16
	v_add_u32_e32 v16, 0x2000, v91
	ds_read2_b32 v[56:57], v16 offset1:16
	ds_read2_b32 v[60:61], v91 offset1:16
	s_waitcnt lgkmcnt(2)
	v_add_f32_e32 v62, -1.0, v58
	v_fma_f32 v62, v128, v62, 1.0
	s_and_b64 s[28:29], s[26:27], exec
	s_waitcnt lgkmcnt(1)
	v_mul_f32_e32 v65, v127, v56
	v_mul_f32_e32 v56, v56, v62
	s_waitcnt lgkmcnt(0)
	v_mul_f32_e32 v60, v60, v56
	v_fma_f32 v66, v129, v60, 0
	v_add_f32_e32 v60, -1.0, v59
	v_fma_f32 v60, v131, v60, 1.0
	v_mul_f32_e32 v60, v57, v60
	ds_write2_b32 v16, v56, v60 offset1:16
	v_mul_f32_e32 v62, v61, v60
	ds_read2_b32 v[60:61], v64 offset0:32 offset1:48
	v_mul_f32_e32 v67, v130, v57
	ds_read2_b32 v[56:57], v16 offset0:32 offset1:48
	v_fmac_f32_e32 v66, v132, v62
	ds_read2_b32 v[62:63], v91 offset0:32 offset1:48
	s_waitcnt lgkmcnt(2)
	v_add_f32_e32 v70, -1.0, v60
	v_fma_f32 v70, v134, v70, 1.0
	v_mul_f32_e32 v68, v67, v67
	s_waitcnt lgkmcnt(1)
	v_mul_f32_e32 v69, v133, v56
	v_mul_f32_e32 v56, v56, v70
	v_fmac_f32_e32 v68, v65, v65
	s_waitcnt lgkmcnt(0)
	v_mul_f32_e32 v62, v62, v56
	v_add_f32_e32 v70, -1.0, v61
	v_fmac_f32_e32 v68, v69, v69
	v_fmac_f32_e32 v66, v135, v62
	v_mul_f32_e32 v62, v136, v57
	v_fma_f32 v70, v137, v70, 1.0
	v_fmac_f32_e32 v68, v62, v62
	v_mul_f32_e32 v57, v57, v70
	ds_write2_b32 v16, v56, v57 offset0:32 offset1:48
	v_add_f32_dpp v16, v68, v68 quad_perm:[1,0,3,2] row_mask:0xf bank_mask:0xf bound_ctrl:1
	v_mul_f32_e32 v56, v63, v57
	s_cselect_b32 s28, s30, s34
	v_add_f32_dpp v16, v16, v16 quad_perm:[2,3,0,1] row_mask:0xf bank_mask:0xf bound_ctrl:1
	s_cselect_b32 s29, 7, 0x1ff
	s_sub_i32 s29, s29, s28
	v_add_f32_dpp v16, v16, v16 row_half_mirror row_mask:0xf bank_mask:0xf bound_ctrl:1
	s_and_b64 s[26:27], s[26:27], exec
	v_fmac_f32_e32 v66, v138, v56
	v_add_f32_dpp v16, v16, v16 row_mirror row_mask:0xf bank_mask:0xf bound_ctrl:1
	v_sqrt_f32_e32 v16, v16
	s_cselect_b32 s31, 0x4000, 0
	s_and_b64 s[26:27], s[64:65], exec
	v_add_f32_dpp v56, v66, v66 quad_perm:[1,0,3,2] row_mask:0xf bank_mask:0xf bound_ctrl:1
	v_max_f32_e32 v16, 0x2b8cbccc, v16
	v_rcp_f32_e32 v57, v16
	s_cselect_b32 s26, s28, s29
	v_add_f32_dpp v16, v56, v56 quad_perm:[2,3,0,1] row_mask:0xf bank_mask:0xf bound_ctrl:1
	s_lshl_b32 s35, s26, 5
	v_mul_f32_e32 v63, v65, v57
	v_mul_f32_e32 v65, v67, v57
	v_mul_f32_e32 v58, v58, v63
	v_mul_f32_e32 v59, v59, v65
	v_add_f32_dpp v16, v16, v16 row_half_mirror row_mask:0xf bank_mask:0xf bound_ctrl:1
	v_add_u32_e32 v66, 0x6000, v91
	ds_write2_b32 v64, v58, v59 offset1:16
	v_mul_f32_e32 v58, v69, v57
	v_mul_f32_e32 v57, v62, v57
	s_add_i32 s35, s35, s31
	v_mov_b32_dpp v56, v16 row_mirror row_mask:0xf bank_mask:0xf bound_ctrl:1
	v_mul_f32_e32 v59, v60, v58
	ds_write2_b32 v66, v58, v57 offset0:32 offset1:48
	v_mul_f32_e32 v57, v61, v57
	ds_write2_b32 v66, v63, v65 offset1:16
	ds_write2_b32 v64, v59, v57 offset0:32 offset1:48
	s_and_saveexec_b64 s[26:27], s[16:17]
	s_cbranch_execz .LBB0_490
	v_add_u32_e32 v58, s35, v87
	v_ashrrev_i32_e32 v59, 31, v58
	v_lshlrev_b64 v[58:59], 5, v[58:59]
	v_lshl_add_u64 v[58:59], s[78:79], 0, v[58:59]
	v_add_f32_e32 v16, v16, v56
	global_store_dword v[58:59], v16, off

.LBB0_492:
	s_or_b64 exec, exec, s[26:27]
	s_waitcnt lgkmcnt(0)
	s_cmpk_lg_i32 s34, 0x1ff
	s_cselect_b64 s[28:29], -1, 0
	s_cmpk_eq_i32 s34, 0x1ff
	s_barrier
	s_cbranch_scc1 .LBB0_514
	s_add_i32 s26, s34, 9
	s_add_i32 s27, s34, 1
	s_cmp_lt_u32 s30, 7
	s_cselect_b32 s30, s26, s27
	s_cselect_b32 s26, 7, 0x1ff
	s_cselect_b32 s37, 0x100, s47
	s_cselect_b32 s36, 0x4000, 0
	s_sub_i32 s31, s26, s30
	s_and_b64 s[26:27], s[64:65], exec
	s_cselect_b32 s26, s30, s31
	s_lshl_b32 s38, s26, 5
	s_waitcnt vmcnt(3)
	s_add_i32 s26, s36, s38
	s_mul_i32 s26, s26, s83
	s_mov_b32 s27, 0
	v_lshl_add_u64 v[56:57], v[218:219], 0, s[26:27]
	v_lshl_add_u64 v[58:59], v[220:221], 0, s[26:27]
	v_lshl_add_u64 v[60:61], v[222:223], 0, s[26:27]
	v_lshl_add_u64 v[62:63], v[244:245], 0, s[26:27]
	global_load_dwordx4 v[20:23], v[56:57], off
	global_load_dwordx4 v[52:55], v[58:59], off
	global_load_dwordx4 v[28:31], v[60:61], off
	global_load_dwordx4 v[0:3], v[62:63], off
	s_and_saveexec_b64 s[30:31], s[14:15]
	s_cbranch_execz .Lri_skip4
	v_lshl_add_u64 v[64:65], v[246:247], 0, s[26:27]
	global_load_dwordx4 v[48:51], v[64:65], off

.LBB0_650:
	s_or_b64 exec, exec, s[22:23]
	s_mul_hi_i32 s19, s34, 0x2080000
	s_mul_i32 s34, s34, 0x2080000
	s_add_u32 s22, s16, s34
	s_addc_u32 s23, s17, s19
	s_ashr_i32 s19, s18, 31
	s_lshl_b64 s[16:17], s[18:19], 2
	s_add_u32 s16, s20, s16
	s_addc_u32 s17, s21, s17
	s_lshl_b32 s18, s31, 2
	s_add_u32 s42, s16, s18
	v_ashrrev_i32_e32 v4, 3, v82
	s_addc_u32 s43, s17, 0
	s_lshl_b32 s18, s36, 1
	v_lshl_add_u32 v74, v4, 2, 0
	v_ashrrev_i32_e32 v4, 4, v82
	s_add_u32 s18, s22, s18
	v_lshl_add_u32 v75, v82, 3, 0
	v_lshl_add_u32 v77, v4, 2, 0
	v_lshlrev_b32_e32 v4, 2, v82
	s_addc_u32 s19, s23, 0
	s_lshl_b32 s20, s35, 1
	v_add_u32_e32 v80, v85, v83
	s_movk_i32 s22, 0xffde
	v_and_b32_e32 v12, 15, v82
	v_sub_u32_e32 v78, v75, v4
	s_add_u32 s18, s18, s20
	v_mad_u64_u32 v[4:5], s[20:21], v80, s22, v[82:83]
	v_add_u32_e32 v81, v88, v87
	v_add_u32_e32 v83, v90, v89
	s_addc_u32 s19, s19, 0
	v_mad_u64_u32 v[6:7], s[20:21], v81, s22, v[16:17]
	v_mad_u64_u32 v[10:11], s[20:21], v83, s22, v[84:85]
	v_add_u32_e32 v84, v8, v1
	v_add_u32_e32 v85, v9, v3
	v_lshlrev_b32_e32 v16, 1, v12
	v_mad_u64_u32 v[0:1], s[20:21], v84, s22, v[0:1]
	v_mad_u64_u32 v[2:3], s[20:21], v85, s22, v[2:3]
	v_lshl_add_u64 v[8:9], s[18:19], 0, v[16:17]
	s_mov_b64 s[18:19], 0x928000
	v_lshl_add_u64 v[50:51], v[8:9], 0, s[18:19]
	v_lshlrev_b32_e32 v1, 9, v80
	v_lshlrev_b32_e32 v3, 5, v4
	s_movk_i32 s19, 0xfe40
	v_add3_u32 v1, 0, v1, v3
	v_mul_lo_u32 v5, v80, s19
	s_mov_b32 s18, 0x8000
	v_add_u32_e32 v3, 0x3dc0, v1
	v_subrev_u32_e32 v7, 64, v1
	v_add3_u32 v8, v1, v5, s18
	v_lshlrev_b32_e32 v1, 9, v81
	v_lshlrev_b32_e32 v5, 5, v6
	v_lshl_add_u32 v76, v12, 4, 0
	v_add3_u32 v1, 0, v1, v5
	v_mul_lo_u32 v5, v81, s19
	v_mad_u32_u24 v86, v12, 48, v76
	v_add_u32_e32 v9, 0x3dc0, v1
	v_subrev_u32_e32 v11, 64, v1
	v_add3_u32 v12, v1, v5, s18
	v_lshlrev_b32_e32 v1, 9, v83
	v_lshlrev_b32_e32 v5, 5, v10
	v_add3_u32 v1, 0, v1, v5
	v_mul_lo_u32 v5, v83, s19
	v_add_u32_e32 v13, 0x3dc0, v1
	v_subrev_u32_e32 v14, 64, v1
	v_add3_u32 v15, v1, v5, s18
	v_lshlrev_b32_e32 v1, 9, v84
	v_lshlrev_b32_e32 v5, 5, v0
	v_add3_u32 v1, 0, v1, v5
	v_mul_lo_u32 v5, v84, s19
	v_add_u32_e32 v16, 0x3dc0, v1
	v_subrev_u32_e32 v38, 64, v1
	v_add3_u32 v39, v1, v5, s18
	v_lshlrev_b32_e32 v1, 9, v85
	v_lshlrev_b32_e32 v5, 5, v2
	v_add3_u32 v1, 0, v1, v5
	v_mul_lo_u32 v5, v85, s19
	v_mov_b32_e32 v43, s28
	v_mov_b32_e32 v44, s29
	v_cmp_gt_u32_e32 vcc, 18, v4
	v_add_u32_e32 v40, 0x3dc0, v1
	v_subrev_u32_e32 v41, 64, v1
	v_add3_u32 v42, v1, v5, s18
	v_cndmask_b32_e32 v1, v43, v44, vcc
	v_mov_b32_e32 v45, s30
	v_cmp_gt_i32_e64 s[18:19], 2, v4
	v_cmp_gt_u32_e64 s[20:21], 18, v6
	v_cmp_gt_i32_e64 s[22:23], 2, v6
	v_cndmask_b32_e64 v1, v1, v45, s[18:19]
	v_lshl_add_u32 v4, v4, 3, v1
	v_cndmask_b32_e64 v1, v43, v44, s[20:21]
	v_ashrrev_i32_e32 v5, 31, v4
	v_cndmask_b32_e64 v1, v1, v45, s[22:23]
	v_cmp_gt_u32_e64 s[24:25], 18, v10
	v_lshl_add_u64 v[52:53], v[4:5], 1, s[44:45]
	v_lshl_add_u32 v4, v6, 3, v1
	v_cndmask_b32_e64 v1, v43, v44, s[24:25]
	v_cmp_gt_i32_e64 s[26:27], 2, v10
	v_ashrrev_i32_e32 v5, 31, v4
	v_cmp_gt_u32_e64 s[28:29], 18, v0
	v_cndmask_b32_e64 v1, v1, v45, s[26:27]
	v_lshl_add_u64 v[54:55], v[4:5], 1, s[44:45]
	v_lshl_add_u32 v4, v10, 3, v1
	v_cndmask_b32_e64 v1, v43, v44, s[28:29]
	v_cmp_gt_i32_e64 s[30:31], 2, v0
	v_cmp_gt_u32_e64 s[34:35], 18, v2
	v_cmp_gt_i32_e64 s[36:37], 2, v2
	v_cndmask_b32_e64 v1, v1, v45, s[30:31]
	v_lshl_add_u32 v0, v0, 3, v1
	v_ashrrev_i32_e32 v1, 31, v0
	v_lshl_add_u64 v[58:59], v[0:1], 1, s[44:45]
	v_cndmask_b32_e64 v0, v43, v44, s[34:35]
	v_cndmask_b32_e64 v0, v0, v45, s[36:37]
	v_lshl_add_u32 v0, v2, 3, v0
	v_ashrrev_i32_e32 v1, 31, v0
	v_lshl_add_u64 v[60:61], v[0:1], 1, s[44:45]
	v_cndmask_b32_e32 v0, v3, v7, vcc
	v_cndmask_b32_e64 v87, v0, v8, s[18:19]
	v_cndmask_b32_e64 v0, v9, v11, s[20:21]
	v_cndmask_b32_e64 v88, v0, v12, s[22:23]
	v_cndmask_b32_e64 v0, v13, v14, s[24:25]
	v_cndmask_b32_e64 v89, v0, v15, s[26:27]
	v_cndmask_b32_e64 v0, v16, v38, s[28:29]
	s_movk_i32 s16, 0x200
	v_ashrrev_i32_e32 v5, 31, v4
	v_cndmask_b32_e64 v90, v0, v39, s[30:31]
	v_cndmask_b32_e64 v0, v40, v41, s[34:35]
	v_mov_b32_e32 v70, 0
	v_add_u32_e32 v79, 0x9200, v78
	v_cmp_gt_i32_e64 s[16:17], s16, v82
	v_lshl_add_u64 v[56:57], v[4:5], 1, s[44:45]
	v_cndmask_b32_e64 v91, v0, v42, s[36:37]
	s_mov_b32 s22, 0
	v_mov_b32_e32 v71, v70
	v_mov_b32_e32 v62, v70
	v_mov_b32_e32 v63, v70
	v_mov_b32_e32 v64, v70
	v_mov_b32_e32 v65, v70
	v_mov_b32_e32 v69, v70
	v_mov_b32_e32 v67, v70
	s_waitcnt lgkmcnt(0)
	s_barrier
	v_mov_b32_e32 v200, 0
	v_mov_b32_e32 v201, 0
	v_mov_b32_e32 v202, 0
	v_mov_b32_e32 v203, 0
	v_mov_b32_e32 v204, 0
	v_mov_b32_e32 v205, 0
	v_mov_b32_e32 v206, 0
	v_mov_b32_e32 v207, 0
	s_branch .LBB0_653

.LBB0_667:
	s_andn2_b64 vcc, exec, s[38:39]
	s_cbranch_vccnz .Lmb_fwd
	ds_read_b128 v[130:133], v76 offset:15872
	ds_read_b128 v[134:137], v76 offset:16128
	ds_read_b32 v162, v77 offset:34752
	ds_read_b32 v164, v17 offset:34940
	ds_read_b128 v[138:141], v76 offset:15360
	ds_read_b128 v[142:145], v76 offset:15616
	ds_read_b32 v166, v77 offset:34688
	ds_read_b32 v168, v17 offset:34936
	ds_read_b128 v[146:149], v76 offset:32256
	ds_read_b128 v[150:153], v76 offset:32512
	s_waitcnt lgkmcnt(6)
	v_pk_mul_f32 v[170:171], v[200:201], v[164:165] op_sel_hi:[1,0]
	v_pk_mul_f32 v[172:173], v[202:203], v[164:165] op_sel_hi:[1,0]
	v_pk_mul_f32 v[174:175], v[204:205], v[164:165] op_sel_hi:[1,0]
	v_pk_mul_f32 v[176:177], v[206:207], v[164:165] op_sel_hi:[1,0]
	v_pk_fma_f32 v[200:201], v[130:131], v[162:163], v[170:171] op_sel_hi:[1,0,1]
	v_pk_fma_f32 v[202:203], v[132:133], v[162:163], v[172:173] op_sel_hi:[1,0,1]
	v_pk_fma_f32 v[204:205], v[134:135], v[162:163], v[174:175] op_sel_hi:[1,0,1]
	v_pk_fma_f32 v[206:207], v[136:137], v[162:163], v[176:177] op_sel_hi:[1,0,1]
	ds_read_b128 v[130:133], v76 offset:14848
	ds_read_b128 v[134:137], v76 offset:15104
	ds_read_b32 v162, v77 offset:34624
	ds_read_b32 v164, v17 offset:34932
	ds_read_b128 v[154:157], v76 offset:31744
	ds_read_b128 v[158:161], v76 offset:32000
	s_waitcnt lgkmcnt(6)
	v_pk_mul_f32 v[170:171], v[200:201], v[168:169] op_sel_hi:[1,0]
	v_pk_mul_f32 v[178:179], v[200:201], v[146:147]
	v_pk_mul_f32 v[172:173], v[202:203], v[168:169] op_sel_hi:[1,0]
	v_pk_fma_f32 v[178:179], v[202:203], v[148:149], v[178:179]
	v_pk_mul_f32 v[174:175], v[204:205], v[168:169] op_sel_hi:[1,0]
	v_pk_fma_f32 v[178:179], v[204:205], v[150:151], v[178:179]
	v_pk_mul_f32 v[176:177], v[206:207], v[168:169] op_sel_hi:[1,0]
	v_pk_fma_f32 v[178:179], v[206:207], v[152:153], v[178:179]
	v_pk_fma_f32 v[200:201], v[138:139], v[166:167], v[170:171] op_sel_hi:[1,0,1]
	v_pk_fma_f32 v[202:203], v[140:141], v[166:167], v[172:173] op_sel_hi:[1,0,1]
	v_pk_fma_f32 v[204:205], v[142:143], v[166:167], v[174:175] op_sel_hi:[1,0,1]
	v_pk_fma_f32 v[206:207], v[144:145], v[166:167], v[176:177] op_sel_hi:[1,0,1]
	v_add_f32_e32 v180, v178, v179
	ds_write_b32 v79, v180 offset:31744
	ds_read_b128 v[138:141], v76 offset:14336
	ds_read_b128 v[142:145], v76 offset:14592
	ds_read_b32 v166, v77 offset:34560
	ds_read_b32 v168, v17 offset:34928
	ds_read_b128 v[146:149], v76 offset:31232
	ds_read_b128 v[150:153], v76 offset:31488
	s_waitcnt lgkmcnt(7)
	v_pk_mul_f32 v[170:171], v[200:201], v[164:165] op_sel_hi:[1,0]
	v_pk_mul_f32 v[178:179], v[200:201], v[154:155]
	v_pk_mul_f32 v[172:173], v[202:203], v[164:165] op_sel_hi:[1,0]
	v_pk_fma_f32 v[178:179], v[202:203], v[156:157], v[178:179]
	v_pk_mul_f32 v[174:175], v[204:205], v[164:165] op_sel_hi:[1,0]
	v_pk_fma_f32 v[178:179], v[204:205], v[158:159], v[178:179]
	v_pk_mul_f32 v[176:177], v[206:207], v[164:165] op_sel_hi:[1,0]
	v_pk_fma_f32 v[178:179], v[206:207], v[160:161], v[178:179]
	v_pk_fma_f32 v[200:201], v[130:131], v[162:163], v[170:171] op_sel_hi:[1,0,1]
	v_pk_fma_f32 v[202:203], v[132:133], v[162:163], v[172:173] op_sel_hi:[1,0,1]
	v_pk_fma_f32 v[204:205], v[134:135], v[162:163], v[174:175] op_sel_hi:[1,0,1]
	v_pk_fma_f32 v[206:207], v[136:137], v[162:163], v[176:177] op_sel_hi:[1,0,1]
	v_add_f32_e32 v180, v178, v179
	ds_write_b32 v79, v180 offset:30720
	ds_read_b128 v[130:133], v76 offset:13824
	ds_read_b128 v[134:137], v76 offset:14080
	ds_read_b32 v162, v77 offset:34496
	ds_read_b32 v164, v17 offset:34924
	ds_read_b128 v[154:157], v76 offset:30720
	ds_read_b128 v[158:161], v76 offset:30976
	s_waitcnt lgkmcnt(7)
	v_pk_mul_f32 v[170:171], v[200:201], v[168:169] op_sel_hi:[1,0]
	v_pk_mul_f32 v[178:179], v[200:201], v[146:147]
	v_pk_mul_f32 v[172:173], v[202:203], v[168:169] op_sel_hi:[1,0]
	v_pk_fma_f32 v[178:179], v[202:203], v[148:149], v[178:179]
	v_pk_mul_f32 v[174:175], v[204:205], v[168:169] op_sel_hi:[1,0]
	v_pk_fma_f32 v[178:179], v[204:205], v[150:151], v[178:179]
	v_pk_mul_f32 v[176:177], v[206:207], v[168:169] op_sel_hi:[1,0]
	v_pk_fma_f32 v[178:179], v[206:207], v[152:153], v[178:179]
	v_pk_fma_f32 v[200:201], v[138:139], v[166:167], v[170:171] op_sel_hi:[1,0,1]
	v_pk_fma_f32 v[202:203], v[140:141], v[166:167], v[172:173] op_sel_hi:[1,0,1]
	v_pk_fma_f32 v[204:205], v[142:143], v[166:167], v[174:175] op_sel_hi:[1,0,1]
	v_pk_fma_f32 v[206:207], v[144:145], v[166:167], v[176:177] op_sel_hi:[1,0,1]
	v_add_f32_e32 v180, v178, v179
	ds_write_b32 v79, v180 offset:29696
	ds_read_b128 v[138:141], v76 offset:13312
	ds_read_b128 v[142:145], v76 offset:13568
	ds_read_b32 v166, v77 offset:34432
	ds_read_b32 v168, v17 offset:34920
	ds_read_b128 v[146:149], v76 offset:30208
	ds_read_b128 v[150:153], v76 offset:30464
	s_waitcnt lgkmcnt(7)
	v_pk_mul_f32 v[170:171], v[200:201], v[164:165] op_sel_hi:[1,0]
	v_pk_mul_f32 v[178:179], v[200:201], v[154:155]
	v_pk_mul_f32 v[172:173], v[202:203], v[164:165] op_sel_hi:[1,0]
	v_pk_fma_f32 v[178:179], v[202:203], v[156:157], v[178:179]
	v_pk_mul_f32 v[174:175], v[204:205], v[164:165] op_sel_hi:[1,0]
	v_pk_fma_f32 v[178:179], v[204:205], v[158:159], v[178:179]
	v_pk_mul_f32 v[176:177], v[206:207], v[164:165] op_sel_hi:[1,0]
	v_pk_fma_f32 v[178:179], v[206:207], v[160:161], v[178:179]
	v_pk_fma_f32 v[200:201], v[130:131], v[162:163], v[170:171] op_sel_hi:[1,0,1]
	v_pk_fma_f32 v[202:203], v[132:133], v[162:163], v[172:173] op_sel_hi:[1,0,1]
	v_pk_fma_f32 v[204:205], v[134:135], v[162:163], v[174:175] op_sel_hi:[1,0,1]
	v_pk_fma_f32 v[206:207], v[136:137], v[162:163], v[176:177] op_sel_hi:[1,0,1]
	v_add_f32_e32 v180, v178, v179
	ds_write_b32 v79, v180 offset:28672
	ds_read_b128 v[130:133], v76 offset:12800
	ds_read_b128 v[134:137], v76 offset:13056
	ds_read_b32 v162, v77 offset:34368
	ds_read_b32 v164, v17 offset:34916
	ds_read_b128 v[154:157], v76 offset:29696
	ds_read_b128 v[158:161], v76 offset:29952
	s_waitcnt lgkmcnt(7)
	v_pk_mul_f32 v[170:171], v[200:201], v[168:169] op_sel_hi:[1,0]
	v_pk_mul_f32 v[178:179], v[200:201], v[146:147]
	v_pk_mul_f32 v[172:173], v[202:203], v[168:169] op_sel_hi:[1,0]
	v_pk_fma_f32 v[178:179], v[202:203], v[148:149], v[178:179]
	v_pk_mul_f32 v[174:175], v[204:205], v[168:169] op_sel_hi:[1,0]
	v_pk_fma_f32 v[178:179], v[204:205], v[150:151], v[178:179]
	v_pk_mul_f32 v[176:177], v[206:207], v[168:169] op_sel_hi:[1,0]
	v_pk_fma_f32 v[178:179], v[206:207], v[152:153], v[178:179]
	v_pk_fma_f32 v[200:201], v[138:139], v[166:167], v[170:171] op_sel_hi:[1,0,1]
	v_pk_fma_f32 v[202:203], v[140:141], v[166:167], v[172:173] op_sel_hi:[1,0,1]
	v_pk_fma_f32 v[204:205], v[142:143], v[166:167], v[174:175] op_sel_hi:[1,0,1]
	v_pk_fma_f32 v[206:207], v[144:145], v[166:167], v[176:177] op_sel_hi:[1,0,1]
	v_add_f32_e32 v180, v178, v179
	ds_write_b32 v79, v180 offset:27648
	ds_read_b128 v[138:141], v76 offset:12288
	ds_read_b128 v[142:145], v76 offset:12544
	ds_read_b32 v166, v77 offset:34304
	ds_read_b32 v168, v17 offset:34912
	ds_read_b128 v[146:149], v76 offset:29184
	ds_read_b128 v[150:153], v76 offset:29440
	s_waitcnt lgkmcnt(7)
	v_pk_mul_f32 v[170:171], v[200:201], v[164:165] op_sel_hi:[1,0]
	v_pk_mul_f32 v[178:179], v[200:201], v[154:155]
	v_pk_mul_f32 v[172:173], v[202:203], v[164:165] op_sel_hi:[1,0]
	v_pk_fma_f32 v[178:179], v[202:203], v[156:157], v[178:179]
	v_pk_mul_f32 v[174:175], v[204:205], v[164:165] op_sel_hi:[1,0]
	v_pk_fma_f32 v[178:179], v[204:205], v[158:159], v[178:179]
	v_pk_mul_f32 v[176:177], v[206:207], v[164:165] op_sel_hi:[1,0]
	v_pk_fma_f32 v[178:179], v[206:207], v[160:161], v[178:179]
	v_pk_fma_f32 v[200:201], v[130:131], v[162:163], v[170:171] op_sel_hi:[1,0,1]
	v_pk_fma_f32 v[202:203], v[132:133], v[162:163], v[172:173] op_sel_hi:[1,0,1]
	v_pk_fma_f32 v[204:205], v[134:135], v[162:163], v[174:175] op_sel_hi:[1,0,1]
	v_pk_fma_f32 v[206:207], v[136:137], v[162:163], v[176:177] op_sel_hi:[1,0,1]
	v_add_f32_e32 v180, v178, v179
	ds_write_b32 v79, v180 offset:26624
	ds_read_b128 v[130:133], v76 offset:11776
	ds_read_b128 v[134:137], v76 offset:12032
	ds_read_b32 v162, v77 offset:34240
	ds_read_b32 v164, v17 offset:34908
	ds_read_b128 v[154:157], v76 offset:28672
	ds_read_b128 v[158:161], v76 offset:28928
	s_waitcnt lgkmcnt(7)
	v_pk_mul_f32 v[170:171], v[200:201], v[168:169] op_sel_hi:[1,0]
	v_pk_mul_f32 v[178:179], v[200:201], v[146:147]
	v_pk_mul_f32 v[172:173], v[202:203], v[168:169] op_sel_hi:[1,0]
	v_pk_fma_f32 v[178:179], v[202:203], v[148:149], v[178:179]
	v_pk_mul_f32 v[174:175], v[204:205], v[168:169] op_sel_hi:[1,0]
	v_pk_fma_f32 v[178:179], v[204:205], v[150:151], v[178:179]
	v_pk_mul_f32 v[176:177], v[206:207], v[168:169] op_sel_hi:[1,0]
	v_pk_fma_f32 v[178:179], v[206:207], v[152:153], v[178:179]
	v_pk_fma_f32 v[200:201], v[138:139], v[166:167], v[170:171] op_sel_hi:[1,0,1]
	v_pk_fma_f32 v[202:203], v[140:141], v[166:167], v[172:173] op_sel_hi:[1,0,1]
	v_pk_fma_f32 v[204:205], v[142:143], v[166:167], v[174:175] op_sel_hi:[1,0,1]
	v_pk_fma_f32 v[206:207], v[144:145], v[166:167], v[176:177] op_sel_hi:[1,0,1]
	v_add_f32_e32 v180, v178, v179
	ds_write_b32 v79, v180 offset:25600
	ds_read_b128 v[138:141], v76 offset:11264
	ds_read_b128 v[142:145], v76 offset:11520
	ds_read_b32 v166, v77 offset:34176
	ds_read_b32 v168, v17 offset:34904
	ds_read_b128 v[146:149], v76 offset:28160
	ds_read_b128 v[150:153], v76 offset:28416
	s_waitcnt lgkmcnt(7)
	v_pk_mul_f32 v[170:171], v[200:201], v[164:165] op_sel_hi:[1,0]
	v_pk_mul_f32 v[178:179], v[200:201], v[154:155]
	v_pk_mul_f32 v[172:173], v[202:203], v[164:165] op_sel_hi:[1,0]
	v_pk_fma_f32 v[178:179], v[202:203], v[156:157], v[178:179]
	v_pk_mul_f32 v[174:175], v[204:205], v[164:165] op_sel_hi:[1,0]
	v_pk_fma_f32 v[178:179], v[204:205], v[158:159], v[178:179]
	v_pk_mul_f32 v[176:177], v[206:207], v[164:165] op_sel_hi:[1,0]
	v_pk_fma_f32 v[178:179], v[206:207], v[160:161], v[178:179]
	v_pk_fma_f32 v[200:201], v[130:131], v[162:163], v[170:171] op_sel_hi:[1,0,1]
	v_pk_fma_f32 v[202:203], v[132:133], v[162:163], v[172:173] op_sel_hi:[1,0,1]
	v_pk_fma_f32 v[204:205], v[134:135], v[162:163], v[174:175] op_sel_hi:[1,0,1]
	v_pk_fma_f32 v[206:207], v[136:137], v[162:163], v[176:177] op_sel_hi:[1,0,1]
	v_add_f32_e32 v180, v178, v179
	ds_write_b32 v79, v180 offset:24576
	ds_read_b128 v[130:133], v76 offset:10752
	ds_read_b128 v[134:137], v76 offset:11008
	ds_read_b32 v162, v77 offset:34112
	ds_read_b32 v164, v17 offset:34900
	ds_read_b128 v[154:157], v76 offset:27648
	ds_read_b128 v[158:161], v76 offset:27904
	s_waitcnt lgkmcnt(7)
	v_pk_mul_f32 v[170:171], v[200:201], v[168:169] op_sel_hi:[1,0]
	v_pk_mul_f32 v[178:179], v[200:201], v[146:147]
	v_pk_mul_f32 v[172:173], v[202:203], v[168:169] op_sel_hi:[1,0]
	v_pk_fma_f32 v[178:179], v[202:203], v[148:149], v[178:179]
	v_pk_mul_f32 v[174:175], v[204:205], v[168:169] op_sel_hi:[1,0]
	v_pk_fma_f32 v[178:179], v[204:205], v[150:151], v[178:179]
	v_pk_mul_f32 v[176:177], v[206:207], v[168:169] op_sel_hi:[1,0]
	v_pk_fma_f32 v[178:179], v[206:207], v[152:153], v[178:179]
	v_pk_fma_f32 v[200:201], v[138:139], v[166:167], v[170:171] op_sel_hi:[1,0,1]
	v_pk_fma_f32 v[202:203], v[140:141], v[166:167], v[172:173] op_sel_hi:[1,0,1]
	v_pk_fma_f32 v[204:205], v[142:143], v[166:167], v[174:175] op_sel_hi:[1,0,1]
	v_pk_fma_f32 v[206:207], v[144:145], v[166:167], v[176:177] op_sel_hi:[1,0,1]
	v_add_f32_e32 v180, v178, v179
	ds_write_b32 v79, v180 offset:23552
	ds_read_b128 v[138:141], v76 offset:10240
	ds_read_b128 v[142:145], v76 offset:10496
	ds_read_b32 v166, v77 offset:34048
	ds_read_b32 v168, v17 offset:34896
	ds_read_b128 v[146:149], v76 offset:27136
	ds_read_b128 v[150:153], v76 offset:27392
	s_waitcnt lgkmcnt(7)
	v_pk_mul_f32 v[170:171], v[200:201], v[164:165] op_sel_hi:[1,0]
	v_pk_mul_f32 v[178:179], v[200:201], v[154:155]
	v_pk_mul_f32 v[172:173], v[202:203], v[164:165] op_sel_hi:[1,0]
	v_pk_fma_f32 v[178:179], v[202:203], v[156:157], v[178:179]
	v_pk_mul_f32 v[174:175], v[204:205], v[164:165] op_sel_hi:[1,0]
	v_pk_fma_f32 v[178:179], v[204:205], v[158:159], v[178:179]
	v_pk_mul_f32 v[176:177], v[206:207], v[164:165] op_sel_hi:[1,0]
	v_pk_fma_f32 v[178:179], v[206:207], v[160:161], v[178:179]
	v_pk_fma_f32 v[200:201], v[130:131], v[162:163], v[170:171] op_sel_hi:[1,0,1]
	v_pk_fma_f32 v[202:203], v[132:133], v[162:163], v[172:173] op_sel_hi:[1,0,1]
	v_pk_fma_f32 v[204:205], v[134:135], v[162:163], v[174:175] op_sel_hi:[1,0,1]
	v_pk_fma_f32 v[206:207], v[136:137], v[162:163], v[176:177] op_sel_hi:[1,0,1]
	v_add_f32_e32 v180, v178, v179
	ds_write_b32 v79, v180 offset:22528
	ds_read_b128 v[130:133], v76 offset:9728
	ds_read_b128 v[134:137], v76 offset:9984
	ds_read_b32 v162, v77 offset:33984
	ds_read_b32 v164, v17 offset:34892
	ds_read_b128 v[154:157], v76 offset:26624
	ds_read_b128 v[158:161], v76 offset:26880
	s_waitcnt lgkmcnt(7)
	v_pk_mul_f32 v[170:171], v[200:201], v[168:169] op_sel_hi:[1,0]
	v_pk_mul_f32 v[178:179], v[200:201], v[146:147]
	v_pk_mul_f32 v[172:173], v[202:203], v[168:169] op_sel_hi:[1,0]
	v_pk_fma_f32 v[178:179], v[202:203], v[148:149], v[178:179]
	v_pk_mul_f32 v[174:175], v[204:205], v[168:169] op_sel_hi:[1,0]
	v_pk_fma_f32 v[178:179], v[204:205], v[150:151], v[178:179]
	v_pk_mul_f32 v[176:177], v[206:207], v[168:169] op_sel_hi:[1,0]
	v_pk_fma_f32 v[178:179], v[206:207], v[152:153], v[178:179]
	v_pk_fma_f32 v[200:201], v[138:139], v[166:167], v[170:171] op_sel_hi:[1,0,1]
	v_pk_fma_f32 v[202:203], v[140:141], v[166:167], v[172:173] op_sel_hi:[1,0,1]
	v_pk_fma_f32 v[204:205], v[142:143], v[166:167], v[174:175] op_sel_hi:[1,0,1]
	v_pk_fma_f32 v[206:207], v[144:145], v[166:167], v[176:177] op_sel_hi:[1,0,1]
	v_add_f32_e32 v180, v178, v179
	ds_write_b32 v79, v180 offset:21504
	ds_read_b128 v[138:141], v76 offset:9216
	ds_read_b128 v[142:145], v76 offset:9472
	ds_read_b32 v166, v77 offset:33920
	ds_read_b32 v168, v17 offset:34888
	ds_read_b128 v[146:149], v76 offset:26112
	ds_read_b128 v[150:153], v76 offset:26368
	s_waitcnt lgkmcnt(7)
	v_pk_mul_f32 v[170:171], v[200:201], v[164:165] op_sel_hi:[1,0]
	v_pk_mul_f32 v[178:179], v[200:201], v[154:155]
	v_pk_mul_f32 v[172:173], v[202:203], v[164:165] op_sel_hi:[1,0]
	v_pk_fma_f32 v[178:179], v[202:203], v[156:157], v[178:179]
	v_pk_mul_f32 v[174:175], v[204:205], v[164:165] op_sel_hi:[1,0]
	v_pk_fma_f32 v[178:179], v[204:205], v[158:159], v[178:179]
	v_pk_mul_f32 v[176:177], v[206:207], v[164:165] op_sel_hi:[1,0]
	v_pk_fma_f32 v[178:179], v[206:207], v[160:161], v[178:179]
	v_pk_fma_f32 v[200:201], v[130:131], v[162:163], v[170:171] op_sel_hi:[1,0,1]
	v_pk_fma_f32 v[202:203], v[132:133], v[162:163], v[172:173] op_sel_hi:[1,0,1]
	v_pk_fma_f32 v[204:205], v[134:135], v[162:163], v[174:175] op_sel_hi:[1,0,1]
	v_pk_fma_f32 v[206:207], v[136:137], v[162:163], v[176:177] op_sel_hi:[1,0,1]
	v_add_f32_e32 v180, v178, v179
	ds_write_b32 v79, v180 offset:20480
	ds_read_b128 v[130:133], v76 offset:8704
	ds_read_b128 v[134:137], v76 offset:8960
	ds_read_b32 v162, v77 offset:33856
	ds_read_b32 v164, v17 offset:34884
	ds_read_b128 v[154:157], v76 offset:25600
	ds_read_b128 v[158:161], v76 offset:25856
	s_waitcnt lgkmcnt(7)
	v_pk_mul_f32 v[170:171], v[200:201], v[168:169] op_sel_hi:[1,0]
	v_pk_mul_f32 v[178:179], v[200:201], v[146:147]
	v_pk_mul_f32 v[172:173], v[202:203], v[168:169] op_sel_hi:[1,0]
	v_pk_fma_f32 v[178:179], v[202:203], v[148:149], v[178:179]
	v_pk_mul_f32 v[174:175], v[204:205], v[168:169] op_sel_hi:[1,0]
	v_pk_fma_f32 v[178:179], v[204:205], v[150:151], v[178:179]
	v_pk_mul_f32 v[176:177], v[206:207], v[168:169] op_sel_hi:[1,0]
	v_pk_fma_f32 v[178:179], v[206:207], v[152:153], v[178:179]
	v_pk_fma_f32 v[200:201], v[138:139], v[166:167], v[170:171] op_sel_hi:[1,0,1]
	v_pk_fma_f32 v[202:203], v[140:141], v[166:167], v[172:173] op_sel_hi:[1,0,1]
	v_pk_fma_f32 v[204:205], v[142:143], v[166:167], v[174:175] op_sel_hi:[1,0,1]
	v_pk_fma_f32 v[206:207], v[144:145], v[166:167], v[176:177] op_sel_hi:[1,0,1]
	v_add_f32_e32 v180, v178, v179
	ds_write_b32 v79, v180 offset:19456
	ds_read_b128 v[138:141], v76 offset:8192
	ds_read_b128 v[142:145], v76 offset:8448
	ds_read_b32 v166, v77 offset:33792
	ds_read_b32 v168, v17 offset:34880
	ds_read_b128 v[146:149], v76 offset:25088
	ds_read_b128 v[150:153], v76 offset:25344
	s_waitcnt lgkmcnt(7)
	v_pk_mul_f32 v[170:171], v[200:201], v[164:165] op_sel_hi:[1,0]
	v_pk_mul_f32 v[178:179], v[200:201], v[154:155]
	v_pk_mul_f32 v[172:173], v[202:203], v[164:165] op_sel_hi:[1,0]
	v_pk_fma_f32 v[178:179], v[202:203], v[156:157], v[178:179]
	v_pk_mul_f32 v[174:175], v[204:205], v[164:165] op_sel_hi:[1,0]
	v_pk_fma_f32 v[178:179], v[204:205], v[158:159], v[178:179]
	v_pk_mul_f32 v[176:177], v[206:207], v[164:165] op_sel_hi:[1,0]
	v_pk_fma_f32 v[178:179], v[206:207], v[160:161], v[178:179]
	v_pk_fma_f32 v[200:201], v[130:131], v[162:163], v[170:171] op_sel_hi:[1,0,1]
	v_pk_fma_f32 v[202:203], v[132:133], v[162:163], v[172:173] op_sel_hi:[1,0,1]
	v_pk_fma_f32 v[204:205], v[134:135], v[162:163], v[174:175] op_sel_hi:[1,0,1]
	v_pk_fma_f32 v[206:207], v[136:137], v[162:163], v[176:177] op_sel_hi:[1,0,1]
	v_add_f32_e32 v180, v178, v179
	ds_write_b32 v79, v180 offset:18432
	ds_read_b128 v[130:133], v76 offset:7680
	ds_read_b128 v[134:137], v76 offset:7936
	ds_read_b32 v162, v77 offset:33728
	ds_read_b32 v164, v17 offset:34876
	ds_read_b128 v[154:157], v76 offset:24576
	ds_read_b128 v[158:161], v76 offset:24832
	s_waitcnt lgkmcnt(7)
	v_pk_mul_f32 v[170:171], v[200:201], v[168:169] op_sel_hi:[1,0]
	v_pk_mul_f32 v[178:179], v[200:201], v[146:147]
	v_pk_mul_f32 v[172:173], v[202:203], v[168:169] op_sel_hi:[1,0]
	v_pk_fma_f32 v[178:179], v[202:203], v[148:149], v[178:179]
	v_pk_mul_f32 v[174:175], v[204:205], v[168:169] op_sel_hi:[1,0]
	v_pk_fma_f32 v[178:179], v[204:205], v[150:151], v[178:179]
	v_pk_mul_f32 v[176:177], v[206:207], v[168:169] op_sel_hi:[1,0]
	v_pk_fma_f32 v[178:179], v[206:207], v[152:153], v[178:179]
	v_pk_fma_f32 v[200:201], v[138:139], v[166:167], v[170:171] op_sel_hi:[1,0,1]
	v_pk_fma_f32 v[202:203], v[140:141], v[166:167], v[172:173] op_sel_hi:[1,0,1]
	v_pk_fma_f32 v[204:205], v[142:143], v[166:167], v[174:175] op_sel_hi:[1,0,1]
	v_pk_fma_f32 v[206:207], v[144:145], v[166:167], v[176:177] op_sel_hi:[1,0,1]
	v_add_f32_e32 v180, v178, v179
	ds_write_b32 v79, v180 offset:17408
	ds_read_b128 v[138:141], v76 offset:7168
	ds_read_b128 v[142:145], v76 offset:7424
	ds_read_b32 v166, v77 offset:33664
	ds_read_b32 v168, v17 offset:34872
	ds_read_b128 v[146:149], v76 offset:24064
	ds_read_b128 v[150:153], v76 offset:24320
	s_waitcnt lgkmcnt(7)
	v_pk_mul_f32 v[170:171], v[200:201], v[164:165] op_sel_hi:[1,0]
	v_pk_mul_f32 v[178:179], v[200:201], v[154:155]
	v_pk_mul_f32 v[172:173], v[202:203], v[164:165] op_sel_hi:[1,0]
	v_pk_fma_f32 v[178:179], v[202:203], v[156:157], v[178:179]
	v_pk_mul_f32 v[174:175], v[204:205], v[164:165] op_sel_hi:[1,0]
	v_pk_fma_f32 v[178:179], v[204:205], v[158:159], v[178:179]
	v_pk_mul_f32 v[176:177], v[206:207], v[164:165] op_sel_hi:[1,0]
	v_pk_fma_f32 v[178:179], v[206:207], v[160:161], v[178:179]
	v_pk_fma_f32 v[200:201], v[130:131], v[162:163], v[170:171] op_sel_hi:[1,0,1]
	v_pk_fma_f32 v[202:203], v[132:133], v[162:163], v[172:173] op_sel_hi:[1,0,1]
	v_pk_fma_f32 v[204:205], v[134:135], v[162:163], v[174:175] op_sel_hi:[1,0,1]
	v_pk_fma_f32 v[206:207], v[136:137], v[162:163], v[176:177] op_sel_hi:[1,0,1]
	v_add_f32_e32 v180, v178, v179
	ds_write_b32 v79, v180 offset:16384
	ds_read_b128 v[130:133], v76 offset:6656
	ds_read_b128 v[134:137], v76 offset:6912
	ds_read_b32 v162, v77 offset:33600
	ds_read_b32 v164, v17 offset:34868
	ds_read_b128 v[154:157], v76 offset:23552
	ds_read_b128 v[158:161], v76 offset:23808
	s_waitcnt lgkmcnt(7)
	v_pk_mul_f32 v[170:171], v[200:201], v[168:169] op_sel_hi:[1,0]
	v_pk_mul_f32 v[178:179], v[200:201], v[146:147]
	v_pk_mul_f32 v[172:173], v[202:203], v[168:169] op_sel_hi:[1,0]
	v_pk_fma_f32 v[178:179], v[202:203], v[148:149], v[178:179]
	v_pk_mul_f32 v[174:175], v[204:205], v[168:169] op_sel_hi:[1,0]
	v_pk_fma_f32 v[178:179], v[204:205], v[150:151], v[178:179]
	v_pk_mul_f32 v[176:177], v[206:207], v[168:169] op_sel_hi:[1,0]
	v_pk_fma_f32 v[178:179], v[206:207], v[152:153], v[178:179]
	v_pk_fma_f32 v[200:201], v[138:139], v[166:167], v[170:171] op_sel_hi:[1,0,1]
	v_pk_fma_f32 v[202:203], v[140:141], v[166:167], v[172:173] op_sel_hi:[1,0,1]
	v_pk_fma_f32 v[204:205], v[142:143], v[166:167], v[174:175] op_sel_hi:[1,0,1]
	v_pk_fma_f32 v[206:207], v[144:145], v[166:167], v[176:177] op_sel_hi:[1,0,1]
	v_add_f32_e32 v180, v178, v179
	ds_write_b32 v79, v180 offset:15360
	ds_read_b128 v[138:141], v76 offset:6144
	ds_read_b128 v[142:145], v76 offset:6400
	ds_read_b32 v166, v77 offset:33536
	ds_read_b32 v168, v17 offset:34864
	ds_read_b128 v[146:149], v76 offset:23040
	ds_read_b128 v[150:153], v76 offset:23296
	s_waitcnt lgkmcnt(7)
	v_pk_mul_f32 v[170:171], v[200:201], v[164:165] op_sel_hi:[1,0]
	v_pk_mul_f32 v[178:179], v[200:201], v[154:155]
	v_pk_mul_f32 v[172:173], v[202:203], v[164:165] op_sel_hi:[1,0]
	v_pk_fma_f32 v[178:179], v[202:203], v[156:157], v[178:179]
	v_pk_mul_f32 v[174:175], v[204:205], v[164:165] op_sel_hi:[1,0]
	v_pk_fma_f32 v[178:179], v[204:205], v[158:159], v[178:179]
	v_pk_mul_f32 v[176:177], v[206:207], v[164:165] op_sel_hi:[1,0]
	v_pk_fma_f32 v[178:179], v[206:207], v[160:161], v[178:179]
	v_pk_fma_f32 v[200:201], v[130:131], v[162:163], v[170:171] op_sel_hi:[1,0,1]
	v_pk_fma_f32 v[202:203], v[132:133], v[162:163], v[172:173] op_sel_hi:[1,0,1]
	v_pk_fma_f32 v[204:205], v[134:135], v[162:163], v[174:175] op_sel_hi:[1,0,1]
	v_pk_fma_f32 v[206:207], v[136:137], v[162:163], v[176:177] op_sel_hi:[1,0,1]
	v_add_f32_e32 v180, v178, v179
	ds_write_b32 v79, v180 offset:14336
	ds_read_b128 v[130:133], v76 offset:5632
	ds_read_b128 v[134:137], v76 offset:5888
	ds_read_b32 v162, v77 offset:33472
	ds_read_b32 v164, v17 offset:34860
	ds_read_b128 v[154:157], v76 offset:22528
	ds_read_b128 v[158:161], v76 offset:22784
	s_waitcnt lgkmcnt(7)
	v_pk_mul_f32 v[170:171], v[200:201], v[168:169] op_sel_hi:[1,0]
	v_pk_mul_f32 v[178:179], v[200:201], v[146:147]
	v_pk_mul_f32 v[172:173], v[202:203], v[168:169] op_sel_hi:[1,0]
	v_pk_fma_f32 v[178:179], v[202:203], v[148:149], v[178:179]
	v_pk_mul_f32 v[174:175], v[204:205], v[168:169] op_sel_hi:[1,0]
	v_pk_fma_f32 v[178:179], v[204:205], v[150:151], v[178:179]
	v_pk_mul_f32 v[176:177], v[206:207], v[168:169] op_sel_hi:[1,0]
	v_pk_fma_f32 v[178:179], v[206:207], v[152:153], v[178:179]
	v_pk_fma_f32 v[200:201], v[138:139], v[166:167], v[170:171] op_sel_hi:[1,0,1]
	v_pk_fma_f32 v[202:203], v[140:141], v[166:167], v[172:173] op_sel_hi:[1,0,1]
	v_pk_fma_f32 v[204:205], v[142:143], v[166:167], v[174:175] op_sel_hi:[1,0,1]
	v_pk_fma_f32 v[206:207], v[144:145], v[166:167], v[176:177] op_sel_hi:[1,0,1]
	v_add_f32_e32 v180, v178, v179
	ds_write_b32 v79, v180 offset:13312
	ds_read_b128 v[138:141], v76 offset:5120
	ds_read_b128 v[142:145], v76 offset:5376
	ds_read_b32 v166, v77 offset:33408
	ds_read_b32 v168, v17 offset:34856
	ds_read_b128 v[146:149], v76 offset:22016
	ds_read_b128 v[150:153], v76 offset:22272
	s_waitcnt lgkmcnt(7)
	v_pk_mul_f32 v[170:171], v[200:201], v[164:165] op_sel_hi:[1,0]
	v_pk_mul_f32 v[178:179], v[200:201], v[154:155]
	v_pk_mul_f32 v[172:173], v[202:203], v[164:165] op_sel_hi:[1,0]
	v_pk_fma_f32 v[178:179], v[202:203], v[156:157], v[178:179]
	v_pk_mul_f32 v[174:175], v[204:205], v[164:165] op_sel_hi:[1,0]
	v_pk_fma_f32 v[178:179], v[204:205], v[158:159], v[178:179]
	v_pk_mul_f32 v[176:177], v[206:207], v[164:165] op_sel_hi:[1,0]
	v_pk_fma_f32 v[178:179], v[206:207], v[160:161], v[178:179]
	v_pk_fma_f32 v[200:201], v[130:131], v[162:163], v[170:171] op_sel_hi:[1,0,1]
	v_pk_fma_f32 v[202:203], v[132:133], v[162:163], v[172:173] op_sel_hi:[1,0,1]
	v_pk_fma_f32 v[204:205], v[134:135], v[162:163], v[174:175] op_sel_hi:[1,0,1]
	v_pk_fma_f32 v[206:207], v[136:137], v[162:163], v[176:177] op_sel_hi:[1,0,1]
	v_add_f32_e32 v180, v178, v179
	ds_write_b32 v79, v180 offset:12288
	ds_read_b128 v[130:133], v76 offset:4608
	ds_read_b128 v[134:137], v76 offset:4864
	ds_read_b32 v162, v77 offset:33344
	ds_read_b32 v164, v17 offset:34852
	ds_read_b128 v[154:157], v76 offset:21504
	ds_read_b128 v[158:161], v76 offset:21760
	s_waitcnt lgkmcnt(7)
	v_pk_mul_f32 v[170:171], v[200:201], v[168:169] op_sel_hi:[1,0]
	v_pk_mul_f32 v[178:179], v[200:201], v[146:147]
	v_pk_mul_f32 v[172:173], v[202:203], v[168:169] op_sel_hi:[1,0]
	v_pk_fma_f32 v[178:179], v[202:203], v[148:149], v[178:179]
	v_pk_mul_f32 v[174:175], v[204:205], v[168:169] op_sel_hi:[1,0]
	v_pk_fma_f32 v[178:179], v[204:205], v[150:151], v[178:179]
	v_pk_mul_f32 v[176:177], v[206:207], v[168:169] op_sel_hi:[1,0]
	v_pk_fma_f32 v[178:179], v[206:207], v[152:153], v[178:179]
	v_pk_fma_f32 v[200:201], v[138:139], v[166:167], v[170:171] op_sel_hi:[1,0,1]
	v_pk_fma_f32 v[202:203], v[140:141], v[166:167], v[172:173] op_sel_hi:[1,0,1]
	v_pk_fma_f32 v[204:205], v[142:143], v[166:167], v[174:175] op_sel_hi:[1,0,1]
	v_pk_fma_f32 v[206:207], v[144:145], v[166:167], v[176:177] op_sel_hi:[1,0,1]
	v_add_f32_e32 v180, v178, v179
	ds_write_b32 v79, v180 offset:11264
	ds_read_b128 v[138:141], v76 offset:4096
	ds_read_b128 v[142:145], v76 offset:4352
	ds_read_b32 v166, v77 offset:33280
	ds_read_b32 v168, v17 offset:34848
	ds_read_b128 v[146:149], v76 offset:20992
	ds_read_b128 v[150:153], v76 offset:21248
	s_waitcnt lgkmcnt(7)
	v_pk_mul_f32 v[170:171], v[200:201], v[164:165] op_sel_hi:[1,0]
	v_pk_mul_f32 v[178:179], v[200:201], v[154:155]
	v_pk_mul_f32 v[172:173], v[202:203], v[164:165] op_sel_hi:[1,0]
	v_pk_fma_f32 v[178:179], v[202:203], v[156:157], v[178:179]
	v_pk_mul_f32 v[174:175], v[204:205], v[164:165] op_sel_hi:[1,0]
	v_pk_fma_f32 v[178:179], v[204:205], v[158:159], v[178:179]
	v_pk_mul_f32 v[176:177], v[206:207], v[164:165] op_sel_hi:[1,0]
	v_pk_fma_f32 v[178:179], v[206:207], v[160:161], v[178:179]
	v_pk_fma_f32 v[200:201], v[130:131], v[162:163], v[170:171] op_sel_hi:[1,0,1]
	v_pk_fma_f32 v[202:203], v[132:133], v[162:163], v[172:173] op_sel_hi:[1,0,1]
	v_pk_fma_f32 v[204:205], v[134:135], v[162:163], v[174:175] op_sel_hi:[1,0,1]
	v_pk_fma_f32 v[206:207], v[136:137], v[162:163], v[176:177] op_sel_hi:[1,0,1]
	v_add_f32_e32 v180, v178, v179
	ds_write_b32 v79, v180 offset:10240
	ds_read_b128 v[130:133], v76 offset:3584
	ds_read_b128 v[134:137], v76 offset:3840
	ds_read_b32 v162, v77 offset:33216
	ds_read_b32 v164, v17 offset:34844
	ds_read_b128 v[154:157], v76 offset:20480
	ds_read_b128 v[158:161], v76 offset:20736
	s_waitcnt lgkmcnt(7)
	v_pk_mul_f32 v[170:171], v[200:201], v[168:169] op_sel_hi:[1,0]
	v_pk_mul_f32 v[178:179], v[200:201], v[146:147]
	v_pk_mul_f32 v[172:173], v[202:203], v[168:169] op_sel_hi:[1,0]
	v_pk_fma_f32 v[178:179], v[202:203], v[148:149], v[178:179]
	v_pk_mul_f32 v[174:175], v[204:205], v[168:169] op_sel_hi:[1,0]
	v_pk_fma_f32 v[178:179], v[204:205], v[150:151], v[178:179]
	v_pk_mul_f32 v[176:177], v[206:207], v[168:169] op_sel_hi:[1,0]
	v_pk_fma_f32 v[178:179], v[206:207], v[152:153], v[178:179]
	v_pk_fma_f32 v[200:201], v[138:139], v[166:167], v[170:171] op_sel_hi:[1,0,1]
	v_pk_fma_f32 v[202:203], v[140:141], v[166:167], v[172:173] op_sel_hi:[1,0,1]
	v_pk_fma_f32 v[204:205], v[142:143], v[166:167], v[174:175] op_sel_hi:[1,0,1]
	v_pk_fma_f32 v[206:207], v[144:145], v[166:167], v[176:177] op_sel_hi:[1,0,1]
	v_add_f32_e32 v180, v178, v179
	ds_write_b32 v79, v180 offset:9216
	ds_read_b128 v[138:141], v76 offset:3072
	ds_read_b128 v[142:145], v76 offset:3328
	ds_read_b32 v166, v77 offset:33152
	ds_read_b32 v168, v17 offset:34840
	ds_read_b128 v[146:149], v76 offset:19968
	ds_read_b128 v[150:153], v76 offset:20224
	s_waitcnt lgkmcnt(7)
	v_pk_mul_f32 v[170:171], v[200:201], v[164:165] op_sel_hi:[1,0]
	v_pk_mul_f32 v[178:179], v[200:201], v[154:155]
	v_pk_mul_f32 v[172:173], v[202:203], v[164:165] op_sel_hi:[1,0]
	v_pk_fma_f32 v[178:179], v[202:203], v[156:157], v[178:179]
	v_pk_mul_f32 v[174:175], v[204:205], v[164:165] op_sel_hi:[1,0]
	v_pk_fma_f32 v[178:179], v[204:205], v[158:159], v[178:179]
	v_pk_mul_f32 v[176:177], v[206:207], v[164:165] op_sel_hi:[1,0]
	v_pk_fma_f32 v[178:179], v[206:207], v[160:161], v[178:179]
	v_pk_fma_f32 v[200:201], v[130:131], v[162:163], v[170:171] op_sel_hi:[1,0,1]
	v_pk_fma_f32 v[202:203], v[132:133], v[162:163], v[172:173] op_sel_hi:[1,0,1]
	v_pk_fma_f32 v[204:205], v[134:135], v[162:163], v[174:175] op_sel_hi:[1,0,1]
	v_pk_fma_f32 v[206:207], v[136:137], v[162:163], v[176:177] op_sel_hi:[1,0,1]
	v_add_f32_e32 v180, v178, v179
	ds_write_b32 v79, v180 offset:8192
	ds_read_b128 v[130:133], v76 offset:2560
	ds_read_b128 v[134:137], v76 offset:2816
	ds_read_b32 v162, v77 offset:33088
	ds_read_b32 v164, v17 offset:34836
	ds_read_b128 v[154:157], v76 offset:19456
	ds_read_b128 v[158:161], v76 offset:19712
	s_waitcnt lgkmcnt(7)
	v_pk_mul_f32 v[170:171], v[200:201], v[168:169] op_sel_hi:[1,0]
	v_pk_mul_f32 v[178:179], v[200:201], v[146:147]
	v_pk_mul_f32 v[172:173], v[202:203], v[168:169] op_sel_hi:[1,0]
	v_pk_fma_f32 v[178:179], v[202:203], v[148:149], v[178:179]
	v_pk_mul_f32 v[174:175], v[204:205], v[168:169] op_sel_hi:[1,0]
	v_pk_fma_f32 v[178:179], v[204:205], v[150:151], v[178:179]
	v_pk_mul_f32 v[176:177], v[206:207], v[168:169] op_sel_hi:[1,0]
	v_pk_fma_f32 v[178:179], v[206:207], v[152:153], v[178:179]
	v_pk_fma_f32 v[200:201], v[138:139], v[166:167], v[170:171] op_sel_hi:[1,0,1]
	v_pk_fma_f32 v[202:203], v[140:141], v[166:167], v[172:173] op_sel_hi:[1,0,1]
	v_pk_fma_f32 v[204:205], v[142:143], v[166:167], v[174:175] op_sel_hi:[1,0,1]
	v_pk_fma_f32 v[206:207], v[144:145], v[166:167], v[176:177] op_sel_hi:[1,0,1]
	v_add_f32_e32 v180, v178, v179
	ds_write_b32 v79, v180 offset:7168
	ds_read_b128 v[138:141], v76 offset:2048
	ds_read_b128 v[142:145], v76 offset:2304
	ds_read_b32 v166, v77 offset:33024
	ds_read_b32 v168, v17 offset:34832
	ds_read_b128 v[146:149], v76 offset:18944
	ds_read_b128 v[150:153], v76 offset:19200
	s_waitcnt lgkmcnt(7)
	v_pk_mul_f32 v[170:171], v[200:201], v[164:165] op_sel_hi:[1,0]
	v_pk_mul_f32 v[178:179], v[200:201], v[154:155]
	v_pk_mul_f32 v[172:173], v[202:203], v[164:165] op_sel_hi:[1,0]
	v_pk_fma_f32 v[178:179], v[202:203], v[156:157], v[178:179]
	v_pk_mul_f32 v[174:175], v[204:205], v[164:165] op_sel_hi:[1,0]
	v_pk_fma_f32 v[178:179], v[204:205], v[158:159], v[178:179]
	v_pk_mul_f32 v[176:177], v[206:207], v[164:165] op_sel_hi:[1,0]
	v_pk_fma_f32 v[178:179], v[206:207], v[160:161], v[178:179]
	v_pk_fma_f32 v[200:201], v[130:131], v[162:163], v[170:171] op_sel_hi:[1,0,1]
	v_pk_fma_f32 v[202:203], v[132:133], v[162:163], v[172:173] op_sel_hi:[1,0,1]
	v_pk_fma_f32 v[204:205], v[134:135], v[162:163], v[174:175] op_sel_hi:[1,0,1]
	v_pk_fma_f32 v[206:207], v[136:137], v[162:163], v[176:177] op_sel_hi:[1,0,1]
	v_add_f32_e32 v180, v178, v179
	ds_write_b32 v79, v180 offset:6144
	ds_read_b128 v[130:133], v76 offset:1536
	ds_read_b128 v[134:137], v76 offset:1792
	ds_read_b32 v162, v77 offset:32960
	ds_read_b32 v164, v17 offset:34828
	ds_read_b128 v[154:157], v76 offset:18432
	ds_read_b128 v[158:161], v76 offset:18688
	s_waitcnt lgkmcnt(7)
	v_pk_mul_f32 v[170:171], v[200:201], v[168:169] op_sel_hi:[1,0]
	v_pk_mul_f32 v[178:179], v[200:201], v[146:147]
	v_pk_mul_f32 v[172:173], v[202:203], v[168:169] op_sel_hi:[1,0]
	v_pk_fma_f32 v[178:179], v[202:203], v[148:149], v[178:179]
	v_pk_mul_f32 v[174:175], v[204:205], v[168:169] op_sel_hi:[1,0]
	v_pk_fma_f32 v[178:179], v[204:205], v[150:151], v[178:179]
	v_pk_mul_f32 v[176:177], v[206:207], v[168:169] op_sel_hi:[1,0]
	v_pk_fma_f32 v[178:179], v[206:207], v[152:153], v[178:179]
	v_pk_fma_f32 v[200:201], v[138:139], v[166:167], v[170:171] op_sel_hi:[1,0,1]
	v_pk_fma_f32 v[202:203], v[140:141], v[166:167], v[172:173] op_sel_hi:[1,0,1]
	v_pk_fma_f32 v[204:205], v[142:143], v[166:167], v[174:175] op_sel_hi:[1,0,1]
	v_pk_fma_f32 v[206:207], v[144:145], v[166:167], v[176:177] op_sel_hi:[1,0,1]
	v_add_f32_e32 v180, v178, v179
	ds_write_b32 v79, v180 offset:5120
	ds_read_b128 v[138:141], v76 offset:1024
	ds_read_b128 v[142:145], v76 offset:1280
	ds_read_b32 v166, v77 offset:32896
	ds_read_b32 v168, v17 offset:34824
	ds_read_b128 v[146:149], v76 offset:17920
	ds_read_b128 v[150:153], v76 offset:18176
	s_waitcnt lgkmcnt(7)
	v_pk_mul_f32 v[170:171], v[200:201], v[164:165] op_sel_hi:[1,0]
	v_pk_mul_f32 v[178:179], v[200:201], v[154:155]
	v_pk_mul_f32 v[172:173], v[202:203], v[164:165] op_sel_hi:[1,0]
	v_pk_fma_f32 v[178:179], v[202:203], v[156:157], v[178:179]
	v_pk_mul_f32 v[174:175], v[204:205], v[164:165] op_sel_hi:[1,0]
	v_pk_fma_f32 v[178:179], v[204:205], v[158:159], v[178:179]
	v_pk_mul_f32 v[176:177], v[206:207], v[164:165] op_sel_hi:[1,0]
	v_pk_fma_f32 v[178:179], v[206:207], v[160:161], v[178:179]
	v_pk_fma_f32 v[200:201], v[130:131], v[162:163], v[170:171] op_sel_hi:[1,0,1]
	v_pk_fma_f32 v[202:203], v[132:133], v[162:163], v[172:173] op_sel_hi:[1,0,1]
	v_pk_fma_f32 v[204:205], v[134:135], v[162:163], v[174:175] op_sel_hi:[1,0,1]
	v_pk_fma_f32 v[206:207], v[136:137], v[162:163], v[176:177] op_sel_hi:[1,0,1]
	v_add_f32_e32 v180, v178, v179
	ds_write_b32 v79, v180 offset:4096
	ds_read_b128 v[130:133], v76 offset:512
	ds_read_b128 v[134:137], v76 offset:768
	ds_read_b32 v162, v77 offset:32832
	ds_read_b32 v164, v17 offset:34820
	ds_read_b128 v[154:157], v76 offset:17408
	ds_read_b128 v[158:161], v76 offset:17664
	s_waitcnt lgkmcnt(7)
	v_pk_mul_f32 v[170:171], v[200:201], v[168:169] op_sel_hi:[1,0]
	v_pk_mul_f32 v[178:179], v[200:201], v[146:147]
	v_pk_mul_f32 v[172:173], v[202:203], v[168:169] op_sel_hi:[1,0]
	v_pk_fma_f32 v[178:179], v[202:203], v[148:149], v[178:179]
	v_pk_mul_f32 v[174:175], v[204:205], v[168:169] op_sel_hi:[1,0]
	v_pk_fma_f32 v[178:179], v[204:205], v[150:151], v[178:179]
	v_pk_mul_f32 v[176:177], v[206:207], v[168:169] op_sel_hi:[1,0]
	v_pk_fma_f32 v[178:179], v[206:207], v[152:153], v[178:179]
	v_pk_fma_f32 v[200:201], v[138:139], v[166:167], v[170:171] op_sel_hi:[1,0,1]
	v_pk_fma_f32 v[202:203], v[140:141], v[166:167], v[172:173] op_sel_hi:[1,0,1]
	v_pk_fma_f32 v[204:205], v[142:143], v[166:167], v[174:175] op_sel_hi:[1,0,1]
	v_pk_fma_f32 v[206:207], v[144:145], v[166:167], v[176:177] op_sel_hi:[1,0,1]
	v_add_f32_e32 v180, v178, v179
	ds_write_b32 v79, v180 offset:3072
	ds_read_b128 v[138:141], v76
	ds_read_b128 v[142:145], v76 offset:256
	ds_read_b32 v166, v77 offset:32768
	ds_read_b32 v168, v17 offset:34816
	ds_read_b128 v[146:149], v76 offset:16896
	ds_read_b128 v[150:153], v76 offset:17152
	s_waitcnt lgkmcnt(7)
	v_pk_mul_f32 v[170:171], v[200:201], v[164:165] op_sel_hi:[1,0]
	v_pk_mul_f32 v[178:179], v[200:201], v[154:155]
	v_pk_mul_f32 v[172:173], v[202:203], v[164:165] op_sel_hi:[1,0]
	v_pk_fma_f32 v[178:179], v[202:203], v[156:157], v[178:179]
	v_pk_mul_f32 v[174:175], v[204:205], v[164:165] op_sel_hi:[1,0]
	v_pk_fma_f32 v[178:179], v[204:205], v[158:159], v[178:179]
	v_pk_mul_f32 v[176:177], v[206:207], v[164:165] op_sel_hi:[1,0]
	v_pk_fma_f32 v[178:179], v[206:207], v[160:161], v[178:179]
	v_pk_fma_f32 v[200:201], v[130:131], v[162:163], v[170:171] op_sel_hi:[1,0,1]
	v_pk_fma_f32 v[202:203], v[132:133], v[162:163], v[172:173] op_sel_hi:[1,0,1]
	v_pk_fma_f32 v[204:205], v[134:135], v[162:163], v[174:175] op_sel_hi:[1,0,1]
	v_pk_fma_f32 v[206:207], v[136:137], v[162:163], v[176:177] op_sel_hi:[1,0,1]
	v_add_f32_e32 v180, v178, v179
	ds_write_b32 v79, v180 offset:2048
	ds_read_b128 v[154:157], v76 offset:16384
	ds_read_b128 v[158:161], v76 offset:16640
	s_waitcnt lgkmcnt(3)
	v_pk_mul_f32 v[170:171], v[200:201], v[168:169] op_sel_hi:[1,0]
	v_pk_mul_f32 v[178:179], v[200:201], v[146:147]
	v_pk_mul_f32 v[172:173], v[202:203], v[168:169] op_sel_hi:[1,0]
	v_pk_fma_f32 v[178:179], v[202:203], v[148:149], v[178:179]
	v_pk_mul_f32 v[174:175], v[204:205], v[168:169] op_sel_hi:[1,0]
	v_pk_fma_f32 v[178:179], v[204:205], v[150:151], v[178:179]
	v_pk_mul_f32 v[176:177], v[206:207], v[168:169] op_sel_hi:[1,0]
	v_pk_fma_f32 v[178:179], v[206:207], v[152:153], v[178:179]
	v_pk_fma_f32 v[200:201], v[138:139], v[166:167], v[170:171] op_sel_hi:[1,0,1]
	v_pk_fma_f32 v[202:203], v[140:141], v[166:167], v[172:173] op_sel_hi:[1,0,1]
	v_pk_fma_f32 v[204:205], v[142:143], v[166:167], v[174:175] op_sel_hi:[1,0,1]
	v_pk_fma_f32 v[206:207], v[144:145], v[166:167], v[176:177] op_sel_hi:[1,0,1]
	v_add_f32_e32 v180, v178, v179
	ds_write_b32 v79, v180 offset:1024
	s_waitcnt lgkmcnt(1)
	v_pk_mul_f32 v[178:179], v[200:201], v[154:155]
	v_pk_fma_f32 v[178:179], v[202:203], v[156:157], v[178:179]
	v_pk_fma_f32 v[178:179], v[204:205], v[158:159], v[178:179]
	v_pk_fma_f32 v[178:179], v[206:207], v[160:161], v[178:179]
	v_add_f32_e32 v180, v178, v179
	ds_write_b32 v79, v180
	s_branch .LBB0_671
.Lmb_fwd:
	ds_read_b128 v[130:133], v76
	ds_read_b128 v[134:137], v76 offset:256
	ds_read_b32 v162, v77 offset:32768
	ds_read_b32 v164, v17 offset:34816
	ds_read_b128 v[138:141], v76 offset:512
	ds_read_b128 v[142:145], v76 offset:768
	ds_read_b32 v166, v77 offset:32832
	ds_read_b32 v168, v17 offset:34820
	ds_read_b128 v[146:149], v76 offset:16384
	ds_read_b128 v[150:153], v76 offset:16640
	s_waitcnt lgkmcnt(6)
	v_pk_mul_f32 v[170:171], v[200:201], v[164:165] op_sel_hi:[1,0]
	v_pk_mul_f32 v[172:173], v[202:203], v[164:165] op_sel_hi:[1,0]
	v_pk_mul_f32 v[174:175], v[204:205], v[164:165] op_sel_hi:[1,0]
	v_pk_mul_f32 v[176:177], v[206:207], v[164:165] op_sel_hi:[1,0]
	v_pk_fma_f32 v[200:201], v[130:131], v[162:163], v[170:171] op_sel_hi:[1,0,1]
	v_pk_fma_f32 v[202:203], v[132:133], v[162:163], v[172:173] op_sel_hi:[1,0,1]
	v_pk_fma_f32 v[204:205], v[134:135], v[162:163], v[174:175] op_sel_hi:[1,0,1]
	v_pk_fma_f32 v[206:207], v[136:137], v[162:163], v[176:177] op_sel_hi:[1,0,1]
	ds_read_b128 v[130:133], v76 offset:1024
	ds_read_b128 v[134:137], v76 offset:1280
	ds_read_b32 v162, v77 offset:32896
	ds_read_b32 v164, v17 offset:34824
	ds_read_b128 v[154:157], v76 offset:16896
	ds_read_b128 v[158:161], v76 offset:17152
	s_waitcnt lgkmcnt(6)
	v_pk_mul_f32 v[170:171], v[200:201], v[168:169] op_sel_hi:[1,0]
	v_pk_mul_f32 v[178:179], v[200:201], v[146:147]
	v_pk_mul_f32 v[172:173], v[202:203], v[168:169] op_sel_hi:[1,0]
	v_pk_fma_f32 v[178:179], v[202:203], v[148:149], v[178:179]
	v_pk_mul_f32 v[174:175], v[204:205], v[168:169] op_sel_hi:[1,0]
	v_pk_fma_f32 v[178:179], v[204:205], v[150:151], v[178:179]
	v_pk_mul_f32 v[176:177], v[206:207], v[168:169] op_sel_hi:[1,0]
	v_pk_fma_f32 v[178:179], v[206:207], v[152:153], v[178:179]
	v_pk_fma_f32 v[200:201], v[138:139], v[166:167], v[170:171] op_sel_hi:[1,0,1]
	v_pk_fma_f32 v[202:203], v[140:141], v[166:167], v[172:173] op_sel_hi:[1,0,1]
	v_pk_fma_f32 v[204:205], v[142:143], v[166:167], v[174:175] op_sel_hi:[1,0,1]
	v_pk_fma_f32 v[206:207], v[144:145], v[166:167], v[176:177] op_sel_hi:[1,0,1]
	v_add_f32_e32 v180, v178, v179
	ds_write_b32 v79, v180
	ds_read_b128 v[138:141], v76 offset:1536
	ds_read_b128 v[142:145], v76 offset:1792
	ds_read_b32 v166, v77 offset:32960
	ds_read_b32 v168, v17 offset:34828
	ds_read_b128 v[146:149], v76 offset:17408
	ds_read_b128 v[150:153], v76 offset:17664
	s_waitcnt lgkmcnt(7)
	v_pk_mul_f32 v[170:171], v[200:201], v[164:165] op_sel_hi:[1,0]
	v_pk_mul_f32 v[178:179], v[200:201], v[154:155]
	v_pk_mul_f32 v[172:173], v[202:203], v[164:165] op_sel_hi:[1,0]
	v_pk_fma_f32 v[178:179], v[202:203], v[156:157], v[178:179]
	v_pk_mul_f32 v[174:175], v[204:205], v[164:165] op_sel_hi:[1,0]
	v_pk_fma_f32 v[178:179], v[204:205], v[158:159], v[178:179]
	v_pk_mul_f32 v[176:177], v[206:207], v[164:165] op_sel_hi:[1,0]
	v_pk_fma_f32 v[178:179], v[206:207], v[160:161], v[178:179]
	v_pk_fma_f32 v[200:201], v[130:131], v[162:163], v[170:171] op_sel_hi:[1,0,1]
	v_pk_fma_f32 v[202:203], v[132:133], v[162:163], v[172:173] op_sel_hi:[1,0,1]
	v_pk_fma_f32 v[204:205], v[134:135], v[162:163], v[174:175] op_sel_hi:[1,0,1]
	v_pk_fma_f32 v[206:207], v[136:137], v[162:163], v[176:177] op_sel_hi:[1,0,1]
	v_add_f32_e32 v180, v178, v179
	ds_write_b32 v79, v180 offset:1024
	ds_read_b128 v[130:133], v76 offset:2048
	ds_read_b128 v[134:137], v76 offset:2304
	ds_read_b32 v162, v77 offset:33024
	ds_read_b32 v164, v17 offset:34832
	ds_read_b128 v[154:157], v76 offset:17920
	ds_read_b128 v[158:161], v76 offset:18176
	s_waitcnt lgkmcnt(7)
	v_pk_mul_f32 v[170:171], v[200:201], v[168:169] op_sel_hi:[1,0]
	v_pk_mul_f32 v[178:179], v[200:201], v[146:147]
	v_pk_mul_f32 v[172:173], v[202:203], v[168:169] op_sel_hi:[1,0]
	v_pk_fma_f32 v[178:179], v[202:203], v[148:149], v[178:179]
	v_pk_mul_f32 v[174:175], v[204:205], v[168:169] op_sel_hi:[1,0]
	v_pk_fma_f32 v[178:179], v[204:205], v[150:151], v[178:179]
	v_pk_mul_f32 v[176:177], v[206:207], v[168:169] op_sel_hi:[1,0]
	v_pk_fma_f32 v[178:179], v[206:207], v[152:153], v[178:179]
	v_pk_fma_f32 v[200:201], v[138:139], v[166:167], v[170:171] op_sel_hi:[1,0,1]
	v_pk_fma_f32 v[202:203], v[140:141], v[166:167], v[172:173] op_sel_hi:[1,0,1]
	v_pk_fma_f32 v[204:205], v[142:143], v[166:167], v[174:175] op_sel_hi:[1,0,1]
	v_pk_fma_f32 v[206:207], v[144:145], v[166:167], v[176:177] op_sel_hi:[1,0,1]
	v_add_f32_e32 v180, v178, v179
	ds_write_b32 v79, v180 offset:2048
	ds_read_b128 v[138:141], v76 offset:2560
	ds_read_b128 v[142:145], v76 offset:2816
	ds_read_b32 v166, v77 offset:33088
	ds_read_b32 v168, v17 offset:34836
	ds_read_b128 v[146:149], v76 offset:18432
	ds_read_b128 v[150:153], v76 offset:18688
	s_waitcnt lgkmcnt(7)
	v_pk_mul_f32 v[170:171], v[200:201], v[164:165] op_sel_hi:[1,0]
	v_pk_mul_f32 v[178:179], v[200:201], v[154:155]
	v_pk_mul_f32 v[172:173], v[202:203], v[164:165] op_sel_hi:[1,0]
	v_pk_fma_f32 v[178:179], v[202:203], v[156:157], v[178:179]
	v_pk_mul_f32 v[174:175], v[204:205], v[164:165] op_sel_hi:[1,0]
	v_pk_fma_f32 v[178:179], v[204:205], v[158:159], v[178:179]
	v_pk_mul_f32 v[176:177], v[206:207], v[164:165] op_sel_hi:[1,0]
	v_pk_fma_f32 v[178:179], v[206:207], v[160:161], v[178:179]
	v_pk_fma_f32 v[200:201], v[130:131], v[162:163], v[170:171] op_sel_hi:[1,0,1]
	v_pk_fma_f32 v[202:203], v[132:133], v[162:163], v[172:173] op_sel_hi:[1,0,1]
	v_pk_fma_f32 v[204:205], v[134:135], v[162:163], v[174:175] op_sel_hi:[1,0,1]
	v_pk_fma_f32 v[206:207], v[136:137], v[162:163], v[176:177] op_sel_hi:[1,0,1]
	v_add_f32_e32 v180, v178, v179
	ds_write_b32 v79, v180 offset:3072
	ds_read_b128 v[130:133], v76 offset:3072
	ds_read_b128 v[134:137], v76 offset:3328
	ds_read_b32 v162, v77 offset:33152
	ds_read_b32 v164, v17 offset:34840
	ds_read_b128 v[154:157], v76 offset:18944
	ds_read_b128 v[158:161], v76 offset:19200
	s_waitcnt lgkmcnt(7)
	v_pk_mul_f32 v[170:171], v[200:201], v[168:169] op_sel_hi:[1,0]
	v_pk_mul_f32 v[178:179], v[200:201], v[146:147]
	v_pk_mul_f32 v[172:173], v[202:203], v[168:169] op_sel_hi:[1,0]
	v_pk_fma_f32 v[178:179], v[202:203], v[148:149], v[178:179]
	v_pk_mul_f32 v[174:175], v[204:205], v[168:169] op_sel_hi:[1,0]
	v_pk_fma_f32 v[178:179], v[204:205], v[150:151], v[178:179]
	v_pk_mul_f32 v[176:177], v[206:207], v[168:169] op_sel_hi:[1,0]
	v_pk_fma_f32 v[178:179], v[206:207], v[152:153], v[178:179]
	v_pk_fma_f32 v[200:201], v[138:139], v[166:167], v[170:171] op_sel_hi:[1,0,1]
	v_pk_fma_f32 v[202:203], v[140:141], v[166:167], v[172:173] op_sel_hi:[1,0,1]
	v_pk_fma_f32 v[204:205], v[142:143], v[166:167], v[174:175] op_sel_hi:[1,0,1]
	v_pk_fma_f32 v[206:207], v[144:145], v[166:167], v[176:177] op_sel_hi:[1,0,1]
	v_add_f32_e32 v180, v178, v179
	ds_write_b32 v79, v180 offset:4096
	ds_read_b128 v[138:141], v76 offset:3584
	ds_read_b128 v[142:145], v76 offset:3840
	ds_read_b32 v166, v77 offset:33216
	ds_read_b32 v168, v17 offset:34844
	ds_read_b128 v[146:149], v76 offset:19456
	ds_read_b128 v[150:153], v76 offset:19712
	s_waitcnt lgkmcnt(7)
	v_pk_mul_f32 v[170:171], v[200:201], v[164:165] op_sel_hi:[1,0]
	v_pk_mul_f32 v[178:179], v[200:201], v[154:155]
	v_pk_mul_f32 v[172:173], v[202:203], v[164:165] op_sel_hi:[1,0]
	v_pk_fma_f32 v[178:179], v[202:203], v[156:157], v[178:179]
	v_pk_mul_f32 v[174:175], v[204:205], v[164:165] op_sel_hi:[1,0]
	v_pk_fma_f32 v[178:179], v[204:205], v[158:159], v[178:179]
	v_pk_mul_f32 v[176:177], v[206:207], v[164:165] op_sel_hi:[1,0]
	v_pk_fma_f32 v[178:179], v[206:207], v[160:161], v[178:179]
	v_pk_fma_f32 v[200:201], v[130:131], v[162:163], v[170:171] op_sel_hi:[1,0,1]
	v_pk_fma_f32 v[202:203], v[132:133], v[162:163], v[172:173] op_sel_hi:[1,0,1]
	v_pk_fma_f32 v[204:205], v[134:135], v[162:163], v[174:175] op_sel_hi:[1,0,1]
	v_pk_fma_f32 v[206:207], v[136:137], v[162:163], v[176:177] op_sel_hi:[1,0,1]
	v_add_f32_e32 v180, v178, v179
	ds_write_b32 v79, v180 offset:5120
	ds_read_b128 v[130:133], v76 offset:4096
	ds_read_b128 v[134:137], v76 offset:4352
	ds_read_b32 v162, v77 offset:33280
	ds_read_b32 v164, v17 offset:34848
	ds_read_b128 v[154:157], v76 offset:19968
	ds_read_b128 v[158:161], v76 offset:20224
	s_waitcnt lgkmcnt(7)
	v_pk_mul_f32 v[170:171], v[200:201], v[168:169] op_sel_hi:[1,0]
	v_pk_mul_f32 v[178:179], v[200:201], v[146:147]
	v_pk_mul_f32 v[172:173], v[202:203], v[168:169] op_sel_hi:[1,0]
	v_pk_fma_f32 v[178:179], v[202:203], v[148:149], v[178:179]
	v_pk_mul_f32 v[174:175], v[204:205], v[168:169] op_sel_hi:[1,0]
	v_pk_fma_f32 v[178:179], v[204:205], v[150:151], v[178:179]
	v_pk_mul_f32 v[176:177], v[206:207], v[168:169] op_sel_hi:[1,0]
	v_pk_fma_f32 v[178:179], v[206:207], v[152:153], v[178:179]
	v_pk_fma_f32 v[200:201], v[138:139], v[166:167], v[170:171] op_sel_hi:[1,0,1]
	v_pk_fma_f32 v[202:203], v[140:141], v[166:167], v[172:173] op_sel_hi:[1,0,1]
	v_pk_fma_f32 v[204:205], v[142:143], v[166:167], v[174:175] op_sel_hi:[1,0,1]
	v_pk_fma_f32 v[206:207], v[144:145], v[166:167], v[176:177] op_sel_hi:[1,0,1]
	v_add_f32_e32 v180, v178, v179
	ds_write_b32 v79, v180 offset:6144
	ds_read_b128 v[138:141], v76 offset:4608
	ds_read_b128 v[142:145], v76 offset:4864
	ds_read_b32 v166, v77 offset:33344
	ds_read_b32 v168, v17 offset:34852
	ds_read_b128 v[146:149], v76 offset:20480
	ds_read_b128 v[150:153], v76 offset:20736
	s_waitcnt lgkmcnt(7)
	v_pk_mul_f32 v[170:171], v[200:201], v[164:165] op_sel_hi:[1,0]
	v_pk_mul_f32 v[178:179], v[200:201], v[154:155]
	v_pk_mul_f32 v[172:173], v[202:203], v[164:165] op_sel_hi:[1,0]
	v_pk_fma_f32 v[178:179], v[202:203], v[156:157], v[178:179]
	v_pk_mul_f32 v[174:175], v[204:205], v[164:165] op_sel_hi:[1,0]
	v_pk_fma_f32 v[178:179], v[204:205], v[158:159], v[178:179]
	v_pk_mul_f32 v[176:177], v[206:207], v[164:165] op_sel_hi:[1,0]
	v_pk_fma_f32 v[178:179], v[206:207], v[160:161], v[178:179]
	v_pk_fma_f32 v[200:201], v[130:131], v[162:163], v[170:171] op_sel_hi:[1,0,1]
	v_pk_fma_f32 v[202:203], v[132:133], v[162:163], v[172:173] op_sel_hi:[1,0,1]
	v_pk_fma_f32 v[204:205], v[134:135], v[162:163], v[174:175] op_sel_hi:[1,0,1]
	v_pk_fma_f32 v[206:207], v[136:137], v[162:163], v[176:177] op_sel_hi:[1,0,1]
	v_add_f32_e32 v180, v178, v179
	ds_write_b32 v79, v180 offset:7168
	ds_read_b128 v[130:133], v76 offset:5120
	ds_read_b128 v[134:137], v76 offset:5376
	ds_read_b32 v162, v77 offset:33408
	ds_read_b32 v164, v17 offset:34856
	ds_read_b128 v[154:157], v76 offset:20992
	ds_read_b128 v[158:161], v76 offset:21248
	s_waitcnt lgkmcnt(7)
	v_pk_mul_f32 v[170:171], v[200:201], v[168:169] op_sel_hi:[1,0]
	v_pk_mul_f32 v[178:179], v[200:201], v[146:147]
	v_pk_mul_f32 v[172:173], v[202:203], v[168:169] op_sel_hi:[1,0]
	v_pk_fma_f32 v[178:179], v[202:203], v[148:149], v[178:179]
	v_pk_mul_f32 v[174:175], v[204:205], v[168:169] op_sel_hi:[1,0]
	v_pk_fma_f32 v[178:179], v[204:205], v[150:151], v[178:179]
	v_pk_mul_f32 v[176:177], v[206:207], v[168:169] op_sel_hi:[1,0]
	v_pk_fma_f32 v[178:179], v[206:207], v[152:153], v[178:179]
	v_pk_fma_f32 v[200:201], v[138:139], v[166:167], v[170:171] op_sel_hi:[1,0,1]
	v_pk_fma_f32 v[202:203], v[140:141], v[166:167], v[172:173] op_sel_hi:[1,0,1]
	v_pk_fma_f32 v[204:205], v[142:143], v[166:167], v[174:175] op_sel_hi:[1,0,1]
	v_pk_fma_f32 v[206:207], v[144:145], v[166:167], v[176:177] op_sel_hi:[1,0,1]
	v_add_f32_e32 v180, v178, v179
	ds_write_b32 v79, v180 offset:8192
	ds_read_b128 v[138:141], v76 offset:5632
	ds_read_b128 v[142:145], v76 offset:5888
	ds_read_b32 v166, v77 offset:33472
	ds_read_b32 v168, v17 offset:34860
	ds_read_b128 v[146:149], v76 offset:21504
	ds_read_b128 v[150:153], v76 offset:21760
	s_waitcnt lgkmcnt(7)
	v_pk_mul_f32 v[170:171], v[200:201], v[164:165] op_sel_hi:[1,0]
	v_pk_mul_f32 v[178:179], v[200:201], v[154:155]
	v_pk_mul_f32 v[172:173], v[202:203], v[164:165] op_sel_hi:[1,0]
	v_pk_fma_f32 v[178:179], v[202:203], v[156:157], v[178:179]
	v_pk_mul_f32 v[174:175], v[204:205], v[164:165] op_sel_hi:[1,0]
	v_pk_fma_f32 v[178:179], v[204:205], v[158:159], v[178:179]
	v_pk_mul_f32 v[176:177], v[206:207], v[164:165] op_sel_hi:[1,0]
	v_pk_fma_f32 v[178:179], v[206:207], v[160:161], v[178:179]
	v_pk_fma_f32 v[200:201], v[130:131], v[162:163], v[170:171] op_sel_hi:[1,0,1]
	v_pk_fma_f32 v[202:203], v[132:133], v[162:163], v[172:173] op_sel_hi:[1,0,1]
	v_pk_fma_f32 v[204:205], v[134:135], v[162:163], v[174:175] op_sel_hi:[1,0,1]
	v_pk_fma_f32 v[206:207], v[136:137], v[162:163], v[176:177] op_sel_hi:[1,0,1]
	v_add_f32_e32 v180, v178, v179
	ds_write_b32 v79, v180 offset:9216
	ds_read_b128 v[130:133], v76 offset:6144
	ds_read_b128 v[134:137], v76 offset:6400
	ds_read_b32 v162, v77 offset:33536
	ds_read_b32 v164, v17 offset:34864
	ds_read_b128 v[154:157], v76 offset:22016
	ds_read_b128 v[158:161], v76 offset:22272
	s_waitcnt lgkmcnt(7)
	v_pk_mul_f32 v[170:171], v[200:201], v[168:169] op_sel_hi:[1,0]
	v_pk_mul_f32 v[178:179], v[200:201], v[146:147]
	v_pk_mul_f32 v[172:173], v[202:203], v[168:169] op_sel_hi:[1,0]
	v_pk_fma_f32 v[178:179], v[202:203], v[148:149], v[178:179]
	v_pk_mul_f32 v[174:175], v[204:205], v[168:169] op_sel_hi:[1,0]
	v_pk_fma_f32 v[178:179], v[204:205], v[150:151], v[178:179]
	v_pk_mul_f32 v[176:177], v[206:207], v[168:169] op_sel_hi:[1,0]
	v_pk_fma_f32 v[178:179], v[206:207], v[152:153], v[178:179]
	v_pk_fma_f32 v[200:201], v[138:139], v[166:167], v[170:171] op_sel_hi:[1,0,1]
	v_pk_fma_f32 v[202:203], v[140:141], v[166:167], v[172:173] op_sel_hi:[1,0,1]
	v_pk_fma_f32 v[204:205], v[142:143], v[166:167], v[174:175] op_sel_hi:[1,0,1]
	v_pk_fma_f32 v[206:207], v[144:145], v[166:167], v[176:177] op_sel_hi:[1,0,1]
	v_add_f32_e32 v180, v178, v179
	ds_write_b32 v79, v180 offset:10240
	ds_read_b128 v[138:141], v76 offset:6656
	ds_read_b128 v[142:145], v76 offset:6912
	ds_read_b32 v166, v77 offset:33600
	ds_read_b32 v168, v17 offset:34868
	ds_read_b128 v[146:149], v76 offset:22528
	ds_read_b128 v[150:153], v76 offset:22784
	s_waitcnt lgkmcnt(7)
	v_pk_mul_f32 v[170:171], v[200:201], v[164:165] op_sel_hi:[1,0]
	v_pk_mul_f32 v[178:179], v[200:201], v[154:155]
	v_pk_mul_f32 v[172:173], v[202:203], v[164:165] op_sel_hi:[1,0]
	v_pk_fma_f32 v[178:179], v[202:203], v[156:157], v[178:179]
	v_pk_mul_f32 v[174:175], v[204:205], v[164:165] op_sel_hi:[1,0]
	v_pk_fma_f32 v[178:179], v[204:205], v[158:159], v[178:179]
	v_pk_mul_f32 v[176:177], v[206:207], v[164:165] op_sel_hi:[1,0]
	v_pk_fma_f32 v[178:179], v[206:207], v[160:161], v[178:179]
	v_pk_fma_f32 v[200:201], v[130:131], v[162:163], v[170:171] op_sel_hi:[1,0,1]
	v_pk_fma_f32 v[202:203], v[132:133], v[162:163], v[172:173] op_sel_hi:[1,0,1]
	v_pk_fma_f32 v[204:205], v[134:135], v[162:163], v[174:175] op_sel_hi:[1,0,1]
	v_pk_fma_f32 v[206:207], v[136:137], v[162:163], v[176:177] op_sel_hi:[1,0,1]
	v_add_f32_e32 v180, v178, v179
	ds_write_b32 v79, v180 offset:11264
	ds_read_b128 v[130:133], v76 offset:7168
	ds_read_b128 v[134:137], v76 offset:7424
	ds_read_b32 v162, v77 offset:33664
	ds_read_b32 v164, v17 offset:34872
	ds_read_b128 v[154:157], v76 offset:23040
	ds_read_b128 v[158:161], v76 offset:23296
	s_waitcnt lgkmcnt(7)
	v_pk_mul_f32 v[170:171], v[200:201], v[168:169] op_sel_hi:[1,0]
	v_pk_mul_f32 v[178:179], v[200:201], v[146:147]
	v_pk_mul_f32 v[172:173], v[202:203], v[168:169] op_sel_hi:[1,0]
	v_pk_fma_f32 v[178:179], v[202:203], v[148:149], v[178:179]
	v_pk_mul_f32 v[174:175], v[204:205], v[168:169] op_sel_hi:[1,0]
	v_pk_fma_f32 v[178:179], v[204:205], v[150:151], v[178:179]
	v_pk_mul_f32 v[176:177], v[206:207], v[168:169] op_sel_hi:[1,0]
	v_pk_fma_f32 v[178:179], v[206:207], v[152:153], v[178:179]
	v_pk_fma_f32 v[200:201], v[138:139], v[166:167], v[170:171] op_sel_hi:[1,0,1]
	v_pk_fma_f32 v[202:203], v[140:141], v[166:167], v[172:173] op_sel_hi:[1,0,1]
	v_pk_fma_f32 v[204:205], v[142:143], v[166:167], v[174:175] op_sel_hi:[1,0,1]
	v_pk_fma_f32 v[206:207], v[144:145], v[166:167], v[176:177] op_sel_hi:[1,0,1]
	v_add_f32_e32 v180, v178, v179
	ds_write_b32 v79, v180 offset:12288
	ds_read_b128 v[138:141], v76 offset:7680
	ds_read_b128 v[142:145], v76 offset:7936
	ds_read_b32 v166, v77 offset:33728
	ds_read_b32 v168, v17 offset:34876
	ds_read_b128 v[146:149], v76 offset:23552
	ds_read_b128 v[150:153], v76 offset:23808
	s_waitcnt lgkmcnt(7)
	v_pk_mul_f32 v[170:171], v[200:201], v[164:165] op_sel_hi:[1,0]
	v_pk_mul_f32 v[178:179], v[200:201], v[154:155]
	v_pk_mul_f32 v[172:173], v[202:203], v[164:165] op_sel_hi:[1,0]
	v_pk_fma_f32 v[178:179], v[202:203], v[156:157], v[178:179]
	v_pk_mul_f32 v[174:175], v[204:205], v[164:165] op_sel_hi:[1,0]
	v_pk_fma_f32 v[178:179], v[204:205], v[158:159], v[178:179]
	v_pk_mul_f32 v[176:177], v[206:207], v[164:165] op_sel_hi:[1,0]
	v_pk_fma_f32 v[178:179], v[206:207], v[160:161], v[178:179]
	v_pk_fma_f32 v[200:201], v[130:131], v[162:163], v[170:171] op_sel_hi:[1,0,1]
	v_pk_fma_f32 v[202:203], v[132:133], v[162:163], v[172:173] op_sel_hi:[1,0,1]
	v_pk_fma_f32 v[204:205], v[134:135], v[162:163], v[174:175] op_sel_hi:[1,0,1]
	v_pk_fma_f32 v[206:207], v[136:137], v[162:163], v[176:177] op_sel_hi:[1,0,1]
	v_add_f32_e32 v180, v178, v179
	ds_write_b32 v79, v180 offset:13312
	ds_read_b128 v[130:133], v76 offset:8192
	ds_read_b128 v[134:137], v76 offset:8448
	ds_read_b32 v162, v77 offset:33792
	ds_read_b32 v164, v17 offset:34880
	ds_read_b128 v[154:157], v76 offset:24064
	ds_read_b128 v[158:161], v76 offset:24320
	s_waitcnt lgkmcnt(7)
	v_pk_mul_f32 v[170:171], v[200:201], v[168:169] op_sel_hi:[1,0]
	v_pk_mul_f32 v[178:179], v[200:201], v[146:147]
	v_pk_mul_f32 v[172:173], v[202:203], v[168:169] op_sel_hi:[1,0]
	v_pk_fma_f32 v[178:179], v[202:203], v[148:149], v[178:179]
	v_pk_mul_f32 v[174:175], v[204:205], v[168:169] op_sel_hi:[1,0]
	v_pk_fma_f32 v[178:179], v[204:205], v[150:151], v[178:179]
	v_pk_mul_f32 v[176:177], v[206:207], v[168:169] op_sel_hi:[1,0]
	v_pk_fma_f32 v[178:179], v[206:207], v[152:153], v[178:179]
	v_pk_fma_f32 v[200:201], v[138:139], v[166:167], v[170:171] op_sel_hi:[1,0,1]
	v_pk_fma_f32 v[202:203], v[140:141], v[166:167], v[172:173] op_sel_hi:[1,0,1]
	v_pk_fma_f32 v[204:205], v[142:143], v[166:167], v[174:175] op_sel_hi:[1,0,1]
	v_pk_fma_f32 v[206:207], v[144:145], v[166:167], v[176:177] op_sel_hi:[1,0,1]
	v_add_f32_e32 v180, v178, v179
	ds_write_b32 v79, v180 offset:14336
	ds_read_b128 v[138:141], v76 offset:8704
	ds_read_b128 v[142:145], v76 offset:8960
	ds_read_b32 v166, v77 offset:33856
	ds_read_b32 v168, v17 offset:34884
	ds_read_b128 v[146:149], v76 offset:24576
	ds_read_b128 v[150:153], v76 offset:24832
	s_waitcnt lgkmcnt(7)
	v_pk_mul_f32 v[170:171], v[200:201], v[164:165] op_sel_hi:[1,0]
	v_pk_mul_f32 v[178:179], v[200:201], v[154:155]
	v_pk_mul_f32 v[172:173], v[202:203], v[164:165] op_sel_hi:[1,0]
	v_pk_fma_f32 v[178:179], v[202:203], v[156:157], v[178:179]
	v_pk_mul_f32 v[174:175], v[204:205], v[164:165] op_sel_hi:[1,0]
	v_pk_fma_f32 v[178:179], v[204:205], v[158:159], v[178:179]
	v_pk_mul_f32 v[176:177], v[206:207], v[164:165] op_sel_hi:[1,0]
	v_pk_fma_f32 v[178:179], v[206:207], v[160:161], v[178:179]
	v_pk_fma_f32 v[200:201], v[130:131], v[162:163], v[170:171] op_sel_hi:[1,0,1]
	v_pk_fma_f32 v[202:203], v[132:133], v[162:163], v[172:173] op_sel_hi:[1,0,1]
	v_pk_fma_f32 v[204:205], v[134:135], v[162:163], v[174:175] op_sel_hi:[1,0,1]
	v_pk_fma_f32 v[206:207], v[136:137], v[162:163], v[176:177] op_sel_hi:[1,0,1]
	v_add_f32_e32 v180, v178, v179
	ds_write_b32 v79, v180 offset:15360
	ds_read_b128 v[130:133], v76 offset:9216
	ds_read_b128 v[134:137], v76 offset:9472
	ds_read_b32 v162, v77 offset:33920
	ds_read_b32 v164, v17 offset:34888
	ds_read_b128 v[154:157], v76 offset:25088
	ds_read_b128 v[158:161], v76 offset:25344
	s_waitcnt lgkmcnt(7)
	v_pk_mul_f32 v[170:171], v[200:201], v[168:169] op_sel_hi:[1,0]
	v_pk_mul_f32 v[178:179], v[200:201], v[146:147]
	v_pk_mul_f32 v[172:173], v[202:203], v[168:169] op_sel_hi:[1,0]
	v_pk_fma_f32 v[178:179], v[202:203], v[148:149], v[178:179]
	v_pk_mul_f32 v[174:175], v[204:205], v[168:169] op_sel_hi:[1,0]
	v_pk_fma_f32 v[178:179], v[204:205], v[150:151], v[178:179]
	v_pk_mul_f32 v[176:177], v[206:207], v[168:169] op_sel_hi:[1,0]
	v_pk_fma_f32 v[178:179], v[206:207], v[152:153], v[178:179]
	v_pk_fma_f32 v[200:201], v[138:139], v[166:167], v[170:171] op_sel_hi:[1,0,1]
	v_pk_fma_f32 v[202:203], v[140:141], v[166:167], v[172:173] op_sel_hi:[1,0,1]
	v_pk_fma_f32 v[204:205], v[142:143], v[166:167], v[174:175] op_sel_hi:[1,0,1]
	v_pk_fma_f32 v[206:207], v[144:145], v[166:167], v[176:177] op_sel_hi:[1,0,1]
	v_add_f32_e32 v180, v178, v179
	ds_write_b32 v79, v180 offset:16384
	ds_read_b128 v[138:141], v76 offset:9728
	ds_read_b128 v[142:145], v76 offset:9984
	ds_read_b32 v166, v77 offset:33984
	ds_read_b32 v168, v17 offset:34892
	ds_read_b128 v[146:149], v76 offset:25600
	ds_read_b128 v[150:153], v76 offset:25856
	s_waitcnt lgkmcnt(7)
	v_pk_mul_f32 v[170:171], v[200:201], v[164:165] op_sel_hi:[1,0]
	v_pk_mul_f32 v[178:179], v[200:201], v[154:155]
	v_pk_mul_f32 v[172:173], v[202:203], v[164:165] op_sel_hi:[1,0]
	v_pk_fma_f32 v[178:179], v[202:203], v[156:157], v[178:179]
	v_pk_mul_f32 v[174:175], v[204:205], v[164:165] op_sel_hi:[1,0]
	v_pk_fma_f32 v[178:179], v[204:205], v[158:159], v[178:179]
	v_pk_mul_f32 v[176:177], v[206:207], v[164:165] op_sel_hi:[1,0]
	v_pk_fma_f32 v[178:179], v[206:207], v[160:161], v[178:179]
	v_pk_fma_f32 v[200:201], v[130:131], v[162:163], v[170:171] op_sel_hi:[1,0,1]
	v_pk_fma_f32 v[202:203], v[132:133], v[162:163], v[172:173] op_sel_hi:[1,0,1]
	v_pk_fma_f32 v[204:205], v[134:135], v[162:163], v[174:175] op_sel_hi:[1,0,1]
	v_pk_fma_f32 v[206:207], v[136:137], v[162:163], v[176:177] op_sel_hi:[1,0,1]
	v_add_f32_e32 v180, v178, v179
	ds_write_b32 v79, v180 offset:17408
	ds_read_b128 v[130:133], v76 offset:10240
	ds_read_b128 v[134:137], v76 offset:10496
	ds_read_b32 v162, v77 offset:34048
	ds_read_b32 v164, v17 offset:34896
	ds_read_b128 v[154:157], v76 offset:26112
	ds_read_b128 v[158:161], v76 offset:26368
	s_waitcnt lgkmcnt(7)
	v_pk_mul_f32 v[170:171], v[200:201], v[168:169] op_sel_hi:[1,0]
	v_pk_mul_f32 v[178:179], v[200:201], v[146:147]
	v_pk_mul_f32 v[172:173], v[202:203], v[168:169] op_sel_hi:[1,0]
	v_pk_fma_f32 v[178:179], v[202:203], v[148:149], v[178:179]
	v_pk_mul_f32 v[174:175], v[204:205], v[168:169] op_sel_hi:[1,0]
	v_pk_fma_f32 v[178:179], v[204:205], v[150:151], v[178:179]
	v_pk_mul_f32 v[176:177], v[206:207], v[168:169] op_sel_hi:[1,0]
	v_pk_fma_f32 v[178:179], v[206:207], v[152:153], v[178:179]
	v_pk_fma_f32 v[200:201], v[138:139], v[166:167], v[170:171] op_sel_hi:[1,0,1]
	v_pk_fma_f32 v[202:203], v[140:141], v[166:167], v[172:173] op_sel_hi:[1,0,1]
	v_pk_fma_f32 v[204:205], v[142:143], v[166:167], v[174:175] op_sel_hi:[1,0,1]
	v_pk_fma_f32 v[206:207], v[144:145], v[166:167], v[176:177] op_sel_hi:[1,0,1]
	v_add_f32_e32 v180, v178, v179
	ds_write_b32 v79, v180 offset:18432
	ds_read_b128 v[138:141], v76 offset:10752
	ds_read_b128 v[142:145], v76 offset:11008
	ds_read_b32 v166, v77 offset:34112
	ds_read_b32 v168, v17 offset:34900
	ds_read_b128 v[146:149], v76 offset:26624
	ds_read_b128 v[150:153], v76 offset:26880
	s_waitcnt lgkmcnt(7)
	v_pk_mul_f32 v[170:171], v[200:201], v[164:165] op_sel_hi:[1,0]
	v_pk_mul_f32 v[178:179], v[200:201], v[154:155]
	v_pk_mul_f32 v[172:173], v[202:203], v[164:165] op_sel_hi:[1,0]
	v_pk_fma_f32 v[178:179], v[202:203], v[156:157], v[178:179]
	v_pk_mul_f32 v[174:175], v[204:205], v[164:165] op_sel_hi:[1,0]
	v_pk_fma_f32 v[178:179], v[204:205], v[158:159], v[178:179]
	v_pk_mul_f32 v[176:177], v[206:207], v[164:165] op_sel_hi:[1,0]
	v_pk_fma_f32 v[178:179], v[206:207], v[160:161], v[178:179]
	v_pk_fma_f32 v[200:201], v[130:131], v[162:163], v[170:171] op_sel_hi:[1,0,1]
	v_pk_fma_f32 v[202:203], v[132:133], v[162:163], v[172:173] op_sel_hi:[1,0,1]
	v_pk_fma_f32 v[204:205], v[134:135], v[162:163], v[174:175] op_sel_hi:[1,0,1]
	v_pk_fma_f32 v[206:207], v[136:137], v[162:163], v[176:177] op_sel_hi:[1,0,1]
	v_add_f32_e32 v180, v178, v179
	ds_write_b32 v79, v180 offset:19456
	ds_read_b128 v[130:133], v76 offset:11264
	ds_read_b128 v[134:137], v76 offset:11520
	ds_read_b32 v162, v77 offset:34176
	ds_read_b32 v164, v17 offset:34904
	ds_read_b128 v[154:157], v76 offset:27136
	ds_read_b128 v[158:161], v76 offset:27392
	s_waitcnt lgkmcnt(7)
	v_pk_mul_f32 v[170:171], v[200:201], v[168:169] op_sel_hi:[1,0]
	v_pk_mul_f32 v[178:179], v[200:201], v[146:147]
	v_pk_mul_f32 v[172:173], v[202:203], v[168:169] op_sel_hi:[1,0]
	v_pk_fma_f32 v[178:179], v[202:203], v[148:149], v[178:179]
	v_pk_mul_f32 v[174:175], v[204:205], v[168:169] op_sel_hi:[1,0]
	v_pk_fma_f32 v[178:179], v[204:205], v[150:151], v[178:179]
	v_pk_mul_f32 v[176:177], v[206:207], v[168:169] op_sel_hi:[1,0]
	v_pk_fma_f32 v[178:179], v[206:207], v[152:153], v[178:179]
	v_pk_fma_f32 v[200:201], v[138:139], v[166:167], v[170:171] op_sel_hi:[1,0,1]
	v_pk_fma_f32 v[202:203], v[140:141], v[166:167], v[172:173] op_sel_hi:[1,0,1]
	v_pk_fma_f32 v[204:205], v[142:143], v[166:167], v[174:175] op_sel_hi:[1,0,1]
	v_pk_fma_f32 v[206:207], v[144:145], v[166:167], v[176:177] op_sel_hi:[1,0,1]
	v_add_f32_e32 v180, v178, v179
	ds_write_b32 v79, v180 offset:20480
	ds_read_b128 v[138:141], v76 offset:11776
	ds_read_b128 v[142:145], v76 offset:12032
	ds_read_b32 v166, v77 offset:34240
	ds_read_b32 v168, v17 offset:34908
	ds_read_b128 v[146:149], v76 offset:27648
	ds_read_b128 v[150:153], v76 offset:27904
	s_waitcnt lgkmcnt(7)
	v_pk_mul_f32 v[170:171], v[200:201], v[164:165] op_sel_hi:[1,0]
	v_pk_mul_f32 v[178:179], v[200:201], v[154:155]
	v_pk_mul_f32 v[172:173], v[202:203], v[164:165] op_sel_hi:[1,0]
	v_pk_fma_f32 v[178:179], v[202:203], v[156:157], v[178:179]
	v_pk_mul_f32 v[174:175], v[204:205], v[164:165] op_sel_hi:[1,0]
	v_pk_fma_f32 v[178:179], v[204:205], v[158:159], v[178:179]
	v_pk_mul_f32 v[176:177], v[206:207], v[164:165] op_sel_hi:[1,0]
	v_pk_fma_f32 v[178:179], v[206:207], v[160:161], v[178:179]
	v_pk_fma_f32 v[200:201], v[130:131], v[162:163], v[170:171] op_sel_hi:[1,0,1]
	v_pk_fma_f32 v[202:203], v[132:133], v[162:163], v[172:173] op_sel_hi:[1,0,1]
	v_pk_fma_f32 v[204:205], v[134:135], v[162:163], v[174:175] op_sel_hi:[1,0,1]
	v_pk_fma_f32 v[206:207], v[136:137], v[162:163], v[176:177] op_sel_hi:[1,0,1]
	v_add_f32_e32 v180, v178, v179
	ds_write_b32 v79, v180 offset:21504
	ds_read_b128 v[130:133], v76 offset:12288
	ds_read_b128 v[134:137], v76 offset:12544
	ds_read_b32 v162, v77 offset:34304
	ds_read_b32 v164, v17 offset:34912
	ds_read_b128 v[154:157], v76 offset:28160
	ds_read_b128 v[158:161], v76 offset:28416
	s_waitcnt lgkmcnt(7)
	v_pk_mul_f32 v[170:171], v[200:201], v[168:169] op_sel_hi:[1,0]
	v_pk_mul_f32 v[178:179], v[200:201], v[146:147]
	v_pk_mul_f32 v[172:173], v[202:203], v[168:169] op_sel_hi:[1,0]
	v_pk_fma_f32 v[178:179], v[202:203], v[148:149], v[178:179]
	v_pk_mul_f32 v[174:175], v[204:205], v[168:169] op_sel_hi:[1,0]
	v_pk_fma_f32 v[178:179], v[204:205], v[150:151], v[178:179]
	v_pk_mul_f32 v[176:177], v[206:207], v[168:169] op_sel_hi:[1,0]
	v_pk_fma_f32 v[178:179], v[206:207], v[152:153], v[178:179]
	v_pk_fma_f32 v[200:201], v[138:139], v[166:167], v[170:171] op_sel_hi:[1,0,1]
	v_pk_fma_f32 v[202:203], v[140:141], v[166:167], v[172:173] op_sel_hi:[1,0,1]
	v_pk_fma_f32 v[204:205], v[142:143], v[166:167], v[174:175] op_sel_hi:[1,0,1]
	v_pk_fma_f32 v[206:207], v[144:145], v[166:167], v[176:177] op_sel_hi:[1,0,1]
	v_add_f32_e32 v180, v178, v179
	ds_write_b32 v79, v180 offset:22528
	ds_read_b128 v[138:141], v76 offset:12800
	ds_read_b128 v[142:145], v76 offset:13056
	ds_read_b32 v166, v77 offset:34368
	ds_read_b32 v168, v17 offset:34916
	ds_read_b128 v[146:149], v76 offset:28672
	ds_read_b128 v[150:153], v76 offset:28928
	s_waitcnt lgkmcnt(7)
	v_pk_mul_f32 v[170:171], v[200:201], v[164:165] op_sel_hi:[1,0]
	v_pk_mul_f32 v[178:179], v[200:201], v[154:155]
	v_pk_mul_f32 v[172:173], v[202:203], v[164:165] op_sel_hi:[1,0]
	v_pk_fma_f32 v[178:179], v[202:203], v[156:157], v[178:179]
	v_pk_mul_f32 v[174:175], v[204:205], v[164:165] op_sel_hi:[1,0]
	v_pk_fma_f32 v[178:179], v[204:205], v[158:159], v[178:179]
	v_pk_mul_f32 v[176:177], v[206:207], v[164:165] op_sel_hi:[1,0]
	v_pk_fma_f32 v[178:179], v[206:207], v[160:161], v[178:179]
	v_pk_fma_f32 v[200:201], v[130:131], v[162:163], v[170:171] op_sel_hi:[1,0,1]
	v_pk_fma_f32 v[202:203], v[132:133], v[162:163], v[172:173] op_sel_hi:[1,0,1]
	v_pk_fma_f32 v[204:205], v[134:135], v[162:163], v[174:175] op_sel_hi:[1,0,1]
	v_pk_fma_f32 v[206:207], v[136:137], v[162:163], v[176:177] op_sel_hi:[1,0,1]
	v_add_f32_e32 v180, v178, v179
	ds_write_b32 v79, v180 offset:23552
	ds_read_b128 v[130:133], v76 offset:13312
	ds_read_b128 v[134:137], v76 offset:13568
	ds_read_b32 v162, v77 offset:34432
	ds_read_b32 v164, v17 offset:34920
	ds_read_b128 v[154:157], v76 offset:29184
	ds_read_b128 v[158:161], v76 offset:29440
	s_waitcnt lgkmcnt(7)
	v_pk_mul_f32 v[170:171], v[200:201], v[168:169] op_sel_hi:[1,0]
	v_pk_mul_f32 v[178:179], v[200:201], v[146:147]
	v_pk_mul_f32 v[172:173], v[202:203], v[168:169] op_sel_hi:[1,0]
	v_pk_fma_f32 v[178:179], v[202:203], v[148:149], v[178:179]
	v_pk_mul_f32 v[174:175], v[204:205], v[168:169] op_sel_hi:[1,0]
	v_pk_fma_f32 v[178:179], v[204:205], v[150:151], v[178:179]
	v_pk_mul_f32 v[176:177], v[206:207], v[168:169] op_sel_hi:[1,0]
	v_pk_fma_f32 v[178:179], v[206:207], v[152:153], v[178:179]
	v_pk_fma_f32 v[200:201], v[138:139], v[166:167], v[170:171] op_sel_hi:[1,0,1]
	v_pk_fma_f32 v[202:203], v[140:141], v[166:167], v[172:173] op_sel_hi:[1,0,1]
	v_pk_fma_f32 v[204:205], v[142:143], v[166:167], v[174:175] op_sel_hi:[1,0,1]
	v_pk_fma_f32 v[206:207], v[144:145], v[166:167], v[176:177] op_sel_hi:[1,0,1]
	v_add_f32_e32 v180, v178, v179
	ds_write_b32 v79, v180 offset:24576
	ds_read_b128 v[138:141], v76 offset:13824
	ds_read_b128 v[142:145], v76 offset:14080
	ds_read_b32 v166, v77 offset:34496
	ds_read_b32 v168, v17 offset:34924
	ds_read_b128 v[146:149], v76 offset:29696
	ds_read_b128 v[150:153], v76 offset:29952
	s_waitcnt lgkmcnt(7)
	v_pk_mul_f32 v[170:171], v[200:201], v[164:165] op_sel_hi:[1,0]
	v_pk_mul_f32 v[178:179], v[200:201], v[154:155]
	v_pk_mul_f32 v[172:173], v[202:203], v[164:165] op_sel_hi:[1,0]
	v_pk_fma_f32 v[178:179], v[202:203], v[156:157], v[178:179]
	v_pk_mul_f32 v[174:175], v[204:205], v[164:165] op_sel_hi:[1,0]
	v_pk_fma_f32 v[178:179], v[204:205], v[158:159], v[178:179]
	v_pk_mul_f32 v[176:177], v[206:207], v[164:165] op_sel_hi:[1,0]
	v_pk_fma_f32 v[178:179], v[206:207], v[160:161], v[178:179]
	v_pk_fma_f32 v[200:201], v[130:131], v[162:163], v[170:171] op_sel_hi:[1,0,1]
	v_pk_fma_f32 v[202:203], v[132:133], v[162:163], v[172:173] op_sel_hi:[1,0,1]
	v_pk_fma_f32 v[204:205], v[134:135], v[162:163], v[174:175] op_sel_hi:[1,0,1]
	v_pk_fma_f32 v[206:207], v[136:137], v[162:163], v[176:177] op_sel_hi:[1,0,1]
	v_add_f32_e32 v180, v178, v179
	ds_write_b32 v79, v180 offset:25600
	ds_read_b128 v[130:133], v76 offset:14336
	ds_read_b128 v[134:137], v76 offset:14592
	ds_read_b32 v162, v77 offset:34560
	ds_read_b32 v164, v17 offset:34928
	ds_read_b128 v[154:157], v76 offset:30208
	ds_read_b128 v[158:161], v76 offset:30464
	s_waitcnt lgkmcnt(7)
	v_pk_mul_f32 v[170:171], v[200:201], v[168:169] op_sel_hi:[1,0]
	v_pk_mul_f32 v[178:179], v[200:201], v[146:147]
	v_pk_mul_f32 v[172:173], v[202:203], v[168:169] op_sel_hi:[1,0]
	v_pk_fma_f32 v[178:179], v[202:203], v[148:149], v[178:179]
	v_pk_mul_f32 v[174:175], v[204:205], v[168:169] op_sel_hi:[1,0]
	v_pk_fma_f32 v[178:179], v[204:205], v[150:151], v[178:179]
	v_pk_mul_f32 v[176:177], v[206:207], v[168:169] op_sel_hi:[1,0]
	v_pk_fma_f32 v[178:179], v[206:207], v[152:153], v[178:179]
	v_pk_fma_f32 v[200:201], v[138:139], v[166:167], v[170:171] op_sel_hi:[1,0,1]
	v_pk_fma_f32 v[202:203], v[140:141], v[166:167], v[172:173] op_sel_hi:[1,0,1]
	v_pk_fma_f32 v[204:205], v[142:143], v[166:167], v[174:175] op_sel_hi:[1,0,1]
	v_pk_fma_f32 v[206:207], v[144:145], v[166:167], v[176:177] op_sel_hi:[1,0,1]
	v_add_f32_e32 v180, v178, v179
	ds_write_b32 v79, v180 offset:26624
	ds_read_b128 v[138:141], v76 offset:14848
	ds_read_b128 v[142:145], v76 offset:15104
	ds_read_b32 v166, v77 offset:34624
	ds_read_b32 v168, v17 offset:34932
	ds_read_b128 v[146:149], v76 offset:30720
	ds_read_b128 v[150:153], v76 offset:30976
	s_waitcnt lgkmcnt(7)
	v_pk_mul_f32 v[170:171], v[200:201], v[164:165] op_sel_hi:[1,0]
	v_pk_mul_f32 v[178:179], v[200:201], v[154:155]
	v_pk_mul_f32 v[172:173], v[202:203], v[164:165] op_sel_hi:[1,0]
	v_pk_fma_f32 v[178:179], v[202:203], v[156:157], v[178:179]
	v_pk_mul_f32 v[174:175], v[204:205], v[164:165] op_sel_hi:[1,0]
	v_pk_fma_f32 v[178:179], v[204:205], v[158:159], v[178:179]
	v_pk_mul_f32 v[176:177], v[206:207], v[164:165] op_sel_hi:[1,0]
	v_pk_fma_f32 v[178:179], v[206:207], v[160:161], v[178:179]
	v_pk_fma_f32 v[200:201], v[130:131], v[162:163], v[170:171] op_sel_hi:[1,0,1]
	v_pk_fma_f32 v[202:203], v[132:133], v[162:163], v[172:173] op_sel_hi:[1,0,1]
	v_pk_fma_f32 v[204:205], v[134:135], v[162:163], v[174:175] op_sel_hi:[1,0,1]
	v_pk_fma_f32 v[206:207], v[136:137], v[162:163], v[176:177] op_sel_hi:[1,0,1]
	v_add_f32_e32 v180, v178, v179
	ds_write_b32 v79, v180 offset:27648
	ds_read_b128 v[130:133], v76 offset:15360
	ds_read_b128 v[134:137], v76 offset:15616
	ds_read_b32 v162, v77 offset:34688
	ds_read_b32 v164, v17 offset:34936
	ds_read_b128 v[154:157], v76 offset:31232
	ds_read_b128 v[158:161], v76 offset:31488
	s_waitcnt lgkmcnt(7)
	v_pk_mul_f32 v[170:171], v[200:201], v[168:169] op_sel_hi:[1,0]
	v_pk_mul_f32 v[178:179], v[200:201], v[146:147]
	v_pk_mul_f32 v[172:173], v[202:203], v[168:169] op_sel_hi:[1,0]
	v_pk_fma_f32 v[178:179], v[202:203], v[148:149], v[178:179]
	v_pk_mul_f32 v[174:175], v[204:205], v[168:169] op_sel_hi:[1,0]
	v_pk_fma_f32 v[178:179], v[204:205], v[150:151], v[178:179]
	v_pk_mul_f32 v[176:177], v[206:207], v[168:169] op_sel_hi:[1,0]
	v_pk_fma_f32 v[178:179], v[206:207], v[152:153], v[178:179]
	v_pk_fma_f32 v[200:201], v[138:139], v[166:167], v[170:171] op_sel_hi:[1,0,1]
	v_pk_fma_f32 v[202:203], v[140:141], v[166:167], v[172:173] op_sel_hi:[1,0,1]
	v_pk_fma_f32 v[204:205], v[142:143], v[166:167], v[174:175] op_sel_hi:[1,0,1]
	v_pk_fma_f32 v[206:207], v[144:145], v[166:167], v[176:177] op_sel_hi:[1,0,1]
	v_add_f32_e32 v180, v178, v179
	ds_write_b32 v79, v180 offset:28672
	ds_read_b128 v[138:141], v76 offset:15872
	ds_read_b128 v[142:145], v76 offset:16128
	ds_read_b32 v166, v77 offset:34752
	ds_read_b32 v168, v17 offset:34940
	ds_read_b128 v[146:149], v76 offset:31744
	ds_read_b128 v[150:153], v76 offset:32000
	s_waitcnt lgkmcnt(7)
	v_pk_mul_f32 v[170:171], v[200:201], v[164:165] op_sel_hi:[1,0]
	v_pk_mul_f32 v[178:179], v[200:201], v[154:155]
	v_pk_mul_f32 v[172:173], v[202:203], v[164:165] op_sel_hi:[1,0]
	v_pk_fma_f32 v[178:179], v[202:203], v[156:157], v[178:179]
	v_pk_mul_f32 v[174:175], v[204:205], v[164:165] op_sel_hi:[1,0]
	v_pk_fma_f32 v[178:179], v[204:205], v[158:159], v[178:179]
	v_pk_mul_f32 v[176:177], v[206:207], v[164:165] op_sel_hi:[1,0]
	v_pk_fma_f32 v[178:179], v[206:207], v[160:161], v[178:179]
	v_pk_fma_f32 v[200:201], v[130:131], v[162:163], v[170:171] op_sel_hi:[1,0,1]
	v_pk_fma_f32 v[202:203], v[132:133], v[162:163], v[172:173] op_sel_hi:[1,0,1]
	v_pk_fma_f32 v[204:205], v[134:135], v[162:163], v[174:175] op_sel_hi:[1,0,1]
	v_pk_fma_f32 v[206:207], v[136:137], v[162:163], v[176:177] op_sel_hi:[1,0,1]
	v_add_f32_e32 v180, v178, v179
	ds_write_b32 v79, v180 offset:29696
	ds_read_b128 v[154:157], v76 offset:32256
	ds_read_b128 v[158:161], v76 offset:32512
	s_waitcnt lgkmcnt(3)
	v_pk_mul_f32 v[170:171], v[200:201], v[168:169] op_sel_hi:[1,0]
	v_pk_mul_f32 v[178:179], v[200:201], v[146:147]
	v_pk_mul_f32 v[172:173], v[202:203], v[168:169] op_sel_hi:[1,0]
	v_pk_fma_f32 v[178:179], v[202:203], v[148:149], v[178:179]
	v_pk_mul_f32 v[174:175], v[204:205], v[168:169] op_sel_hi:[1,0]
	v_pk_fma_f32 v[178:179], v[204:205], v[150:151], v[178:179]
	v_pk_mul_f32 v[176:177], v[206:207], v[168:169] op_sel_hi:[1,0]
	v_pk_fma_f32 v[178:179], v[206:207], v[152:153], v[178:179]
	v_pk_fma_f32 v[200:201], v[138:139], v[166:167], v[170:171] op_sel_hi:[1,0,1]
	v_pk_fma_f32 v[202:203], v[140:141], v[166:167], v[172:173] op_sel_hi:[1,0,1]
	v_pk_fma_f32 v[204:205], v[142:143], v[166:167], v[174:175] op_sel_hi:[1,0,1]
	v_pk_fma_f32 v[206:207], v[144:145], v[166:167], v[176:177] op_sel_hi:[1,0,1]
	v_add_f32_e32 v180, v178, v179
	ds_write_b32 v79, v180 offset:30720
	s_waitcnt lgkmcnt(1)
	v_pk_mul_f32 v[178:179], v[200:201], v[154:155]
	v_pk_fma_f32 v[178:179], v[202:203], v[156:157], v[178:179]
	v_pk_fma_f32 v[178:179], v[204:205], v[158:159], v[178:179]
	v_pk_fma_f32 v[178:179], v[206:207], v[160:161], v[178:179]
	v_add_f32_e32 v180, v178, v179
	ds_write_b32 v79, v180 offset:31744

.LBB0_943:
	s_and_b32 s12, s5, 64
	s_mulk_i32 s12, 0x90
	v_add_u32_e32 v150, s12, v237
	ds_read_b128 v[152:155], v150
	ds_read_b128 v[168:171], v150 offset:64
	v_add_u32_e32 v204, s12, v238
	v_add_u32_e32 v151, 0x4800, v204
	v_lshl_add_u64 v[102:103], v[144:145], 0, v[16:17]
	global_load_dwordx4 v[102:105], v[102:103], off
	v_lshl_add_u64 v[106:107], v[140:141], 0, v[16:17]
	v_lshl_add_u64 v[110:111], v[142:143], 0, v[16:17]
	global_load_dwordx4 v[106:109], v[106:107], off
	s_waitcnt vmcnt(9) lgkmcnt(1)
	v_mfma_f32_16x16x32_bf16 v[156:159], v[152:155], v[8:11], v[0:3]
	global_load_dwordx4 v[110:113], v[110:111], off
	v_lshl_add_u64 v[114:115], v[138:139], 0, v[16:17]
	global_load_dwordx4 v[114:117], v[114:115], off
	s_waitcnt vmcnt(9)
	v_mfma_f32_16x16x32_bf16 v[160:163], v[152:155], v[18:21], v[0:3]
	ds_read_b128 v[184:187], v150 offset:2368
	s_add_i32 s5, s5, 64
	s_and_b32 s12, s5, 64
	s_waitcnt vmcnt(7)
	v_mfma_f32_16x16x32_bf16 v[164:167], v[152:155], v[26:29], v[0:3]
	s_mulk_i32 s12, 0x90
	v_lshl_add_u64 v[138:139], v[138:139], 0, s[66:67]
	v_lshl_add_u64 v[140:141], v[140:141], 0, s[66:67]
	s_waitcnt vmcnt(5)
	v_mfma_f32_16x16x32_bf16 v[152:155], v[152:155], v[34:37], v[0:3]
	v_lshl_add_u64 v[142:143], v[142:143], 0, s[68:69]
	v_lshl_add_u64 v[144:145], v[144:145], 0, s[68:69]
	s_cmp_eq_u32 s11, s5
	s_waitcnt lgkmcnt(1)
	v_mfma_f32_16x16x32_bf16 v[156:159], v[168:171], v[4:7], v[156:159]
	v_mfma_f32_16x16x32_bf16 v[160:163], v[168:171], v[12:15], v[160:163]
	v_mfma_f32_16x16x32_bf16 v[164:167], v[168:171], v[22:25], v[164:167]
	s_nop 5
	v_exp_f32_e32 v189, v157
	v_exp_f32_e32 v191, v158
	v_exp_f32_e32 v195, v159
	s_waitcnt vmcnt(4)
	v_mfma_f32_16x16x32_bf16 v[152:155], v[168:171], v[30:33], v[152:155]
	ds_read_b128 v[168:171], v150 offset:2304
	v_exp_f32_e32 v197, v165
	v_exp_f32_e32 v199, v166
	s_waitcnt lgkmcnt(0)
	v_mfma_f32_16x16x32_bf16 v[172:175], v[168:171], v[8:11], v[0:3]
	v_exp_f32_e32 v203, v167
	s_nop 1
	v_exp_f32_e32 v196, v153
	v_exp_f32_e32 v198, v154
	v_mfma_f32_16x16x32_bf16 v[176:179], v[168:171], v[18:21], v[0:3]
	v_exp_f32_e32 v202, v155
	v_exp_f32_e32 v188, v161
	v_exp_f32_e32 v190, v162
	v_mfma_f32_16x16x32_bf16 v[180:183], v[168:171], v[26:29], v[0:3]
	v_exp_f32_e32 v194, v163
	v_add_f32_e32 v154, v198, v202
	v_add_f32_e32 v155, v199, v203
	v_cvt_pk_bf16_f32 v165, v199, v203
	v_mfma_f32_16x16x32_bf16 v[168:171], v[168:171], v[34:37], v[0:3]
	v_mfma_f32_16x16x32_bf16 v[172:175], v[184:187], v[4:7], v[172:175]
	v_mfma_f32_16x16x32_bf16 v[176:179], v[184:187], v[12:15], v[176:179]
	v_mfma_f32_16x16x32_bf16 v[180:183], v[184:187], v[22:25], v[180:183]
	s_nop 5
	v_exp_f32_e32 v193, v174
	v_exp_f32_e32 v192, v178
	v_exp_f32_e32 v174, v179
	v_mfma_f32_16x16x32_bf16 v[168:171], v[184:187], v[30:33], v[168:171]
	v_exp_f32_e32 v187, v172
	v_exp_f32_e32 v186, v176
	v_exp_f32_e32 v172, v177
	v_exp_f32_e32 v177, v164
	v_exp_f32_e32 v176, v152
	v_exp_f32_e32 v179, v180
	v_exp_f32_e32 v181, v181
	v_exp_f32_e32 v201, v182
	v_exp_f32_e32 v183, v183
	v_exp_f32_e32 v178, v168
	v_exp_f32_e32 v180, v169
	v_exp_f32_e32 v200, v170
	v_exp_f32_e32 v182, v171
	v_exp_f32_e32 v185, v156
	v_exp_f32_e32 v184, v160
	v_add_f32_e32 v152, v176, v196
	v_add_f32_e32 v153, v177, v197
	v_exp_f32_e32 v173, v173
	v_exp_f32_e32 v175, v175
	v_add_f32_e32 v152, v152, v154
	v_add_f32_e32 v153, v153, v155
	v_add_f32_e32 v154, v178, v180
	v_add_f32_e32 v155, v179, v181
	v_add_f32_e32 v156, v200, v182
	v_add_f32_e32 v157, v201, v183
	v_add_f32_e32 v160, v192, v174
	v_add_f32_e32 v161, v193, v175
	v_add_f32_e32 v154, v154, v156
	v_add_f32_e32 v155, v155, v157
	v_cvt_pk_bf16_f32 v156, v185, v189
	v_cvt_pk_bf16_f32 v157, v191, v195
	v_cvt_pk_bf16_f32 v158, v187, v173
	v_cvt_pk_bf16_f32 v159, v193, v175
	v_cvt_pk_bf16_f32 v162, v186, v172
	s_nop 0
	v_add_f32_e32 v152, v152, v154
	v_add_f32_e32 v153, v153, v155
	v_add_f32_e32 v154, v190, v194
	v_add_f32_e32 v155, v191, v195
	v_add_f32_e32 v146, v146, v152
	v_add_f32_e32 v147, v147, v153
	v_add_f32_e32 v152, v184, v188
	v_add_f32_e32 v153, v185, v189
	v_cvt_pk_bf16_f32 v163, v192, v174
	v_cvt_pk_bf16_f32 v164, v177, v197
	v_cvt_pk_bf16_f32 v166, v179, v181
	v_cvt_pk_bf16_f32 v167, v201, v183
	v_cvt_pk_bf16_f32 v168, v176, v196
	s_nop 0
	v_add_f32_e32 v152, v152, v154
	v_add_f32_e32 v153, v153, v155
	v_add_f32_e32 v154, v186, v172
	v_add_f32_e32 v155, v187, v173
	v_cvt_pk_bf16_f32 v169, v198, v202
	v_cvt_pk_bf16_f32 v170, v178, v180
	v_cvt_pk_bf16_f32 v171, v200, v182
	s_nop 0
	v_add_f32_e32 v154, v154, v160
	v_add_f32_e32 v155, v155, v161
	v_cvt_pk_bf16_f32 v160, v184, v188
	v_cvt_pk_bf16_f32 v161, v190, v194
	ds_read_b128 v[188:191], v150 offset:6976
	v_add_f32_e32 v152, v152, v154
	v_add_f32_e32 v153, v153, v155
	s_nop 0
	v_add_f32_e32 v148, v148, v152
	v_add_f32_e32 v149, v149, v153
	ds_read2_b64 v[152:155], v151 offset1:4
	s_waitcnt lgkmcnt(0)
	v_mfma_f32_16x16x32_bf16 v[98:101], v[152:155], v[156:159], v[98:101]
	v_mfma_f32_16x16x32_bf16 v[94:97], v[152:155], v[160:163], v[94:97]
	v_mfma_f32_16x16x32_bf16 v[90:93], v[152:155], v[164:167], v[90:93]
	v_mfma_f32_16x16x32_bf16 v[86:89], v[152:155], v[168:171], v[86:89]
	v_add_u32_e32 v152, 0x5000, v204
	ds_read2_b64 v[172:175], v152 offset0:32 offset1:36
	v_add_u32_e32 v153, 0x5800, v204
	s_waitcnt lgkmcnt(0)
	v_mfma_f32_16x16x32_bf16 v[82:85], v[172:175], v[156:159], v[82:85]
	v_add_u32_e32 v154, 0x6000, v204
	v_mfma_f32_16x16x32_bf16 v[78:81], v[172:175], v[160:163], v[78:81]
	v_mfma_f32_16x16x32_bf16 v[74:77], v[172:175], v[164:167], v[74:77]
	v_mfma_f32_16x16x32_bf16 v[70:73], v[172:175], v[168:171], v[70:73]
	ds_read2_b64 v[172:175], v153 offset0:64 offset1:68
	s_waitcnt lgkmcnt(0)
	v_mfma_f32_16x16x32_bf16 v[66:69], v[172:175], v[156:159], v[66:69]
	v_mfma_f32_16x16x32_bf16 v[62:65], v[172:175], v[160:163], v[62:65]
	v_mfma_f32_16x16x32_bf16 v[58:61], v[172:175], v[164:167], v[58:61]
	v_mfma_f32_16x16x32_bf16 v[54:57], v[172:175], v[168:171], v[54:57]
	ds_read2_b64 v[172:175], v154 offset0:96 offset1:100
	s_waitcnt lgkmcnt(0)
	v_mfma_f32_16x16x32_bf16 v[50:53], v[172:175], v[156:159], v[50:53]
	ds_read_b128 v[156:159], v150 offset:4608
	v_mfma_f32_16x16x32_bf16 v[46:49], v[172:175], v[160:163], v[46:49]
	v_mfma_f32_16x16x32_bf16 v[42:45], v[172:175], v[164:167], v[42:45]
	v_mfma_f32_16x16x32_bf16 v[38:41], v[172:175], v[168:171], v[38:41]
	ds_read_b128 v[172:175], v150 offset:4672
	s_waitcnt lgkmcnt(1)
	v_mfma_f32_16x16x32_bf16 v[160:163], v[156:159], v[8:11], v[0:3]
	v_mfma_f32_16x16x32_bf16 v[164:167], v[156:159], v[18:21], v[0:3]
	v_mfma_f32_16x16x32_bf16 v[168:171], v[156:159], v[26:29], v[0:3]
	v_mfma_f32_16x16x32_bf16 v[156:159], v[156:159], v[34:37], v[0:3]
	s_waitcnt lgkmcnt(0)
	v_mfma_f32_16x16x32_bf16 v[160:163], v[172:175], v[4:7], v[160:163]
	v_mfma_f32_16x16x32_bf16 v[164:167], v[172:175], v[12:15], v[164:167]
	v_mfma_f32_16x16x32_bf16 v[168:171], v[172:175], v[22:25], v[168:171]
	s_nop 5
	v_exp_f32_e32 v193, v161
	v_exp_f32_e32 v195, v162
	v_exp_f32_e32 v199, v163
	v_mfma_f32_16x16x32_bf16 v[156:159], v[172:175], v[30:33], v[156:159]
	ds_read_b128 v[172:175], v150 offset:6912
	v_exp_f32_e32 v192, v165
	v_exp_f32_e32 v194, v166
	s_waitcnt lgkmcnt(0)
	v_mfma_f32_16x16x32_bf16 v[176:179], v[172:175], v[8:11], v[0:3]
	v_exp_f32_e32 v198, v167
	v_exp_f32_e32 v169, v169
	v_exp_f32_e32 v171, v171
	v_mfma_f32_16x16x32_bf16 v[180:183], v[172:175], v[18:21], v[0:3]
	v_add_f32_e64 v162, v194, v198
	v_add_f32_e64 v163, v195, v199
	v_mfma_f32_16x16x32_bf16 v[184:187], v[172:175], v[26:29], v[0:3]
	v_mfma_f32_16x16x32_bf16 v[172:175], v[172:175], v[34:37], v[0:3]
	v_mfma_f32_16x16x32_bf16 v[176:179], v[188:191], v[4:7], v[176:179]
	v_mfma_f32_16x16x32_bf16 v[180:183], v[188:191], v[12:15], v[180:183]
	v_mfma_f32_16x16x32_bf16 v[184:187], v[188:191], v[22:25], v[184:187]
	s_nop 5
	v_exp_f32_e32 v177, v177
	v_exp_f32_e32 v197, v178
	v_exp_f32_e32 v179, v179
	v_mfma_f32_16x16x32_bf16 v[172:175], v[188:191], v[30:33], v[172:175]
	v_exp_f32_e32 v189, v160
	v_exp_f32_e32 v188, v164
	v_exp_f32_e32 v191, v176
	v_exp_f32_e32 v190, v180
	v_exp_f32_e32 v176, v181
	v_exp_f32_e32 v196, v182
	v_exp_f32_e32 v178, v183
	v_add_f32_e32 v160, v188, v192
	v_add_f32_e32 v161, v189, v193
	v_cvt_pk_bf16_f32 v166, v190, v176
	v_exp_f32_e32 v183, v170
	v_add_f32_e32 v160, v160, v162
	v_add_f32_e32 v161, v161, v163
	v_add_f32_e32 v162, v190, v176
	v_add_f32_e32 v163, v191, v177
	v_add_f32_e32 v164, v196, v178
	v_add_f32_e32 v165, v197, v179
	v_exp_f32_e32 v176, v156
	v_add_f32_e32 v162, v162, v164
	v_add_f32_e32 v163, v163, v165
	v_exp_f32_e32 v182, v158
	v_add_f32_e32 v164, v160, v162
	v_add_f32_e32 v165, v161, v163
	v_cvt_pk_bf16_f32 v162, v191, v177
	v_exp_f32_e32 v177, v168
	v_exp_f32_e32 v168, v157
	v_exp_f32_e32 v170, v159
	v_cvt_pk_bf16_f32 v163, v197, v179
	v_cvt_pk_bf16_f32 v167, v196, v178
	v_exp_f32_e32 v179, v184
	v_exp_f32_e32 v181, v185
	v_exp_f32_e32 v185, v186
	v_exp_f32_e32 v187, v187
	v_exp_f32_e32 v178, v172
	v_exp_f32_e32 v180, v173
	v_exp_f32_e32 v184, v174
	v_exp_f32_e32 v186, v175
	v_add_f32_e32 v156, v176, v168
	v_add_f32_e32 v157, v177, v169
	v_add_f32_e32 v158, v182, v170
	v_add_f32_e32 v159, v183, v171
	v_cvt_pk_bf16_f32 v160, v189, v193
	v_add_f32_e32 v172, v184, v186
	v_add_f32_e32 v173, v185, v187
	v_add_f32_e32 v156, v156, v158
	v_add_f32_e32 v157, v157, v159
	v_add_f32_e32 v158, v178, v180
	v_add_f32_e32 v159, v179, v181
	v_cvt_pk_bf16_f32 v161, v195, v199
	v_add_f32_e32 v148, v148, v164
	v_add_f32_e32 v149, v149, v165
	v_add_f32_e32 v158, v158, v172
	v_add_f32_e32 v159, v159, v173
	v_cvt_pk_bf16_f32 v164, v188, v192
	v_cvt_pk_bf16_f32 v165, v194, v198
	v_cvt_pk_bf16_f32 v168, v176, v168
	s_nop 0
	v_add_f32_e32 v172, v156, v158
	v_add_f32_e32 v173, v157, v159
	v_cvt_pk_bf16_f32 v156, v177, v169
	v_cvt_pk_bf16_f32 v157, v183, v171
	v_cvt_pk_bf16_f32 v158, v179, v181
	v_cvt_pk_bf16_f32 v159, v185, v187
	v_cvt_pk_bf16_f32 v169, v182, v170
	s_nop 0
	v_add_f32_e32 v146, v146, v172
	v_add_f32_e32 v147, v147, v173
	ds_read2_b64 v[172:175], v151 offset0:8 offset1:12
	v_cvt_pk_bf16_f32 v170, v178, v180
	v_cvt_pk_bf16_f32 v171, v184, v186
	s_waitcnt lgkmcnt(0)
	v_mfma_f32_16x16x32_bf16 v[98:101], v[172:175], v[160:163], v[98:101]
	v_mfma_f32_16x16x32_bf16 v[94:97], v[172:175], v[164:167], v[94:97]
	v_mfma_f32_16x16x32_bf16 v[90:93], v[172:175], v[156:159], v[90:93]
	v_mfma_f32_16x16x32_bf16 v[86:89], v[172:175], v[168:171], v[86:89]
	ds_read2_b64 v[172:175], v152 offset0:40 offset1:44
	ds_read2_b64 v[150:153], v153 offset0:72 offset1:76
	s_waitcnt lgkmcnt(0)
	v_mfma_f32_16x16x32_bf16 v[66:69], v[150:153], v[160:163], v[66:69]
	v_mfma_f32_16x16x32_bf16 v[62:65], v[150:153], v[164:167], v[62:65]
	v_mfma_f32_16x16x32_bf16 v[58:61], v[150:153], v[156:159], v[58:61]
	v_mfma_f32_16x16x32_bf16 v[54:57], v[150:153], v[168:171], v[54:57]
	ds_read2_b64 v[150:153], v154 offset0:104 offset1:108
	v_mfma_f32_16x16x32_bf16 v[82:85], v[172:175], v[160:163], v[82:85]
	v_mfma_f32_16x16x32_bf16 v[78:81], v[172:175], v[164:167], v[78:81]
	v_mfma_f32_16x16x32_bf16 v[74:77], v[172:175], v[156:159], v[74:77]
	v_mfma_f32_16x16x32_bf16 v[70:73], v[172:175], v[168:171], v[70:73]
	s_waitcnt lgkmcnt(0)
	v_mfma_f32_16x16x32_bf16 v[50:53], v[150:153], v[160:163], v[50:53]
	v_mfma_f32_16x16x32_bf16 v[46:49], v[150:153], v[164:167], v[46:49]
	v_mfma_f32_16x16x32_bf16 v[42:45], v[150:153], v[156:159], v[42:45]
	v_mfma_f32_16x16x32_bf16 v[38:41], v[150:153], v[168:171], v[38:41]
	v_add_u32_e32 v150, s12, v230
	v_lshl_add_u32 v151, v233, 1, v150
	s_waitcnt vmcnt(3)
	ds_write_b128 v151, v[102:105]
	s_waitcnt vmcnt(2)
	ds_write_b128 v151, v[106:109] offset:18432
	v_lshl_add_u32 v102, v235, 1, v150
	s_waitcnt vmcnt(1)
	ds_write_b128 v102, v[110:113]
	s_waitcnt vmcnt(0)
	ds_write_b128 v102, v[114:117] offset:18432
	s_waitcnt lgkmcnt(0)
	s_barrier
	s_cbranch_scc0 .LBB0_943
	ds_read_b128 v[102:105], v237 offset:9216
	ds_read_b128 v[106:109], v237 offset:9280
	ds_read_b128 v[186:189], v237 offset:11520
	ds_read_b128 v[196:199], v237 offset:11584
	ds_read_b128 v[244:247], v237 offset:13824
	ds_read_b128 v[248:251], v237 offset:13888
	ds_read_b128 v[216:219], v237 offset:16128
	ds_read_b128 v[220:223], v237 offset:16192
	s_waitcnt lgkmcnt(7)
	v_mfma_f32_16x16x32_bf16 v[110:113], v[102:105], v[8:11], v[0:3]
	s_lshl_b32 s52, s4, 1
	s_add_i32 s6, s6, s3
	s_cmpk_gt_i32 s6, 0x40f
	v_mfma_f32_16x16x32_bf16 v[114:117], v[102:105], v[18:21], v[0:3]
	v_mfma_f32_16x16x32_bf16 v[164:167], v[102:105], v[26:29], v[0:3]
	v_mfma_f32_16x16x32_bf16 v[102:105], v[102:105], v[34:37], v[0:3]
	s_waitcnt lgkmcnt(6)
	v_mfma_f32_16x16x32_bf16 v[110:113], v[106:109], v[4:7], v[110:113]
	v_mfma_f32_16x16x32_bf16 v[114:117], v[106:109], v[12:15], v[114:117]
	s_waitcnt lgkmcnt(5)
	v_mfma_f32_16x16x32_bf16 v[152:155], v[186:189], v[18:21], v[0:3]
	s_nop 4
	v_exp_f32_e32 v140, v110
	v_exp_f32_e32 v150, v111
	v_exp_f32_e32 v156, v112
	v_exp_f32_e32 v162, v113
	s_waitcnt lgkmcnt(4)
	v_mfma_f32_16x16x32_bf16 v[110:113], v[196:199], v[12:15], v[152:155]
	v_exp_f32_e32 v168, v116
	v_exp_f32_e32 v176, v117
	s_nop 0
	v_exp_f32_e32 v154, v114
	v_mfma_f32_16x16x32_bf16 v[178:181], v[106:109], v[22:25], v[164:167]
	s_nop 2
	v_exp_f32_e32 v152, v110
	v_exp_f32_e32 v160, v111
	v_exp_f32_e32 v172, v113
	v_exp_f32_e32 v166, v115
	v_mfma_f32_16x16x32_bf16 v[102:105], v[106:109], v[30:33], v[102:105]
	v_exp_f32_e32 v164, v112
	v_exp_f32_e32 v174, v178
	v_exp_f32_e32 v194, v181
	v_mfma_f32_16x16x32_bf16 v[106:109], v[186:189], v[34:37], v[0:3]
	s_waitcnt lgkmcnt(3)
	v_mfma_f32_16x16x32_bf16 v[114:117], v[244:247], v[34:37], v[0:3]
	s_nop 1
	v_exp_f32_e32 v190, v102
	v_exp_f32_e32 v200, v103
	v_exp_f32_e32 v204, v105
	s_waitcnt lgkmcnt(1)
	v_mfma_f32_16x16x32_bf16 v[34:37], v[216:219], v[34:37], v[0:3]
	v_cvt_pk_bf16_f32 v102, v140, v150
	v_cvt_pk_bf16_f32 v103, v156, v162
	v_mfma_f32_16x16x32_bf16 v[142:145], v[186:189], v[8:11], v[0:3]
	v_mfma_f32_16x16x32_bf16 v[182:185], v[186:189], v[26:29], v[0:3]
	v_mfma_f32_16x16x32_bf16 v[106:109], v[196:199], v[30:33], v[106:109]
	v_mfma_f32_16x16x32_bf16 v[212:215], v[248:251], v[30:33], v[114:117]
	v_cvt_pk_bf16_f32 v114, v190, v200
	s_nop 6
	v_exp_f32_e32 v186, v106
	v_exp_f32_e32 v192, v107
	s_waitcnt lgkmcnt(0)
	v_mfma_f32_16x16x32_bf16 v[30:33], v[220:223], v[30:33], v[34:37]
	v_exp_f32_e32 v202, v109
	v_exp_f32_e32 v191, v212
	v_exp_f32_e32 v201, v213
	v_mfma_f32_16x16x32_bf16 v[34:37], v[244:247], v[26:29], v[0:3]
	v_exp_f32_e32 v205, v215
	s_nop 2
	v_exp_f32_e32 v187, v30
	v_exp_f32_e32 v193, v31
	v_mfma_f32_16x16x32_bf16 v[26:29], v[216:219], v[26:29], v[0:3]
	v_exp_f32_e32 v203, v33
	v_cvt_pk_bf16_f32 v106, v154, v166
	v_cvt_pk_bf16_f32 v107, v168, v176
	v_mfma_f32_16x16x32_bf16 v[142:145], v[196:199], v[4:7], v[142:145]
	v_cvt_pk_bf16_f32 v109, v164, v172
	v_cvt_pk_bf16_f32 v116, v186, v192
	v_mfma_f32_16x16x32_bf16 v[110:113], v[196:199], v[22:25], v[182:185]
	v_exp_f32_e32 v197, v32
	v_exp_f32_e32 v198, v104
	v_exp_f32_e32 v199, v214
	v_mfma_f32_16x16x32_bf16 v[30:33], v[248:251], v[22:25], v[34:37]
	v_exp_f32_e32 v182, v179
	s_nop 2
	v_exp_f32_e32 v170, v110
	v_exp_f32_e32 v178, v111
	v_mfma_f32_16x16x32_bf16 v[22:25], v[220:223], v[22:25], v[26:29]
	v_exp_f32_e32 v184, v180
	v_exp_f32_e32 v180, v112
	v_exp_f32_e32 v188, v113
	v_exp_f32_e32 v175, v30
	v_mfma_f32_16x16x32_bf16 v[26:29], v[244:247], v[18:21], v[0:3]
	s_nop 2
	v_exp_f32_e32 v171, v22
	v_exp_f32_e32 v183, v31
	v_exp_f32_e32 v179, v23
	v_exp_f32_e32 v185, v32
	v_exp_f32_e32 v181, v24
	v_exp_f32_e32 v195, v33
	v_exp_f32_e32 v189, v25
	v_mfma_f32_16x16x32_bf16 v[18:21], v[216:219], v[18:21], v[0:3]
	v_add_f32_e64 v22, v174, v182
	v_add_f32_e64 v23, v175, v183
	v_add_f32_e32 v24, v184, v194
	v_add_f32_e32 v25, v185, v195
	v_cvt_pk_bf16_f32 v112, v170, v178
	v_mfma_f32_16x16x32_bf16 v[28:31], v[248:251], v[12:15], v[26:29]
	v_add_f32_e64 v22, v22, v24
	v_add_f32_e64 v23, v23, v25
	v_exp_f32_e32 v196, v108
	v_add_f32_e32 v34, v190, v200
	v_add_f32_e32 v35, v191, v201
	v_mfma_f32_16x16x32_bf16 v[12:15], v[220:223], v[12:15], v[18:21]
	v_add_f32_e64 v36, v198, v204
	v_add_f32_e64 v37, v199, v205
	v_add_f32_e32 v206, v196, v202
	v_add_f32_e32 v207, v197, v203
	v_add_f32_e32 v34, v34, v36
	v_add_f32_e32 v35, v35, v37
	v_add_f32_e32 v18, v170, v178
	v_add_f32_e32 v19, v171, v179
	v_add_f32_e32 v20, v180, v188
	v_add_f32_e32 v21, v181, v189
	v_add_u32_e32 v170, 0x6800, v238
	v_add_f32_e32 v24, v18, v20
	v_add_f32_e32 v25, v19, v21
	v_mfma_f32_16x16x32_bf16 v[18:21], v[244:247], v[8:11], v[0:3]
	v_add_f32_e64 v26, v22, v24
	v_add_f32_e64 v27, v23, v25
	ds_read2_b64 v[22:25], v170 offset0:128 offset1:132
	v_add_f32_e32 v36, v186, v192
	v_add_f32_e32 v37, v187, v193
	v_mfma_f32_16x16x32_bf16 v[8:11], v[216:219], v[8:11], v[0:3]
	v_exp_f32_e32 v138, v142
	v_exp_f32_e32 v142, v143
	v_exp_f32_e32 v144, v144
	v_mfma_f32_16x16x32_bf16 v[18:21], v[248:251], v[4:7], v[18:21]
	v_exp_f32_e32 v158, v145
	v_cvt_pk_bf16_f32 v104, v138, v142
	v_cvt_pk_bf16_f32 v105, v144, v158
	v_mfma_f32_16x16x32_bf16 v[4:7], v[220:223], v[4:7], v[8:11]
	v_add_f32_e64 v36, v36, v206
	v_add_f32_e64 v37, v37, v207
	v_exp_f32_e32 v169, v30
	v_exp_f32_e32 v177, v31
	s_waitcnt lgkmcnt(0)
	v_mfma_f32_16x16x32_bf16 v[30:33], v[22:25], v[102:105], v[98:101]
	v_exp_f32_e32 v141, v18
	v_add_u32_e32 v18, 0x7800, v238
	v_cvt_pk_bf16_f32 v108, v152, v160
	v_add_f32_e32 v206, v34, v36
	v_add_f32_e32 v207, v35, v37
	v_add_u32_e32 v98, 0x7000, v238
	v_mfma_f32_16x16x32_bf16 v[34:37], v[22:25], v[106:109], v[94:97]
	v_exp_f32_e32 v139, v4
	v_exp_f32_e32 v143, v5
	v_exp_f32_e32 v145, v6
	ds_read2_b64 v[94:97], v98 offset0:160 offset1:164
	v_exp_f32_e32 v159, v7
	ds_read2_b64 v[4:7], v18 offset0:192 offset1:196
	v_exp_f32_e32 v155, v28
	v_exp_f32_e32 v167, v29
	v_exp_f32_e32 v153, v12
	v_exp_f32_e32 v161, v13
	v_exp_f32_e32 v165, v14
	v_exp_f32_e32 v173, v15
	v_add_f32_e32 v8, v154, v166
	v_add_f32_e32 v9, v155, v167
	v_add_f32_e32 v10, v168, v176
	v_add_f32_e32 v11, v169, v177
	v_cvt_pk_bf16_f32 v110, v174, v182
	v_add_f32_e32 v12, v164, v172
	v_add_f32_e32 v13, v165, v173
	v_add_f32_e32 v8, v8, v10
	v_add_f32_e32 v9, v9, v11
	v_add_f32_e32 v10, v152, v160
	v_add_f32_e32 v11, v153, v161
	v_cvt_pk_bf16_f32 v111, v184, v194
	v_cvt_pk_bf16_f32 v113, v180, v188
	v_cvt_pk_bf16_f32 v115, v198, v204
	v_cvt_pk_bf16_f32 v117, v196, v202
	s_waitcnt lgkmcnt(1)
	v_mfma_f32_16x16x32_bf16 v[82:85], v[94:97], v[102:105], v[82:85]
	v_add_f32_e64 v10, v10, v12
	v_add_f32_e64 v11, v11, v13
	v_exp_f32_e32 v151, v19
	v_add_f32_e32 v28, v8, v10
	v_add_f32_e32 v29, v9, v11
	v_mfma_f32_16x16x32_bf16 v[90:93], v[22:25], v[110:113], v[90:93]
	v_add_u32_e32 v19, 0x8000, v238
	v_exp_f32_e32 v157, v20
	v_exp_f32_e32 v163, v21
	v_mfma_f32_16x16x32_bf16 v[86:89], v[22:25], v[114:117], v[86:89]
	v_add_f32_e64 v220, v140, v150
	v_add_f32_e64 v221, v141, v151
	v_add_f32_e32 v28, v148, v28
	v_add_f32_e32 v222, v156, v162
	v_add_f32_e32 v223, v157, v163
	v_mfma_f32_16x16x32_bf16 v[8:11], v[94:97], v[106:109], v[78:81]
	v_cvt_pk_bf16_f32 v148, v175, v183
	v_cvt_pk_bf16_f32 v150, v171, v179
	v_cvt_pk_bf16_f32 v152, v191, v201
	v_mfma_f32_16x16x32_bf16 v[12:15], v[94:97], v[110:113], v[74:77]
	v_cvt_pk_bf16_f32 v154, v187, v193
	v_mfma_f32_16x16x32_bf16 v[22:25], v[94:97], v[114:117], v[70:73]
	s_nop 2
	ds_read2_b64 v[70:73], v19 offset0:224 offset1:228
	ds_read2_b64 v[74:77], v170 offset0:136 offset1:140
	ds_read2_b64 v[78:81], v98 offset0:168 offset1:172
	ds_read2_b64 v[98:101], v18 offset0:200 offset1:204
	ds_read2_b64 v[18:21], v19 offset0:232 offset1:236
	s_waitcnt lgkmcnt(0)
	v_mfma_f32_16x16x32_bf16 v[94:97], v[4:7], v[102:105], v[66:69]
	s_barrier
	s_nop 1
	v_lshl_add_u64 v[66:67], v[128:129], 0, s[52:53]
	v_lshl_add_u64 v[68:69], v[66:67], 0, v[136:137]
	global_load_dwordx2 v[244:245], v[68:69], off
	v_mfma_f32_16x16x32_bf16 v[212:215], v[4:7], v[106:109], v[62:65]
	v_cvt_pk_bf16_f32 v136, v141, v151
	v_cvt_pk_bf16_f32 v137, v157, v163
	v_cvt_pk_bf16_f32 v151, v181, v189
	v_mfma_f32_16x16x32_bf16 v[216:219], v[4:7], v[110:113], v[58:61]
	v_mfma_f32_16x16x32_bf16 v[54:57], v[4:7], v[114:117], v[54:57]
	v_add_f32_e64 v6, v138, v142
	v_add_f32_e64 v7, v139, v143
	v_add_f32_e32 v58, v144, v158
	v_add_f32_e32 v59, v145, v159
	v_add_f32_e32 v4, v220, v222
	v_add_f32_e32 v5, v221, v223
	v_add_f32_e32 v6, v6, v58
	v_add_f32_e32 v7, v7, v59
	v_mfma_f32_16x16x32_bf16 v[106:109], v[70:73], v[106:109], v[46:49]
	v_add_f32_e64 v4, v4, v6
	v_add_f32_e64 v5, v5, v7
	v_cvt_pk_bf16_f32 v138, v139, v143
	v_cvt_pk_bf16_f32 v139, v145, v159
	v_mfma_f32_16x16x32_bf16 v[114:117], v[70:73], v[114:117], v[38:41]
	v_add_f32_e32 v4, v149, v4
	v_add_f32_e32 v58, v4, v5
	v_cvt_pk_bf16_f32 v38, v155, v167
	v_cvt_pk_bf16_f32 v39, v169, v177
	v_cvt_pk_bf16_f32 v40, v153, v161
	v_mfma_f32_16x16x32_bf16 v[140:143], v[74:77], v[136:139], v[30:33]
	v_cvt_pk_bf16_f32 v41, v165, v173
	v_cvt_pk_bf16_f32 v149, v185, v195
	v_cvt_pk_bf16_f32 v153, v199, v205
	v_cvt_pk_bf16_f32 v155, v197, v203
	v_mfma_f32_16x16x32_bf16 v[110:113], v[70:73], v[110:113], v[42:45]
	v_mfma_f32_16x16x32_bf16 v[46:49], v[74:77], v[38:41], v[34:37]
	v_mfma_f32_16x16x32_bf16 v[30:33], v[74:77], v[148:151], v[90:93]
	s_nop 1
	v_and_b32_e32 v35, 64, v209
	v_xor_b32_e32 v34, 16, v209
	v_add_u32_e32 v42, 64, v35
	v_mfma_f32_16x16x32_bf16 v[4:7], v[74:77], v[152:155], v[86:89]
	global_load_dwordx2 v[76:77], v[68:69], off offset:32
	v_cmp_lt_i32_e32 vcc, v34, v42
	v_mfma_f32_16x16x32_bf16 v[102:105], v[70:73], v[102:105], v[50:53]
	s_nop 0
	v_cndmask_b32_e32 v34, v209, v34, vcc
	v_lshlrev_b32_e32 v72, 2, v34
	v_add_f32_e32 v88, v28, v29
	v_mfma_f32_16x16x32_bf16 v[50:53], v[78:81], v[38:41], v[8:11]
	s_nop 2
	ds_bpermute_b32 v9, v72, v58
	v_xor_b32_e32 v8, 32, v209
	v_cmp_lt_i32_e32 vcc, v8, v42
	v_mfma_f32_16x16x32_bf16 v[62:65], v[78:81], v[136:139], v[82:85]
	v_add_f32_e32 v10, v147, v26
	v_cndmask_b32_e32 v8, v209, v8, vcc
	v_lshlrev_b32_e32 v73, 2, v8
	v_mfma_f32_16x16x32_bf16 v[34:37], v[78:81], v[148:151], v[12:15]
	s_waitcnt lgkmcnt(0)
	v_add_f32_e32 v8, v58, v9
	ds_bpermute_b32 v9, v73, v8
	v_add_f32_e32 v75, v10, v27
	v_mfma_f32_16x16x32_bf16 v[12:15], v[78:81], v[152:155], v[22:25]
	global_load_dwordx2 v[78:79], v[68:69], off offset:64
	global_load_dwordx2 v[80:81], v[68:69], off offset:96
	s_waitcnt lgkmcnt(0)
	v_add_f32_e32 v70, v8, v9
	v_div_scale_f32 v22, s[4:5], v70, v70, 1.0
	v_rcp_f32_e32 v23, v22
	v_add_f32_e32 v8, v146, v206
	v_add_f32_e32 v74, v8, v207
	v_div_scale_f32 v24, vcc, 1.0, v70, 1.0
	v_fma_f32 v8, -v22, v23, 1.0
	v_fmac_f32_e32 v23, v8, v23
	v_mul_f32_e32 v25, v24, v23
	v_fma_f32 v71, -v22, v25, v24
	v_fmac_f32_e32 v25, v71, v23
	v_fma_f32 v22, -v22, v25, v24
	v_div_fmas_f32 v71, v22, v23, v25
	v_div_fixup_f32 v70, v71, v70, 1.0
	s_waitcnt vmcnt(3)
	v_lshlrev_b32_e32 v71, 16, v244
	v_mul_f32_e32 v82, 0xbfb8aa3b, v71
	v_exp_f32_e32 v82, v82
	v_and_b32_e32 v84, 0xffff0000, v244
	v_lshlrev_b32_e32 v86, 16, v245
	v_and_b32_e32 v89, 0xffff0000, v245
	v_add_f32_e32 v82, 1.0, v82
	v_rcp_f32_e32 v83, v82
	v_mul_f32_e32 v82, 0xbfb8aa3b, v84
	v_exp_f32_e32 v85, v82
	v_mov_b32_e32 v82, v140
	v_pk_mul_f32 v[82:83], v[82:83], v[70:71]
	v_mfma_f32_16x16x32_bf16 v[58:61], v[98:101], v[136:139], v[94:97]
	v_add_f32_e32 v71, 1.0, v85
	v_mul_f32_e32 v87, v82, v83
	v_rcp_f32_e32 v83, v71
	v_mov_b32_e32 v71, v84
	v_mul_f32_e32 v84, 0xbfb8aa3b, v86
	v_exp_f32_e32 v84, v84
	v_mov_b32_e32 v82, v141
	v_pk_mul_f32 v[82:83], v[82:83], v[70:71]
	v_mfma_f32_16x16x32_bf16 v[8:11], v[98:101], v[152:155], v[54:57]
	v_mul_f32_e32 v71, v82, v83
	v_cvt_pk_bf16_f32 v82, v87, v71
	v_add_f32_e32 v71, 1.0, v84
	v_rcp_f32_e32 v85, v71
	v_mul_f32_e32 v71, 0xbfb8aa3b, v89
	v_exp_f32_e32 v83, v71
	v_mov_b32_e32 v84, v142
	v_mov_b32_e32 v71, v86
	v_pk_mul_f32 v[84:85], v[84:85], v[70:71]
	v_add_f32_e32 v71, 1.0, v83
	v_rcp_f32_e32 v87, v71
	v_mov_b32_e32 v86, v143
	v_mov_b32_e32 v71, v89
	v_mul_f32_e32 v83, v84, v85
	v_pk_mul_f32 v[84:85], v[86:87], v[70:71]
	v_mfma_f32_16x16x32_bf16 v[54:57], v[18:21], v[136:139], v[102:105]
	v_mul_f32_e32 v71, v84, v85
	v_cvt_pk_bf16_f32 v83, v83, v71
	s_waitcnt vmcnt(2)
	v_lshlrev_b32_e32 v71, 16, v76
	global_store_dwordx2 v[68:69], v[82:83], off
	v_mul_f32_e32 v82, 0xbfb8aa3b, v71
	v_exp_f32_e32 v82, v82
	v_and_b32_e32 v83, 0xffff0000, v76
	v_lshlrev_b32_e32 v84, 16, v77
	v_and_b32_e32 v85, 0xffff0000, v77
	v_add_f32_e32 v76, 1.0, v82
	v_rcp_f32_e32 v77, v76
	v_mul_f32_e32 v76, 0xbfb8aa3b, v83
	v_exp_f32_e32 v82, v76
	v_mov_b32_e32 v76, v62
	v_pk_mul_f32 v[76:77], v[76:77], v[70:71]
	v_mov_b32_e32 v71, v83
	v_add_f32_e32 v62, 1.0, v82
	v_mul_f32_e32 v86, v76, v77
	v_rcp_f32_e32 v77, v62
	v_mul_f32_e32 v62, 0xbfb8aa3b, v84
	v_exp_f32_e32 v82, v62
	v_mov_b32_e32 v76, v63
	v_pk_mul_f32 v[62:63], v[76:77], v[70:71]
	v_mov_b32_e32 v76, v64
	v_mul_f32_e32 v62, v62, v63
	v_add_f32_e32 v63, 1.0, v82
	v_rcp_f32_e32 v77, v63
	v_mul_f32_e32 v63, 0xbfb8aa3b, v85
	v_exp_f32_e32 v63, v63
	v_mov_b32_e32 v71, v84
	v_pk_mul_f32 v[76:77], v[76:77], v[70:71]
	v_mov_b32_e32 v82, v65
	v_add_f32_e32 v63, 1.0, v63
	v_rcp_f32_e32 v83, v63
	v_mov_b32_e32 v71, v85
	v_cvt_pk_bf16_f32 v62, v86, v62
	v_mul_f32_e32 v63, v76, v77
	v_pk_mul_f32 v[64:65], v[82:83], v[70:71]
	s_waitcnt vmcnt(2)
	v_lshlrev_b32_e32 v71, 16, v78
	v_mul_f32_e32 v64, v64, v65
	v_cvt_pk_bf16_f32 v63, v63, v64
	global_store_dwordx2 v[68:69], v[62:63], off offset:32
	v_mul_f32_e32 v62, 0xbfb8aa3b, v71
	v_exp_f32_e32 v62, v62
	v_and_b32_e32 v64, 0xffff0000, v78
	v_lshlrev_b32_e32 v78, 16, v79
	v_mul_f32_e32 v77, 0xbfb8aa3b, v78
	v_add_f32_e32 v62, 1.0, v62
	v_rcp_f32_e32 v63, v62
	v_mul_f32_e32 v62, 0xbfb8aa3b, v64
	v_exp_f32_e32 v65, v62
	v_mov_b32_e32 v62, v58
	v_pk_mul_f32 v[62:63], v[62:63], v[70:71]
	v_mov_b32_e32 v71, v64
	v_add_f32_e32 v58, 1.0, v65
	v_mul_f32_e32 v76, v62, v63
	v_rcp_f32_e32 v63, v58
	v_mov_b32_e32 v62, v59
	v_lshl_add_u64 v[58:59], v[66:67], 0, v[134:135]
	global_load_dwordx2 v[64:65], v[58:59], off
	v_exp_f32_e32 v77, v77
	v_pk_mul_f32 v[62:63], v[62:63], v[70:71]
	v_and_b32_e32 v82, 0xffff0000, v79
	v_mul_f32_e32 v62, v62, v63
	v_add_f32_e32 v63, 1.0, v77
	v_rcp_f32_e32 v77, v63
	v_mul_f32_e32 v63, 0xbfb8aa3b, v82
	v_exp_f32_e32 v63, v63
	v_cvt_pk_bf16_f32 v62, v76, v62
	v_mov_b32_e32 v76, v60
	v_mov_b32_e32 v71, v78
	v_add_f32_e32 v60, 1.0, v63
	v_rcp_f32_e32 v79, v60
	v_pk_mul_f32 v[76:77], v[76:77], v[70:71]
	v_mov_b32_e32 v78, v61
	v_mov_b32_e32 v71, v82
	v_pk_mul_f32 v[60:61], v[78:79], v[70:71]
	v_mul_f32_e32 v63, v76, v77
	v_mul_f32_e32 v60, v60, v61
	s_waitcnt vmcnt(3)
	v_lshlrev_b32_e32 v71, 16, v80
	v_cvt_pk_bf16_f32 v63, v63, v60
	v_mul_f32_e32 v60, 0xbfb8aa3b, v71
	v_exp_f32_e32 v60, v60
	global_store_dwordx2 v[68:69], v[62:63], off offset:64
	v_and_b32_e32 v62, 0xffff0000, v80
	v_lshlrev_b32_e32 v76, 16, v81
	v_add_f32_e32 v60, 1.0, v60
	v_rcp_f32_e32 v61, v60
	v_mul_f32_e32 v60, 0xbfb8aa3b, v62
	v_exp_f32_e32 v63, v60
	v_mov_b32_e32 v60, v54
	v_pk_mul_f32 v[60:61], v[60:61], v[70:71]
	v_mov_b32_e32 v71, v62
	v_add_f32_e32 v54, 1.0, v63
	global_load_dwordx2 v[62:63], v[58:59], off offset:32
	v_mul_f32_e32 v77, v60, v61
	v_rcp_f32_e32 v61, v54
	v_mul_f32_e32 v54, 0xbfb8aa3b, v76
	v_exp_f32_e32 v79, v54
	v_mov_b32_e32 v60, v55
	v_pk_mul_f32 v[54:55], v[60:61], v[70:71]
	v_and_b32_e32 v78, 0xffff0000, v81
	v_mul_f32_e32 v54, v54, v55
	v_add_f32_e32 v55, 1.0, v79
	v_rcp_f32_e32 v61, v55
	v_mul_f32_e32 v55, 0xbfb8aa3b, v78
	v_mov_b32_e32 v60, v56
	v_exp_f32_e32 v55, v55
	ds_bpermute_b32 v56, v72, v88
	v_cvt_pk_bf16_f32 v54, v77, v54
	v_mov_b32_e32 v71, v76
	v_add_f32_e32 v55, 1.0, v55
	v_rcp_f32_e32 v77, v55
	s_waitcnt lgkmcnt(0)
	v_add_f32_e32 v55, v88, v56
	ds_bpermute_b32 v79, v73, v55
	v_pk_mul_f32 v[60:61], v[60:61], v[70:71]
	v_mov_b32_e32 v76, v57
	v_mul_f32_e32 v60, v60, v61
	v_mov_b32_e32 v71, v78
	s_waitcnt lgkmcnt(0)
	v_add_f32_e32 v61, v55, v79
	v_pk_mul_f32 v[56:57], v[76:77], v[70:71]
	v_div_scale_f32 v70, s[4:5], v61, v61, 1.0
	v_rcp_f32_e32 v71, v70
	v_mul_f32_e32 v55, v56, v57
	v_cvt_pk_bf16_f32 v55, v60, v55
	global_store_dwordx2 v[68:69], v[54:55], off offset:96
	v_fma_f32 v54, -v70, v71, 1.0
	v_fmac_f32_e32 v71, v54, v71
	v_div_scale_f32 v54, vcc, 1.0, v61, 1.0
	v_mul_f32_e32 v55, v54, v71
	v_fma_f32 v56, -v70, v55, v54
	v_fmac_f32_e32 v55, v56, v71
	global_load_dwordx2 v[56:57], v[58:59], off offset:64
	v_fma_f32 v54, -v70, v55, v54
	v_div_fmas_f32 v54, v54, v71, v55
	v_div_fixup_f32 v54, v54, v61, 1.0
	global_load_dwordx2 v[60:61], v[58:59], off offset:96
	s_waitcnt vmcnt(5)
	v_lshlrev_b32_e32 v55, 16, v64
	v_mul_f32_e32 v68, 0xbfb8aa3b, v55
	v_exp_f32_e32 v68, v68
	v_and_b32_e32 v69, 0xffff0000, v64
	v_lshlrev_b32_e32 v70, 16, v65
	v_and_b32_e32 v71, 0xffff0000, v65
	v_add_f32_e32 v64, 1.0, v68
	v_rcp_f32_e32 v65, v64
	v_mul_f32_e32 v64, 0xbfb8aa3b, v69
	v_exp_f32_e32 v68, v64
	v_mov_b32_e32 v64, v46
	v_pk_mul_f32 v[64:65], v[64:65], v[54:55]
	v_mov_b32_e32 v55, v69
	v_add_f32_e32 v46, 1.0, v68
	v_mul_f32_e32 v76, v64, v65
	v_rcp_f32_e32 v65, v46
	v_mul_f32_e32 v46, 0xbfb8aa3b, v70
	v_exp_f32_e32 v68, v46
	v_mov_b32_e32 v64, v47
	v_pk_mul_f32 v[46:47], v[64:65], v[54:55]
	v_mov_b32_e32 v64, v48
	v_mul_f32_e32 v46, v46, v47
	v_add_f32_e32 v47, 1.0, v68
	v_rcp_f32_e32 v65, v47
	v_mul_f32_e32 v47, 0xbfb8aa3b, v71
	v_exp_f32_e32 v47, v47
	v_mov_b32_e32 v55, v70
	v_pk_mul_f32 v[64:65], v[64:65], v[54:55]
	v_mov_b32_e32 v68, v49
	v_add_f32_e32 v47, 1.0, v47
	v_rcp_f32_e32 v69, v47
	v_mov_b32_e32 v55, v71
	v_cvt_pk_bf16_f32 v46, v76, v46
	v_mul_f32_e32 v47, v64, v65
	v_pk_mul_f32 v[48:49], v[68:69], v[54:55]
	s_waitcnt vmcnt(3)
	v_lshlrev_b32_e32 v55, 16, v62
	v_mul_f32_e32 v48, v48, v49
	v_cvt_pk_bf16_f32 v47, v47, v48
	global_store_dwordx2 v[58:59], v[46:47], off
	v_mul_f32_e32 v46, 0xbfb8aa3b, v55
	v_exp_f32_e32 v46, v46
	v_and_b32_e32 v48, 0xffff0000, v62
	v_lshlrev_b32_e32 v62, 16, v63
	v_and_b32_e32 v63, 0xffff0000, v63
	v_add_f32_e32 v46, 1.0, v46
	v_rcp_f32_e32 v47, v46
	v_mul_f32_e32 v46, 0xbfb8aa3b, v48
	v_exp_f32_e32 v49, v46
	v_mov_b32_e32 v46, v50
	v_pk_mul_f32 v[46:47], v[46:47], v[54:55]
	v_mov_b32_e32 v55, v48
	v_mul_f32_e32 v50, v46, v47
	v_add_f32_e32 v46, 1.0, v49
	v_rcp_f32_e32 v47, v46
	v_mul_f32_e32 v48, 0xbfb8aa3b, v62
	v_exp_f32_e32 v48, v48
	v_mov_b32_e32 v46, v51
	v_pk_mul_f32 v[46:47], v[46:47], v[54:55]
	v_mov_b32_e32 v55, v62
	v_mul_f32_e32 v46, v46, v47
	v_add_f32_e32 v47, 1.0, v48
	v_rcp_f32_e32 v49, v47
	v_mul_f32_e32 v47, 0xbfb8aa3b, v63
	v_exp_f32_e32 v47, v47
	v_mov_b32_e32 v48, v52
	v_cvt_pk_bf16_f32 v46, v50, v46
	v_pk_mul_f32 v[48:49], v[48:49], v[54:55]
	v_add_f32_e32 v47, 1.0, v47
	v_rcp_f32_e32 v51, v47
	v_mov_b32_e32 v50, v53
	v_mov_b32_e32 v55, v63
	v_mul_f32_e32 v47, v48, v49
	v_pk_mul_f32 v[48:49], v[50:51], v[54:55]
	v_mfma_f32_16x16x32_bf16 v[42:45], v[98:101], v[38:41], v[212:215]
	v_mul_f32_e32 v48, v48, v49
	s_waitcnt vmcnt(2)
	v_lshlrev_b32_e32 v55, 16, v56
	v_cvt_pk_bf16_f32 v47, v47, v48
	global_store_dwordx2 v[58:59], v[46:47], off offset:32
	v_mul_f32_e32 v46, 0xbfb8aa3b, v55
	v_exp_f32_e32 v46, v46
	v_and_b32_e32 v48, 0xffff0000, v56
	v_lshlrev_b32_e32 v52, 16, v57
	v_mul_f32_e32 v51, 0xbfb8aa3b, v52
	v_add_f32_e32 v46, 1.0, v46
	v_rcp_f32_e32 v47, v46
	v_mul_f32_e32 v46, 0xbfb8aa3b, v48
	v_exp_f32_e32 v49, v46
	v_mov_b32_e32 v46, v42
	v_pk_mul_f32 v[46:47], v[46:47], v[54:55]
	v_mov_b32_e32 v55, v48
	v_add_f32_e32 v42, 1.0, v49
	v_mul_f32_e32 v50, v46, v47
	v_rcp_f32_e32 v47, v42
	v_mov_b32_e32 v46, v43
	v_lshl_add_u64 v[42:43], v[66:67], 0, v[132:133]
	global_load_dwordx2 v[48:49], v[42:43], off
	v_exp_f32_e32 v51, v51
	v_pk_mul_f32 v[46:47], v[46:47], v[54:55]
	v_and_b32_e32 v56, 0xffff0000, v57
	v_mul_f32_e32 v46, v46, v47
	v_add_f32_e32 v47, 1.0, v51
	v_rcp_f32_e32 v51, v47
	v_mul_f32_e32 v47, 0xbfb8aa3b, v56
	v_exp_f32_e32 v47, v47
	v_cvt_pk_bf16_f32 v46, v50, v46
	v_mov_b32_e32 v50, v44
	v_mov_b32_e32 v55, v52
	v_add_f32_e32 v44, 1.0, v47
	v_rcp_f32_e32 v53, v44
	v_pk_mul_f32 v[50:51], v[50:51], v[54:55]
	v_mov_b32_e32 v52, v45
	v_mov_b32_e32 v55, v56
	v_pk_mul_f32 v[44:45], v[52:53], v[54:55]
	v_mul_f32_e32 v47, v50, v51
	v_mul_f32_e32 v44, v44, v45
	s_waitcnt vmcnt(3)
	v_lshlrev_b32_e32 v55, 16, v60
	v_cvt_pk_bf16_f32 v47, v47, v44
	v_mul_f32_e32 v44, 0xbfb8aa3b, v55
	v_exp_f32_e32 v44, v44
	global_store_dwordx2 v[58:59], v[46:47], off offset:64
	v_and_b32_e32 v46, 0xffff0000, v60
	v_mfma_f32_16x16x32_bf16 v[38:41], v[18:21], v[38:41], v[106:109]
	v_add_f32_e32 v44, 1.0, v44
	v_rcp_f32_e32 v45, v44
	v_mul_f32_e32 v44, 0xbfb8aa3b, v46
	v_exp_f32_e32 v47, v44
	v_lshlrev_b32_e32 v50, 16, v61
	s_nop 2
	v_mov_b32_e32 v44, v38
	v_pk_mul_f32 v[44:45], v[44:45], v[54:55]
	v_add_f32_e32 v38, 1.0, v47
	v_mov_b32_e32 v55, v46
	global_load_dwordx2 v[46:47], v[42:43], off offset:32
	v_mul_f32_e32 v51, v44, v45
	v_rcp_f32_e32 v45, v38
	v_mul_f32_e32 v38, 0xbfb8aa3b, v50
	v_exp_f32_e32 v53, v38
	v_mov_b32_e32 v44, v39
	v_pk_mul_f32 v[38:39], v[44:45], v[54:55]
	v_and_b32_e32 v52, 0xffff0000, v61
	v_mul_f32_e32 v38, v38, v39
	v_add_f32_e32 v39, 1.0, v53
	v_rcp_f32_e32 v45, v39
	v_mul_f32_e32 v39, 0xbfb8aa3b, v52
	v_mov_b32_e32 v44, v40
	v_exp_f32_e32 v39, v39
	ds_bpermute_b32 v40, v72, v75
	v_cvt_pk_bf16_f32 v38, v51, v38
	v_mov_b32_e32 v55, v50
	v_add_f32_e32 v39, 1.0, v39
	v_rcp_f32_e32 v51, v39
	s_waitcnt lgkmcnt(0)
	v_add_f32_e32 v39, v75, v40
	ds_bpermute_b32 v53, v73, v39
	v_pk_mul_f32 v[44:45], v[44:45], v[54:55]
	v_mov_b32_e32 v50, v41
	v_mul_f32_e32 v44, v44, v45
	v_mov_b32_e32 v55, v52
	s_waitcnt lgkmcnt(0)
	v_add_f32_e32 v45, v39, v53
	v_pk_mul_f32 v[40:41], v[50:51], v[54:55]
	v_div_scale_f32 v50, s[4:5], v45, v45, 1.0
	v_rcp_f32_e32 v51, v50
	v_mul_f32_e32 v39, v40, v41
	v_cvt_pk_bf16_f32 v39, v44, v39
	global_store_dwordx2 v[58:59], v[38:39], off offset:96
	v_fma_f32 v38, -v50, v51, 1.0
	v_fmac_f32_e32 v51, v38, v51
	v_div_scale_f32 v38, vcc, 1.0, v45, 1.0
	v_mul_f32_e32 v39, v38, v51
	v_fma_f32 v40, -v50, v39, v38
	v_fmac_f32_e32 v39, v40, v51
	global_load_dwordx2 v[40:41], v[42:43], off offset:64
	v_fma_f32 v38, -v50, v39, v38
	v_div_fmas_f32 v38, v38, v51, v39
	v_div_fixup_f32 v38, v38, v45, 1.0
	global_load_dwordx2 v[44:45], v[42:43], off offset:96
	s_waitcnt vmcnt(5)
	v_lshlrev_b32_e32 v39, 16, v48
	v_mul_f32_e32 v50, 0xbfb8aa3b, v39
	v_exp_f32_e32 v50, v50
	v_and_b32_e32 v51, 0xffff0000, v48
	v_lshlrev_b32_e32 v52, 16, v49
	v_and_b32_e32 v53, 0xffff0000, v49
	v_add_f32_e32 v48, 1.0, v50
	v_rcp_f32_e32 v49, v48
	v_mul_f32_e32 v48, 0xbfb8aa3b, v51
	v_exp_f32_e32 v50, v48
	v_mov_b32_e32 v48, v30
	v_pk_mul_f32 v[48:49], v[48:49], v[38:39]
	v_mov_b32_e32 v39, v51
	v_add_f32_e32 v30, 1.0, v50
	v_mul_f32_e32 v54, v48, v49
	v_rcp_f32_e32 v49, v30
	v_mul_f32_e32 v30, 0xbfb8aa3b, v52
	v_exp_f32_e32 v50, v30
	v_mov_b32_e32 v48, v31
	v_pk_mul_f32 v[30:31], v[48:49], v[38:39]
	v_mov_b32_e32 v48, v32
	v_mul_f32_e32 v30, v30, v31
	v_add_f32_e32 v31, 1.0, v50
	v_rcp_f32_e32 v49, v31
	v_mul_f32_e32 v31, 0xbfb8aa3b, v53
	v_exp_f32_e32 v31, v31
	v_mov_b32_e32 v39, v52
	v_pk_mul_f32 v[48:49], v[48:49], v[38:39]
	v_mov_b32_e32 v50, v33
	v_add_f32_e32 v31, 1.0, v31
	v_rcp_f32_e32 v51, v31
	v_mov_b32_e32 v39, v53
	v_cvt_pk_bf16_f32 v30, v54, v30
	v_mul_f32_e32 v31, v48, v49
	v_pk_mul_f32 v[32:33], v[50:51], v[38:39]
	s_waitcnt vmcnt(3)
	v_lshlrev_b32_e32 v39, 16, v46
	v_mul_f32_e32 v32, v32, v33
	v_cvt_pk_bf16_f32 v31, v31, v32
	global_store_dwordx2 v[42:43], v[30:31], off
	v_mul_f32_e32 v30, 0xbfb8aa3b, v39
	v_exp_f32_e32 v30, v30
	v_and_b32_e32 v32, 0xffff0000, v46
	v_lshlrev_b32_e32 v46, 16, v47
	v_and_b32_e32 v47, 0xffff0000, v47
	v_add_f32_e32 v30, 1.0, v30
	v_rcp_f32_e32 v31, v30
	v_mul_f32_e32 v30, 0xbfb8aa3b, v32
	v_exp_f32_e32 v33, v30
	v_mov_b32_e32 v30, v34
	v_pk_mul_f32 v[30:31], v[30:31], v[38:39]
	v_mov_b32_e32 v39, v32
	v_mul_f32_e32 v34, v30, v31
	v_add_f32_e32 v30, 1.0, v33
	v_rcp_f32_e32 v31, v30
	v_mul_f32_e32 v32, 0xbfb8aa3b, v46
	v_exp_f32_e32 v32, v32
	v_mov_b32_e32 v30, v35
	v_pk_mul_f32 v[30:31], v[30:31], v[38:39]
	v_mov_b32_e32 v39, v46
	v_mul_f32_e32 v30, v30, v31
	v_add_f32_e32 v31, 1.0, v32
	v_rcp_f32_e32 v33, v31
	v_mul_f32_e32 v31, 0xbfb8aa3b, v47
	v_exp_f32_e32 v31, v31
	v_mov_b32_e32 v32, v36
	v_cvt_pk_bf16_f32 v30, v34, v30
	v_pk_mul_f32 v[32:33], v[32:33], v[38:39]
	v_add_f32_e32 v31, 1.0, v31
	v_rcp_f32_e32 v35, v31
	v_mov_b32_e32 v34, v37
	v_mov_b32_e32 v39, v47
	v_mul_f32_e32 v31, v32, v33
	v_pk_mul_f32 v[32:33], v[34:35], v[38:39]
	v_mfma_f32_16x16x32_bf16 v[26:29], v[98:101], v[148:151], v[216:219]
	v_mul_f32_e32 v32, v32, v33
	s_waitcnt vmcnt(2)
	v_lshlrev_b32_e32 v39, 16, v40
	v_cvt_pk_bf16_f32 v31, v31, v32
	global_store_dwordx2 v[42:43], v[30:31], off offset:32
	v_mul_f32_e32 v30, 0xbfb8aa3b, v39
	v_exp_f32_e32 v30, v30
	v_and_b32_e32 v32, 0xffff0000, v40
	v_lshlrev_b32_e32 v36, 16, v41
	v_mul_f32_e32 v35, 0xbfb8aa3b, v36
	v_add_f32_e32 v30, 1.0, v30
	v_rcp_f32_e32 v31, v30
	v_mul_f32_e32 v30, 0xbfb8aa3b, v32
	v_exp_f32_e32 v33, v30
	v_mov_b32_e32 v30, v26
	v_pk_mul_f32 v[30:31], v[30:31], v[38:39]
	v_mov_b32_e32 v39, v32
	v_add_f32_e32 v26, 1.0, v33
	v_mul_f32_e32 v34, v30, v31
	v_rcp_f32_e32 v31, v26
	v_mov_b32_e32 v30, v27
	v_lshl_add_u64 v[26:27], v[66:67], 0, v[130:131]
	global_load_dwordx2 v[32:33], v[26:27], off
	v_exp_f32_e32 v35, v35
	v_pk_mul_f32 v[30:31], v[30:31], v[38:39]
	v_and_b32_e32 v40, 0xffff0000, v41
	v_mul_f32_e32 v30, v30, v31
	v_add_f32_e32 v31, 1.0, v35
	v_rcp_f32_e32 v35, v31
	v_mul_f32_e32 v31, 0xbfb8aa3b, v40
	v_exp_f32_e32 v31, v31
	v_cvt_pk_bf16_f32 v30, v34, v30
	v_mov_b32_e32 v34, v28
	v_mov_b32_e32 v39, v36
	v_add_f32_e32 v28, 1.0, v31
	v_rcp_f32_e32 v37, v28
	v_pk_mul_f32 v[34:35], v[34:35], v[38:39]
	v_mov_b32_e32 v36, v29
	v_mov_b32_e32 v39, v40
	v_pk_mul_f32 v[28:29], v[36:37], v[38:39]
	v_mul_f32_e32 v31, v34, v35
	v_mul_f32_e32 v28, v28, v29
	s_waitcnt vmcnt(3)
	v_lshlrev_b32_e32 v39, 16, v44
	v_cvt_pk_bf16_f32 v31, v31, v28
	v_mul_f32_e32 v28, 0xbfb8aa3b, v39
	v_exp_f32_e32 v28, v28
	global_store_dwordx2 v[42:43], v[30:31], off offset:64
	v_and_b32_e32 v30, 0xffff0000, v44
	v_mfma_f32_16x16x32_bf16 v[22:25], v[18:21], v[148:151], v[110:113]
	v_add_f32_e32 v28, 1.0, v28
	v_rcp_f32_e32 v29, v28
	v_mul_f32_e32 v28, 0xbfb8aa3b, v30
	v_exp_f32_e32 v31, v28
	v_lshlrev_b32_e32 v34, 16, v45
	s_nop 2
	v_mov_b32_e32 v28, v22
	v_pk_mul_f32 v[28:29], v[28:29], v[38:39]
	v_add_f32_e32 v22, 1.0, v31
	v_mul_f32_e32 v35, v28, v29
	v_rcp_f32_e32 v29, v22
	v_mov_b32_e32 v28, v23
	global_load_dwordx2 v[22:23], v[26:27], off offset:32
	v_mov_b32_e32 v39, v30
	v_mul_f32_e32 v30, 0xbfb8aa3b, v34
	v_exp_f32_e32 v30, v30
	v_pk_mul_f32 v[28:29], v[28:29], v[38:39]
	v_and_b32_e32 v36, 0xffff0000, v45
	v_mul_f32_e32 v28, v28, v29
	v_add_f32_e32 v29, 1.0, v30
	v_rcp_f32_e32 v31, v29
	ds_bpermute_b32 v29, v72, v74
	v_mov_b32_e32 v30, v24
	v_mul_f32_e32 v24, 0xbfb8aa3b, v36
	v_exp_f32_e32 v24, v24
	v_cvt_pk_bf16_f32 v28, v35, v28
	s_waitcnt lgkmcnt(0)
	v_add_f32_e32 v29, v74, v29
	ds_bpermute_b32 v37, v73, v29
	v_add_f32_e32 v24, 1.0, v24
	v_rcp_f32_e32 v35, v24
	v_mov_b32_e32 v39, v34
	v_pk_mul_f32 v[30:31], v[30:31], v[38:39]
	v_mov_b32_e32 v34, v25
	v_mul_f32_e32 v30, v30, v31
	v_mov_b32_e32 v39, v36
	s_waitcnt lgkmcnt(0)
	v_add_f32_e32 v31, v29, v37
	v_pk_mul_f32 v[24:25], v[34:35], v[38:39]
	v_div_scale_f32 v34, s[4:5], v31, v31, 1.0
	v_rcp_f32_e32 v35, v34
	v_mul_f32_e32 v24, v24, v25
	v_cvt_pk_bf16_f32 v29, v30, v24
	global_store_dwordx2 v[42:43], v[28:29], off offset:96
	v_fma_f32 v24, -v34, v35, 1.0
	v_fmac_f32_e32 v35, v24, v35
	v_div_scale_f32 v24, vcc, 1.0, v31, 1.0
	v_mul_f32_e32 v28, v24, v35
	v_fma_f32 v25, -v34, v28, v24
	v_fmac_f32_e32 v28, v25, v35
	v_fma_f32 v29, -v34, v28, v24
	global_load_dwordx2 v[24:25], v[26:27], off offset:64
	v_div_fmas_f32 v28, v29, v35, v28
	v_div_fixup_f32 v28, v28, v31, 1.0
	global_load_dwordx2 v[30:31], v[26:27], off offset:96
	s_waitcnt vmcnt(5)
	v_lshlrev_b32_e32 v29, 16, v32
	v_mul_f32_e32 v34, 0xbfb8aa3b, v29
	v_exp_f32_e32 v34, v34
	v_and_b32_e32 v35, 0xffff0000, v32
	v_lshlrev_b32_e32 v36, 16, v33
	v_and_b32_e32 v37, 0xffff0000, v33
	v_add_f32_e32 v32, 1.0, v34
	v_rcp_f32_e32 v33, v32
	v_mul_f32_e32 v32, 0xbfb8aa3b, v35
	v_exp_f32_e32 v34, v32
	v_mov_b32_e32 v32, v4
	v_pk_mul_f32 v[32:33], v[32:33], v[28:29]
	v_mov_b32_e32 v29, v35
	v_add_f32_e32 v4, 1.0, v34
	v_mul_f32_e32 v38, v32, v33
	v_rcp_f32_e32 v33, v4
	v_mul_f32_e32 v4, 0xbfb8aa3b, v36
	v_exp_f32_e32 v34, v4
	v_mov_b32_e32 v32, v5
	v_pk_mul_f32 v[4:5], v[32:33], v[28:29]
	v_mov_b32_e32 v32, v6
	v_mul_f32_e32 v4, v4, v5
	v_add_f32_e32 v5, 1.0, v34
	v_rcp_f32_e32 v33, v5
	v_mul_f32_e32 v5, 0xbfb8aa3b, v37
	v_exp_f32_e32 v5, v5
	v_mov_b32_e32 v29, v36
	v_pk_mul_f32 v[32:33], v[32:33], v[28:29]
	v_mov_b32_e32 v34, v7
	v_add_f32_e32 v5, 1.0, v5
	v_rcp_f32_e32 v35, v5
	v_mov_b32_e32 v29, v37
	v_cvt_pk_bf16_f32 v4, v38, v4
	v_mul_f32_e32 v5, v32, v33
	v_pk_mul_f32 v[6:7], v[34:35], v[28:29]
	v_mfma_f32_16x16x32_bf16 v[18:21], v[18:21], v[152:155], v[114:117]
	v_mul_f32_e32 v6, v6, v7
	s_waitcnt vmcnt(3)
	v_lshlrev_b32_e32 v29, 16, v22
	v_cvt_pk_bf16_f32 v5, v5, v6
	global_store_dwordx2 v[26:27], v[4:5], off
	v_mul_f32_e32 v4, 0xbfb8aa3b, v29
	v_exp_f32_e32 v4, v4
	v_and_b32_e32 v6, 0xffff0000, v22
	v_lshlrev_b32_e32 v22, 16, v23
	v_and_b32_e32 v23, 0xffff0000, v23
	v_add_f32_e32 v4, 1.0, v4
	v_rcp_f32_e32 v5, v4
	v_mul_f32_e32 v4, 0xbfb8aa3b, v6
	v_exp_f32_e32 v7, v4
	v_mov_b32_e32 v4, v12
	v_pk_mul_f32 v[4:5], v[4:5], v[28:29]
	v_mov_b32_e32 v29, v6
	v_mul_f32_e32 v12, v4, v5
	v_add_f32_e32 v4, 1.0, v7
	v_rcp_f32_e32 v5, v4
	v_mul_f32_e32 v6, 0xbfb8aa3b, v22
	v_exp_f32_e32 v6, v6
	v_mov_b32_e32 v4, v13
	v_pk_mul_f32 v[4:5], v[4:5], v[28:29]
	v_mov_b32_e32 v29, v22
	v_mul_f32_e32 v4, v4, v5
	v_add_f32_e32 v5, 1.0, v6
	v_rcp_f32_e32 v7, v5
	v_mul_f32_e32 v5, 0xbfb8aa3b, v23
	v_exp_f32_e32 v5, v5
	v_mov_b32_e32 v6, v14
	v_cvt_pk_bf16_f32 v4, v12, v4
	v_pk_mul_f32 v[6:7], v[6:7], v[28:29]
	v_add_f32_e32 v5, 1.0, v5
	v_rcp_f32_e32 v13, v5
	v_mov_b32_e32 v12, v15
	v_mov_b32_e32 v29, v23
	v_mul_f32_e32 v5, v6, v7
	v_pk_mul_f32 v[6:7], v[12:13], v[28:29]
	s_waitcnt vmcnt(2)
	v_lshlrev_b32_e32 v29, 16, v24
	v_mul_f32_e32 v6, v6, v7
	v_cvt_pk_bf16_f32 v5, v5, v6
	global_store_dwordx2 v[26:27], v[4:5], off offset:32
	v_mul_f32_e32 v4, 0xbfb8aa3b, v29
	v_exp_f32_e32 v4, v4
	v_and_b32_e32 v6, 0xffff0000, v24
	v_lshlrev_b32_e32 v12, 16, v25
	v_and_b32_e32 v13, 0xffff0000, v25
	v_add_f32_e32 v4, 1.0, v4
	v_rcp_f32_e32 v5, v4
	v_mul_f32_e32 v4, 0xbfb8aa3b, v6
	v_exp_f32_e32 v7, v4
	v_mov_b32_e32 v4, v8
	v_pk_mul_f32 v[4:5], v[4:5], v[28:29]
	v_mov_b32_e32 v29, v6
	v_mul_f32_e32 v8, v4, v5
	v_add_f32_e32 v4, 1.0, v7
	v_rcp_f32_e32 v5, v4
	v_mul_f32_e32 v6, 0xbfb8aa3b, v12
	v_exp_f32_e32 v6, v6
	v_mov_b32_e32 v4, v9
	v_pk_mul_f32 v[4:5], v[4:5], v[28:29]
	v_mov_b32_e32 v29, v12
	v_mul_f32_e32 v4, v4, v5
	v_add_f32_e32 v5, 1.0, v6
	v_rcp_f32_e32 v7, v5
	v_mul_f32_e32 v5, 0xbfb8aa3b, v13
	v_exp_f32_e32 v5, v5
	v_mov_b32_e32 v6, v10
	v_cvt_pk_bf16_f32 v4, v8, v4
	v_pk_mul_f32 v[6:7], v[6:7], v[28:29]
	v_add_f32_e32 v5, 1.0, v5
	v_rcp_f32_e32 v9, v5
	v_mov_b32_e32 v8, v11
	v_mov_b32_e32 v29, v13
	v_mul_f32_e32 v5, v6, v7
	v_pk_mul_f32 v[6:7], v[8:9], v[28:29]
	s_waitcnt vmcnt(2)
	v_lshlrev_b32_e32 v29, 16, v30
	v_mul_f32_e32 v6, v6, v7
	v_cvt_pk_bf16_f32 v5, v5, v6
	global_store_dwordx2 v[26:27], v[4:5], off offset:64
	v_mul_f32_e32 v4, 0xbfb8aa3b, v29
	v_exp_f32_e32 v4, v4
	v_and_b32_e32 v6, 0xffff0000, v30
	v_lshlrev_b32_e32 v8, 16, v31
	v_and_b32_e32 v10, 0xffff0000, v31
	v_add_f32_e32 v4, 1.0, v4
	v_rcp_f32_e32 v5, v4
	v_mul_f32_e32 v4, 0xbfb8aa3b, v6
	v_exp_f32_e32 v7, v4
	v_mov_b32_e32 v4, v18
	v_pk_mul_f32 v[4:5], v[4:5], v[28:29]
	v_mov_b32_e32 v29, v6
	v_mul_f32_e32 v9, v4, v5
	v_add_f32_e32 v4, 1.0, v7
	v_rcp_f32_e32 v5, v4
	v_mul_f32_e32 v6, 0xbfb8aa3b, v8
	v_exp_f32_e32 v6, v6
	v_mov_b32_e32 v4, v19
	v_pk_mul_f32 v[4:5], v[4:5], v[28:29]
	v_mov_b32_e32 v29, v8
	v_mul_f32_e32 v4, v4, v5
	v_add_f32_e32 v5, 1.0, v6
	v_rcp_f32_e32 v7, v5
	v_mul_f32_e32 v5, 0xbfb8aa3b, v10
	v_exp_f32_e32 v5, v5
	v_cvt_pk_bf16_f32 v4, v9, v4
	v_mov_b32_e32 v6, v20
	v_pk_mul_f32 v[6:7], v[6:7], v[28:29]
	v_add_f32_e32 v5, 1.0, v5
	v_rcp_f32_e32 v9, v5
	v_mov_b32_e32 v8, v21
	v_mov_b32_e32 v29, v10
	v_mul_f32_e32 v5, v6, v7
	v_pk_mul_f32 v[6:7], v[8:9], v[28:29]
	s_nop 0
	v_mul_f32_e32 v6, v6, v7
	v_cvt_pk_bf16_f32 v5, v5, v6
	global_store_dwordx2 v[26:27], v[4:5], off offset:96
	s_cbranch_scc0 .LBB0_937
